# gdn_prep work queue: next ticket fetched (atomic) at the start of stage C and consumed at the loop top, on top of v15
# baseline (speedup 1.0000x reference)
; __device__ __forceinline__ const float* in_ptr(int i) { return (const float*)gptr(i); }
; #define WSP() (gptr(22))
; template <int STRIP> __device__ __forceinline__ void ph_gdn_prep_fast(const bf16* __restrict__ proj, const float* __restrict__ small, const float* __restrict__ conv_w, const float* __restrict__ a_log, const float* __restrict__ dt_bias, ...
;     ...
;     volatile unsigned* qw = (volatile unsigned*)(lds_dyn + 2 * GP_CHUNK);
;     ...
;     for (;;) {
;         int tid = tid0; asm volatile("" : "+v"(tid));
;         __syncthreads();
;         if (tid == 0) *qw = __hip_atomic_fetch_add(queue, 1u, __ATOMIC_RELAXED, __HIP_MEMORY_SCOPE_AGENT);
; __global__ void __launch_bounds__(NTHREADS, 2) mega(Params P) {
;     ...
;         { unsigned char* ws = WSP(); ph_gdn_prep_fast<0>((bf16*)(ws + WS_PROJ), (float*)(ws + WS_SMALL), in_ptr(I_CONV_A) + (size_t)l * 4 * 2304, in_ptr(I_A_LOG) + l * 6, in_ptr(I_DT_BIAS) + l * 6,
;                                                       (bf16*)(ws + WS_UF), (bf16*)(ws + WS_WP), (bf16*)(ws + WS_QGP), (bf16*)(ws + WS_KDT), (bf16*)(ws + WS_AP), (float*)(ws + WS_EGL), (unsigned*)(ws + WS_CTL + CTL_QUEUE) + 64 * (8 + l)); }
.LBB0_1247:
	v_mov_b32_e32 v1, 22
	s_barrier
	v_readlane_b32 s6, v254, 35
	s_mul_i32 s5, s96, 0x9000
	s_mul_hi_u32 s4, s96, 0x9000
	v_lshl_add_u32 v1, v1, 3, s6
	ds_read_b64 v[4:5], v1
	v_mov_b32_e32 v1, 3
	s_mov_b64 s[8:9], s[96:97]
	v_lshl_add_u32 v1, v1, 3, s6
	s_waitcnt lgkmcnt(0)
	v_readfirstlane_b32 s2, v5
	v_readfirstlane_b32 s3, v4
	ds_read_b64 v[4:5], v1
	v_mov_b32_e32 v1, 4
	s_add_u32 s20, s3, 0xe400000
	v_lshl_add_u32 v1, v1, 3, s6
	s_waitcnt lgkmcnt(0)
	v_readfirstlane_b32 s0, v5
	v_readfirstlane_b32 s1, v4
	ds_read_b64 v[4:5], v1
	s_addc_u32 s21, s2, 0
	s_add_u32 s94, s3, 0x28400000
	v_mov_b32_e32 v1, 5
	s_addc_u32 s95, s2, 0
	s_add_u32 s96, s1, s5
	v_lshl_add_u32 v1, v1, 3, s6
	s_addc_u32 s97, s0, s4
	s_waitcnt lgkmcnt(0)
	v_readfirstlane_b32 s4, v5
	v_readfirstlane_b32 s5, v4
	ds_read_b64 v[4:5], v1
	s_mul_i32 s64, s8, 6
	s_lshl_b64 s[0:1], s[64:65], 2
	s_add_u32 s62, s5, s0
	s_addc_u32 s63, s4, s1
	s_waitcnt lgkmcnt(0)
	v_readfirstlane_b32 s5, v4
	v_readfirstlane_b32 s4, v5
	s_add_u32 s44, s5, s0
	s_addc_u32 s45, s4, s1
	s_add_u32 s50, s3, 0x2e400000
	s_addc_u32 s51, s2, 0
	s_add_u32 s34, s3, 0x31400000
	s_addc_u32 s35, s2, 0
	s_add_u32 s36, s3, 0x34400000
	s_addc_u32 s37, s2, 0
	s_add_u32 s38, s3, 0x37400000
	s_addc_u32 s39, s2, 0
	s_add_u32 s42, s3, 0x3a400000
	s_addc_u32 s43, s2, 0
	s_add_u32 s46, s3, 0x2db00000
	s_addc_u32 s47, s2, 0
	v_writelane_b32 v255, s8, 6
	s_lshl_b32 s64, s8, 6
	s_lshl_b64 s[4:5], s[64:65], 2
	v_writelane_b32 v255, s9, 7
	s_add_u32 s0, s3, s4
	v_writelane_b32 v255, s4, 8
	s_addc_u32 s1, s2, s5
	s_add_u32 s52, s0, 0x8800
	v_writelane_b32 v255, s5, 9
	s_addc_u32 s53, s1, 0
	v_mov_b32_e32 v1, v0
	s_mov_b64 s[54:55], 0
	v_cmp_eq_u32_e64 s[0:1], 0, v0
	s_and_saveexec_b64 s[2:3], s[0:1]
	v_mov_b32_e32 v239, 1
	global_atomic_add v239, v3, v239, s[52:53] sc0
	s_mov_b64 exec, s[2:3]
	s_branch .LBB0_1250

; template <int STRIP> __device__ __forceinline__ void ph_gdn_prep_fast(const bf16* __restrict__ proj, const float* __restrict__ small, const float* __restrict__ conv_w, const float* __restrict__ a_log, const float* __restrict__ dt_bias, ...
;     ...
;     for (;;) {
;         int tid = tid0; asm volatile("" : "+v"(tid));
;         __syncthreads();
;         if (tid == 0) *qw = __hip_atomic_fetch_add(queue, 1u, __ATOMIC_RELAXED, __HIP_MEMORY_SCOPE_AGENT);
;         __syncthreads();
;         const int pair = (int)*qw;
.LBB0_1250:
	v_mov_b32_e32 v78, v1
	s_nop 0
	v_cmp_eq_u32_e32 vcc, 0, v78
	s_barrier
	s_and_saveexec_b64 s[0:1], vcc
	s_cbranch_execz .LBB0_1254
	s_mov_b64 s[6:7], exec
	v_mbcnt_lo_u32_b32 v2, s6, 0
	v_mbcnt_hi_u32_b32 v2, s7, v2
	v_cmp_eq_u32_e32 vcc, 0, v2
	s_and_saveexec_b64 s[4:5], vcc
	s_cbranch_execz .LBB0_1253
	s_waitcnt vmcnt(0)
	v_mov_b32_e32 v4, v239

; __device__ __forceinline__ float bf2f(bf16 v) { return __uint_as_float(((unsigned)v) << 16); }
; #define GDN_LOADROW(buf, rr_, i_) do { _Pragma("unroll") for (int j4 = 0; j4 < ((i_) + 3) / 4; ++j4) buf[j4] = *(const f32x4*)(Lm + (i_) * GP_LSTR + 4 * j4); rr_ = bf2f(*(const bf16*)(xsrc + (i_) * GP_STR * 2)) * scl[i_]; } while (0)
; template <int STRIP> __device__ __forceinline__ void ph_gdn_prep_fast(const bf16* __restrict__ proj, const float* __restrict__ small, const float* __restrict__ conv_w, const float* __restrict__ a_log, const float* __restrict__ dt_bias, ...
;     ...
;         if (STRIP != 1 && STRIP != 2) {
;             const int cs = wave >> 2, ci = 2 * pair + cs;
;             unsigned char* L = lds_dyn + cs * GP_CHUNK; const float* sgc = (const float*)(L + GP_SC); const float* sbeta = sgc + 64; const float* segc = sgc + 128; const float* sekd = sgc + 192;
;             const int c = (wave & 3) * 64 + lane; const bool isw = c >= 128; const int cc = c & 127;
;             const unsigned char* xsrc = L + (isw ? GP_K : GP_V) + cc * 2;
;             const float* Lm = (const float*)(L + GP_L);
;             float U[64];
;             const float* scl = isw ? (sgc + 256) : sbeta;
;             f32x4 bA[16], bB[16]; float rA, rB = 0.f;
;             rA = bf2f(*(const bf16*)xsrc) * scl[0];
;     ...
; #pragma unroll
;             for (int i = 0; i < 64; i += 2) {
;                 GDN_LOADROW(bB, rB, i + 1);
;                 GDN_ROW(bA, rA, i);
;                 if (i + 2 < 64) GDN_LOADROW(bA, rA, i + 2);
;                 GDN_ROW(bB, rB, i + 1);
;             }
.LBB0_1303:
	s_or_b64 exec, exec, s[8:9]
	v_ashrrev_i32_e32 v8, 8, v78
	s_mov_b32 s0, 0x11500
	v_and_b32_e32 v4, 0x80, v78
	v_and_b32_e32 v2, 0x80, v78
	v_mad_i32_i24 v10, v8, s0, 0
	v_cmp_ne_u32_e32 vcc, 0, v2
	v_and_b32_e32 v2, 0x7f, v78
	v_cmp_eq_u32_e64 s[0:1], 0, v4
	v_mov_b32_e32 v4, 0x8800
	v_lshlrev_b32_e32 v18, 1, v2
	v_cndmask_b32_e64 v4, v236, v4, s[0:1]
	s_waitcnt lgkmcnt(0)
	s_barrier
	v_add3_u32 v123, v10, v4, v18
	v_mov_b32_e32 v126, 0x11400
	v_mov_b32_e32 v127, 0x11100
	v_and_b32_e32 v125, 3, v78
	v_cndmask_b32_e64 v126, v126, v127, s[0:1]
	v_lshlrev_b32_e32 v125, 3, v125
	v_add_u32_e32 v124, v10, v126
	v_add_u32_e32 v125, 0xcc00, v125
	v_add_u32_e32 v125, v10, v125
	v_cmp_eq_u32_e64 s[2:3], 0, v78
	s_and_saveexec_b64 s[4:5], s[2:3]
	v_mov_b32_e32 v239, 1
	global_atomic_add v239, v3, v239, s[52:53] sc0
	s_mov_b64 exec, s[4:5]
	v_and_b32_e32 v130, 31, v78
	v_bfe_u32 v127, v78, 5, 1
	v_add_u32_e32 v130, 32, v130
	v_mul_u32_u24_e32 v130, 0x110, v130
	v_lshl_add_u32 v130, v127, 2, v130
	v_add_u32_e32 v130, 0xcc00, v130
	v_add_u32_e32 v130, v10, v130
	ds_read_b32 v172, v130 offset:0
	ds_read_b32 v173, v130 offset:8
	ds_read_b32 v174, v130 offset:16
	ds_read_b32 v175, v130 offset:24
	ds_read_b32 v176, v130 offset:32
	ds_read_b32 v177, v130 offset:40
	ds_read_b32 v178, v130 offset:48
	ds_read_b32 v179, v130 offset:56
	ds_read_b32 v222, v130 offset:64
	ds_read_b32 v223, v130 offset:72
	ds_read_b32 v224, v130 offset:80
	ds_read_b32 v225, v130 offset:88
	ds_read_b32 v226, v130 offset:96
	ds_read_b32 v227, v130 offset:104
	ds_read_b32 v228, v130 offset:112
	ds_read_b32 v229, v130 offset:120
	v_mov_b32_e32 v244, 0
	v_mov_b32_e32 v245, 0
	v_mov_b32_e32 v246, 0
	v_mov_b32_e32 v247, 0
	v_mov_b32_e32 v248, 0
	v_mov_b32_e32 v249, 0
	v_mov_b32_e32 v250, 0
	v_mov_b32_e32 v251, 0
	v_mov_b32_e32 v252, 0
	v_mov_b32_e32 v253, 0
	v_mov_b32_e32 v126, 0
	v_mov_b32_e32 v127, 0
	ds_read_b32 v208, v124 offset:0
	ds_read_u16_d16_hi v244, v123 offset:0
	ds_read_b64 v[186:187], v125 offset:272
	ds_read_b32 v209, v124 offset:4
	ds_read_u16_d16_hi v245, v123 offset:272
	ds_read_b64 v[188:189], v125 offset:544
	ds_read_b32 v210, v124 offset:8
	ds_read_u16_d16_hi v246, v123 offset:544
	ds_read_b64 v[190:191], v125 offset:816
	ds_read_b32 v211, v124 offset:12
	ds_read_u16_d16_hi v247, v123 offset:816
	ds_read_b64 v[192:193], v125 offset:1088
	ds_read_b32 v212, v124 offset:16
	ds_read_u16_d16_hi v248, v123 offset:1088
	ds_read_b64 v[194:195], v125 offset:1360
	ds_read_b32 v213, v124 offset:20
	ds_read_u16_d16_hi v249, v123 offset:1360
	ds_read_b64 v[196:197], v125 offset:1632
	ds_read_b32 v214, v124 offset:24
	ds_read_u16_d16_hi v250, v123 offset:1632
	ds_read_b64 v[198:199], v125 offset:1904
	ds_read_b32 v215, v124 offset:28
	ds_read_u16_d16_hi v251, v123 offset:1904
	ds_read_b64 v[200:201], v125 offset:2176
	ds_read_b32 v216, v124 offset:32
	ds_read_u16_d16_hi v252, v123 offset:2176
	ds_read_b64 v[202:203], v125 offset:2448
	ds_read_b64 v[204:205], v125 offset:2480
	ds_read_b32 v217, v124 offset:36
	ds_read_u16_d16_hi v253, v123 offset:2448
	ds_read_b64 v[206:207], v125 offset:2720
	ds_read_b64 v[164:165], v125 offset:2752
	ds_read_b32 v218, v124 offset:40
	ds_read_u16_d16_hi v126, v123 offset:2720
	s_waitcnt lgkmcnt(15)
	v_fma_f32 v4, v208, v244, 0
	s_waitcnt lgkmcnt(15)
	v_mul_f32_dpp v120, v186, v4 quad_perm:[0,0,0,0] row_mask:0xf bank_mask:0xf
	v_fma_f32 v116, v209, v245, -v120
	v_add_f32_e32 v5, 0, v116
	s_waitcnt lgkmcnt(15)
	v_mul_f32_dpp v120, v188, v4 quad_perm:[0,0,0,0] row_mask:0xf bank_mask:0xf
	v_fma_f32 v116, v210, v246, -v120
	v_mul_f32_dpp v117, -v189, v5 quad_perm:[0,0,0,0] row_mask:0xf bank_mask:0xf
	v_add_f32_e32 v6, v117, v116
	s_waitcnt lgkmcnt(15)
	v_mul_f32_dpp v120, v190, v4 quad_perm:[0,0,0,0] row_mask:0xf bank_mask:0xf
	v_fma_f32 v116, v211, v247, -v120
	v_mul_f32_dpp v117, -v191, v5 quad_perm:[0,0,0,0] row_mask:0xf bank_mask:0xf
	v_mul_f32_dpp v118, -v190, v6 quad_perm:[1,1,1,1] row_mask:0xf bank_mask:0xf
	ds_read_b64 v[166:167], v125 offset:2992
	v_add_f32_e32 v121, v117, v116
	v_add_f32_e32 v12, v118, v121
	s_waitcnt lgkmcnt(15)
	v_mul_f32_dpp v120, v192, v4 quad_perm:[0,0,0,0] row_mask:0xf bank_mask:0xf
	v_fma_f32 v116, v212, v248, -v120
	v_mul_f32_dpp v117, -v193, v5 quad_perm:[0,0,0,0] row_mask:0xf bank_mask:0xf
	v_mul_f32_dpp v118, -v192, v6 quad_perm:[1,1,1,1] row_mask:0xf bank_mask:0xf
	v_mul_f32_dpp v119, -v193, v12 quad_perm:[1,1,1,1] row_mask:0xf bank_mask:0xf
	ds_read_b64 v[168:169], v125 offset:3024
	v_add_f32_e32 v121, v117, v116
	v_add_f32_e32 v122, v118, v119
	v_add_f32_e32 v7, v122, v121
	s_waitcnt lgkmcnt(15)
	v_mul_f32_dpp v120, v194, v4 quad_perm:[0,0,0,0] row_mask:0xf bank_mask:0xf
	v_fma_f32 v116, v213, v249, -v120
	v_mul_f32_dpp v117, -v195, v5 quad_perm:[0,0,0,0] row_mask:0xf bank_mask:0xf
	v_mul_f32_dpp v118, -v194, v6 quad_perm:[1,1,1,1] row_mask:0xf bank_mask:0xf
	v_mul_f32_dpp v119, -v195, v12 quad_perm:[1,1,1,1] row_mask:0xf bank_mask:0xf
	ds_read_b32 v219, v124 offset:44
	v_fmac_f32_dpp v116, -v194, v7 quad_perm:[2,2,2,2] row_mask:0xf bank_mask:0xf
	v_add_f32_e32 v121, v117, v116
	v_add_f32_e32 v122, v118, v119
	v_add_f32_e32 v13, v122, v121
	s_waitcnt lgkmcnt(15)
	v_mul_f32_dpp v120, v196, v4 quad_perm:[0,0,0,0] row_mask:0xf bank_mask:0xf
	v_fma_f32 v116, v214, v250, -v120
	v_mul_f32_dpp v117, -v197, v5 quad_perm:[0,0,0,0] row_mask:0xf bank_mask:0xf
	v_mul_f32_dpp v118, -v196, v6 quad_perm:[1,1,1,1] row_mask:0xf bank_mask:0xf
	ds_read_u16_d16_hi v127, v123 offset:2992
	v_mul_f32_dpp v119, -v197, v12 quad_perm:[1,1,1,1] row_mask:0xf bank_mask:0xf
	v_fmac_f32_dpp v116, -v196, v7 quad_perm:[2,2,2,2] row_mask:0xf bank_mask:0xf
	v_fmac_f32_dpp v117, -v197, v13 quad_perm:[2,2,2,2] row_mask:0xf bank_mask:0xf
	ds_read_b64 v[170:171], v125 offset:3264
	v_add_f32_e32 v121, v117, v116
	v_add_f32_e32 v122, v118, v119
	v_add_f32_e32 v14, v122, v121
	s_waitcnt lgkmcnt(15)
; __device__ __forceinline__ float bf2f(bf16 v) { return __uint_as_float(((unsigned)v) << 16); }
; #define GDN_LOADROW(buf, rr_, i_) do { _Pragma("unroll") for (int j4 = 0; j4 < ((i_) + 3) / 4; ++j4) buf[j4] = *(const f32x4*)(Lm + (i_) * GP_LSTR + 4 * j4); rr_ = bf2f(*(const bf16*)(xsrc + (i_) * GP_STR * 2)) * scl[i_]; } while (0)
; template <int STRIP> __device__ __forceinline__ void ph_gdn_prep_fast(const bf16* __restrict__ proj, const float* __restrict__ small, const float* __restrict__ conv_w, const float* __restrict__ a_log, const float* __restrict__ dt_bias, ...
;     ...
;             rA = bf2f(*(const bf16*)xsrc) * scl[0];
;     ...
; #pragma unroll
;             for (int i = 0; i < 64; i += 2) {
;                 GDN_LOADROW(bB, rB, i + 1);
;                 GDN_ROW(bA, rA, i);
;                 if (i + 2 < 64) GDN_LOADROW(bA, rA, i + 2);
;                 GDN_ROW(bB, rB, i + 1);
;             }
	v_mul_f32_dpp v120, v198, v4 quad_perm:[0,0,0,0] row_mask:0xf bank_mask:0xf
	v_fma_f32 v116, v215, v251, -v120
	v_mul_f32_dpp v117, -v199, v5 quad_perm:[0,0,0,0] row_mask:0xf bank_mask:0xf
	v_mul_f32_dpp v118, -v198, v6 quad_perm:[1,1,1,1] row_mask:0xf bank_mask:0xf
	v_mul_f32_dpp v119, -v199, v12 quad_perm:[1,1,1,1] row_mask:0xf bank_mask:0xf
	ds_read_b64 v[132:133], v125 offset:3296
	v_fmac_f32_dpp v116, -v198, v7 quad_perm:[2,2,2,2] row_mask:0xf bank_mask:0xf
	v_fmac_f32_dpp v117, -v199, v13 quad_perm:[2,2,2,2] row_mask:0xf bank_mask:0xf
	v_fmac_f32_dpp v118, -v198, v14 quad_perm:[3,3,3,3] row_mask:0xf bank_mask:0xf
	ds_read_b32 v220, v124 offset:48
	v_add_f32_e32 v121, v117, v116
	v_add_f32_e32 v122, v118, v119
	v_add_f32_e32 v15, v122, v121
	s_waitcnt lgkmcnt(15)
	v_mul_f32_dpp v120, v200, v4 quad_perm:[0,0,0,0] row_mask:0xf bank_mask:0xf
	v_fma_f32 v116, v216, v252, -v120
	v_mul_f32_dpp v117, -v201, v5 quad_perm:[0,0,0,0] row_mask:0xf bank_mask:0xf
	v_mul_f32_dpp v118, -v200, v6 quad_perm:[1,1,1,1] row_mask:0xf bank_mask:0xf
	v_mul_f32_dpp v119, -v201, v12 quad_perm:[1,1,1,1] row_mask:0xf bank_mask:0xf
	ds_read_u16_d16_hi v244, v123 offset:3264
	v_fmac_f32_dpp v116, -v200, v7 quad_perm:[2,2,2,2] row_mask:0xf bank_mask:0xf
	v_fmac_f32_dpp v117, -v201, v13 quad_perm:[2,2,2,2] row_mask:0xf bank_mask:0xf
	v_fmac_f32_dpp v118, -v200, v14 quad_perm:[3,3,3,3] row_mask:0xf bank_mask:0xf
	ds_read_b64 v[134:135], v125 offset:3536
	v_fmac_f32_dpp v119, -v201, v15 quad_perm:[3,3,3,3] row_mask:0xf bank_mask:0xf
	v_add_f32_e32 v121, v117, v116
	v_add_f32_e32 v122, v118, v119
	v_add_f32_e32 v16, v122, v121
	s_waitcnt lgkmcnt(13)
	v_mul_f32_dpp v120, v202, v4 quad_perm:[0,0,0,0] row_mask:0xf bank_mask:0xf
	v_fma_f32 v116, v217, v253, -v120
	v_mul_f32_dpp v117, -v203, v5 quad_perm:[0,0,0,0] row_mask:0xf bank_mask:0xf
	v_mul_f32_dpp v118, -v202, v6 quad_perm:[1,1,1,1] row_mask:0xf bank_mask:0xf
	ds_read_b64 v[136:137], v125 offset:3568
	v_mul_f32_dpp v119, -v203, v12 quad_perm:[1,1,1,1] row_mask:0xf bank_mask:0xf
	v_fmac_f32_dpp v116, -v202, v7 quad_perm:[2,2,2,2] row_mask:0xf bank_mask:0xf
	v_fmac_f32_dpp v117, -v203, v13 quad_perm:[2,2,2,2] row_mask:0xf bank_mask:0xf
	ds_read_b32 v221, v124 offset:52
	v_fmac_f32_dpp v118, -v202, v14 quad_perm:[3,3,3,3] row_mask:0xf bank_mask:0xf
	v_fmac_f32_dpp v119, -v203, v15 quad_perm:[3,3,3,3] row_mask:0xf bank_mask:0xf
	v_fmac_f32_dpp v116, -v204, v16 quad_perm:[0,0,0,0] row_mask:0xf bank_mask:0xf
	ds_read_u16_d16_hi v245, v123 offset:3536
	v_add_f32_e32 v121, v117, v116
	v_add_f32_e32 v122, v118, v119
	v_add_f32_e32 v17, v122, v121
	s_waitcnt lgkmcnt(12)
	v_mul_f32_dpp v120, v206, v4 quad_perm:[0,0,0,0] row_mask:0xf bank_mask:0xf
	v_fma_f32 v116, v218, v126, -v120
	v_mul_f32_dpp v117, -v207, v5 quad_perm:[0,0,0,0] row_mask:0xf bank_mask:0xf
	v_mul_f32_dpp v118, -v206, v6 quad_perm:[1,1,1,1] row_mask:0xf bank_mask:0xf
	v_mul_f32_dpp v119, -v207, v12 quad_perm:[1,1,1,1] row_mask:0xf bank_mask:0xf
	ds_read_b64 v[138:139], v125 offset:3808
	v_fmac_f32_dpp v116, -v206, v7 quad_perm:[2,2,2,2] row_mask:0xf bank_mask:0xf
	v_fmac_f32_dpp v117, -v207, v13 quad_perm:[2,2,2,2] row_mask:0xf bank_mask:0xf
	v_fmac_f32_dpp v118, -v206, v14 quad_perm:[3,3,3,3] row_mask:0xf bank_mask:0xf
	ds_read_b64 v[140:141], v125 offset:3840
	v_fmac_f32_dpp v119, -v207, v15 quad_perm:[3,3,3,3] row_mask:0xf bank_mask:0xf
	v_fmac_f32_dpp v116, -v164, v16 quad_perm:[0,0,0,0] row_mask:0xf bank_mask:0xf
	v_fmac_f32_dpp v117, -v165, v17 quad_perm:[0,0,0,0] row_mask:0xf bank_mask:0xf
	ds_read_b32 v181, v124 offset:56
	v_add_f32_e32 v121, v117, v116
	v_add_f32_e32 v122, v118, v119
	v_add_f32_e32 v19, v122, v121
	s_waitcnt lgkmcnt(11)
	v_mul_f32_dpp v120, v166, v4 quad_perm:[0,0,0,0] row_mask:0xf bank_mask:0xf
	v_fma_f32 v116, v219, v127, -v120
	v_mul_f32_dpp v117, -v167, v5 quad_perm:[0,0,0,0] row_mask:0xf bank_mask:0xf
	v_mul_f32_dpp v118, -v166, v6 quad_perm:[1,1,1,1] row_mask:0xf bank_mask:0xf
	v_mul_f32_dpp v119, -v167, v12 quad_perm:[1,1,1,1] row_mask:0xf bank_mask:0xf
	ds_read_u16_d16_hi v246, v123 offset:3808
	v_fmac_f32_dpp v116, -v166, v7 quad_perm:[2,2,2,2] row_mask:0xf bank_mask:0xf
	v_fmac_f32_dpp v117, -v167, v13 quad_perm:[2,2,2,2] row_mask:0xf bank_mask:0xf
	v_fmac_f32_dpp v118, -v166, v14 quad_perm:[3,3,3,3] row_mask:0xf bank_mask:0xf
	ds_read_b64 v[142:143], v125 offset:4080
	v_fmac_f32_dpp v119, -v167, v15 quad_perm:[3,3,3,3] row_mask:0xf bank_mask:0xf
	v_fmac_f32_dpp v116, -v168, v16 quad_perm:[0,0,0,0] row_mask:0xf bank_mask:0xf
	v_fmac_f32_dpp v117, -v169, v17 quad_perm:[0,0,0,0] row_mask:0xf bank_mask:0xf
	ds_read_b64 v[144:145], v125 offset:4112
	v_fmac_f32_dpp v118, -v168, v19 quad_perm:[1,1,1,1] row_mask:0xf bank_mask:0xf
	v_add_f32_e32 v121, v117, v116
	v_add_f32_e32 v122, v118, v119
	v_add_f32_e32 v20, v122, v121
	s_waitcnt lgkmcnt(10)
	v_mul_f32_dpp v120, v170, v4 quad_perm:[0,0,0,0] row_mask:0xf bank_mask:0xf
	v_fma_f32 v116, v220, v244, -v120
	v_mul_f32_dpp v117, -v171, v5 quad_perm:[0,0,0,0] row_mask:0xf bank_mask:0xf
	v_mul_f32_dpp v118, -v170, v6 quad_perm:[1,1,1,1] row_mask:0xf bank_mask:0xf
	ds_read_b32 v182, v124 offset:60
	v_mul_f32_dpp v119, -v171, v12 quad_perm:[1,1,1,1] row_mask:0xf bank_mask:0xf
	v_fmac_f32_dpp v116, -v170, v7 quad_perm:[2,2,2,2] row_mask:0xf bank_mask:0xf
	v_fmac_f32_dpp v117, -v171, v13 quad_perm:[2,2,2,2] row_mask:0xf bank_mask:0xf
	ds_read_u16_d16_hi v247, v123 offset:4080
	v_fmac_f32_dpp v118, -v170, v14 quad_perm:[3,3,3,3] row_mask:0xf bank_mask:0xf
	v_fmac_f32_dpp v119, -v171, v15 quad_perm:[3,3,3,3] row_mask:0xf bank_mask:0xf
	v_fmac_f32_dpp v116, -v132, v16 quad_perm:[0,0,0,0] row_mask:0xf bank_mask:0xf
	ds_read_b64 v[146:147], v125 offset:4352
	v_fmac_f32_dpp v117, -v133, v17 quad_perm:[0,0,0,0] row_mask:0xf bank_mask:0xf
	v_fmac_f32_dpp v118, -v132, v19 quad_perm:[1,1,1,1] row_mask:0xf bank_mask:0xf
	v_fmac_f32_dpp v119, -v133, v20 quad_perm:[1,1,1,1] row_mask:0xf bank_mask:0xf
	ds_read_b64 v[148:149], v125 offset:4384
	v_add_f32_e32 v121, v117, v116
	v_add_f32_e32 v122, v118, v119
	v_add_f32_e32 v21, v122, v121
	s_waitcnt lgkmcnt(10)
; __device__ __forceinline__ float bf2f(bf16 v) { return __uint_as_float(((unsigned)v) << 16); }
; #define GDN_LOADROW(buf, rr_, i_) do { _Pragma("unroll") for (int j4 = 0; j4 < ((i_) + 3) / 4; ++j4) buf[j4] = *(const f32x4*)(Lm + (i_) * GP_LSTR + 4 * j4); rr_ = bf2f(*(const bf16*)(xsrc + (i_) * GP_STR * 2)) * scl[i_]; } while (0)
; template <int STRIP> __device__ __forceinline__ void ph_gdn_prep_fast(const bf16* __restrict__ proj, const float* __restrict__ small, const float* __restrict__ conv_w, const float* __restrict__ a_log, const float* __restrict__ dt_bias, ...
;     ...
;             rA = bf2f(*(const bf16*)xsrc) * scl[0];
;     ...
; #pragma unroll
;             for (int i = 0; i < 64; i += 2) {
;                 GDN_LOADROW(bB, rB, i + 1);
;                 GDN_ROW(bA, rA, i);
;                 if (i + 2 < 64) GDN_LOADROW(bA, rA, i + 2);
;                 GDN_ROW(bB, rB, i + 1);
;             }
	v_mul_f32_dpp v120, v134, v4 quad_perm:[0,0,0,0] row_mask:0xf bank_mask:0xf
	v_fma_f32 v116, v221, v245, -v120
	v_mul_f32_dpp v117, -v135, v5 quad_perm:[0,0,0,0] row_mask:0xf bank_mask:0xf
	v_mul_f32_dpp v118, -v134, v6 quad_perm:[1,1,1,1] row_mask:0xf bank_mask:0xf
	v_mul_f32_dpp v119, -v135, v12 quad_perm:[1,1,1,1] row_mask:0xf bank_mask:0xf
	ds_read_b32 v183, v124 offset:64
	v_fmac_f32_dpp v116, -v134, v7 quad_perm:[2,2,2,2] row_mask:0xf bank_mask:0xf
	v_fmac_f32_dpp v117, -v135, v13 quad_perm:[2,2,2,2] row_mask:0xf bank_mask:0xf
	v_fmac_f32_dpp v118, -v134, v14 quad_perm:[3,3,3,3] row_mask:0xf bank_mask:0xf
	ds_read_u16_d16_hi v248, v123 offset:4352
	v_fmac_f32_dpp v119, -v135, v15 quad_perm:[3,3,3,3] row_mask:0xf bank_mask:0xf
	v_fmac_f32_dpp v116, -v136, v16 quad_perm:[0,0,0,0] row_mask:0xf bank_mask:0xf
	v_fmac_f32_dpp v117, -v137, v17 quad_perm:[0,0,0,0] row_mask:0xf bank_mask:0xf
	ds_read_b64 v[150:151], v125 offset:4624
	v_fmac_f32_dpp v118, -v136, v19 quad_perm:[1,1,1,1] row_mask:0xf bank_mask:0xf
	v_fmac_f32_dpp v119, -v137, v20 quad_perm:[1,1,1,1] row_mask:0xf bank_mask:0xf
	v_fmac_f32_dpp v116, -v136, v21 quad_perm:[2,2,2,2] row_mask:0xf bank_mask:0xf
	ds_read_b64 v[152:153], v125 offset:4656
	v_add_f32_e32 v121, v117, v116
	v_add_f32_e32 v122, v118, v119
	v_add_f32_e32 v22, v122, v121
	s_waitcnt lgkmcnt(10)
	v_mul_f32_dpp v120, v138, v4 quad_perm:[0,0,0,0] row_mask:0xf bank_mask:0xf
	v_fma_f32 v116, v181, v246, -v120
	v_mul_f32_dpp v117, -v139, v5 quad_perm:[0,0,0,0] row_mask:0xf bank_mask:0xf
	v_mul_f32_dpp v118, -v138, v6 quad_perm:[1,1,1,1] row_mask:0xf bank_mask:0xf
	v_mul_f32_dpp v119, -v139, v12 quad_perm:[1,1,1,1] row_mask:0xf bank_mask:0xf
	ds_read_b64 v[154:155], v125 offset:4688
	v_fmac_f32_dpp v116, -v138, v7 quad_perm:[2,2,2,2] row_mask:0xf bank_mask:0xf
	v_fmac_f32_dpp v117, -v139, v13 quad_perm:[2,2,2,2] row_mask:0xf bank_mask:0xf
	v_fmac_f32_dpp v118, -v138, v14 quad_perm:[3,3,3,3] row_mask:0xf bank_mask:0xf
	ds_read_b32 v185, v124 offset:68
	v_fmac_f32_dpp v119, -v139, v15 quad_perm:[3,3,3,3] row_mask:0xf bank_mask:0xf
	v_fmac_f32_dpp v116, -v140, v16 quad_perm:[0,0,0,0] row_mask:0xf bank_mask:0xf
	v_fmac_f32_dpp v117, -v141, v17 quad_perm:[0,0,0,0] row_mask:0xf bank_mask:0xf
	ds_read_u16_d16_hi v249, v123 offset:4624
	v_fmac_f32_dpp v118, -v140, v19 quad_perm:[1,1,1,1] row_mask:0xf bank_mask:0xf
	v_fmac_f32_dpp v119, -v141, v20 quad_perm:[1,1,1,1] row_mask:0xf bank_mask:0xf
	v_fmac_f32_dpp v116, -v140, v21 quad_perm:[2,2,2,2] row_mask:0xf bank_mask:0xf
	ds_read_b64 v[156:157], v125 offset:4896
	v_fmac_f32_dpp v117, -v141, v22 quad_perm:[2,2,2,2] row_mask:0xf bank_mask:0xf
	v_add_f32_e32 v121, v117, v116
	v_add_f32_e32 v122, v118, v119
	v_add_f32_e32 v23, v122, v121
	s_waitcnt lgkmcnt(10)
	v_mul_f32_dpp v120, v142, v4 quad_perm:[0,0,0,0] row_mask:0xf bank_mask:0xf
	v_fma_f32 v116, v182, v247, -v120
	v_mul_f32_dpp v117, -v143, v5 quad_perm:[0,0,0,0] row_mask:0xf bank_mask:0xf
	v_mul_f32_dpp v118, -v142, v6 quad_perm:[1,1,1,1] row_mask:0xf bank_mask:0xf
	ds_read_b64 v[158:159], v125 offset:4928
	v_mul_f32_dpp v119, -v143, v12 quad_perm:[1,1,1,1] row_mask:0xf bank_mask:0xf
	v_fmac_f32_dpp v116, -v142, v7 quad_perm:[2,2,2,2] row_mask:0xf bank_mask:0xf
	v_fmac_f32_dpp v117, -v143, v13 quad_perm:[2,2,2,2] row_mask:0xf bank_mask:0xf
	ds_read_b64 v[160:161], v125 offset:4960
	v_fmac_f32_dpp v118, -v142, v14 quad_perm:[3,3,3,3] row_mask:0xf bank_mask:0xf
	v_fmac_f32_dpp v119, -v143, v15 quad_perm:[3,3,3,3] row_mask:0xf bank_mask:0xf
	v_fmac_f32_dpp v116, -v144, v16 quad_perm:[0,0,0,0] row_mask:0xf bank_mask:0xf
	ds_read_b32 v208, v124 offset:72
	v_fmac_f32_dpp v117, -v145, v17 quad_perm:[0,0,0,0] row_mask:0xf bank_mask:0xf
	v_fmac_f32_dpp v118, -v144, v19 quad_perm:[1,1,1,1] row_mask:0xf bank_mask:0xf
	v_fmac_f32_dpp v119, -v145, v20 quad_perm:[1,1,1,1] row_mask:0xf bank_mask:0xf
	ds_read_u16_d16_hi v250, v123 offset:4896
	v_fmac_f32_dpp v116, -v144, v21 quad_perm:[2,2,2,2] row_mask:0xf bank_mask:0xf
	v_fmac_f32_dpp v117, -v145, v22 quad_perm:[2,2,2,2] row_mask:0xf bank_mask:0xf
	v_fmac_f32_dpp v118, -v144, v23 quad_perm:[3,3,3,3] row_mask:0xf bank_mask:0xf
	ds_read_b64 v[162:163], v125 offset:5168
	v_add_f32_e32 v121, v117, v116
	v_add_f32_e32 v122, v118, v119
	v_add_f32_e32 v24, v122, v121
	s_waitcnt lgkmcnt(11)
	v_mul_f32_dpp v120, v146, v4 quad_perm:[0,0,0,0] row_mask:0xf bank_mask:0xf
	v_fma_f32 v116, v183, v248, -v120
	v_mul_f32_dpp v117, -v147, v5 quad_perm:[0,0,0,0] row_mask:0xf bank_mask:0xf
	v_mul_f32_dpp v118, -v146, v6 quad_perm:[1,1,1,1] row_mask:0xf bank_mask:0xf
	v_mul_f32_dpp v119, -v147, v12 quad_perm:[1,1,1,1] row_mask:0xf bank_mask:0xf
	ds_read_b64 v[186:187], v125 offset:5200
	v_fmac_f32_dpp v116, -v146, v7 quad_perm:[2,2,2,2] row_mask:0xf bank_mask:0xf
	v_fmac_f32_dpp v117, -v147, v13 quad_perm:[2,2,2,2] row_mask:0xf bank_mask:0xf
	v_fmac_f32_dpp v118, -v146, v14 quad_perm:[3,3,3,3] row_mask:0xf bank_mask:0xf
	ds_read_b64 v[188:189], v125 offset:5232
	v_fmac_f32_dpp v119, -v147, v15 quad_perm:[3,3,3,3] row_mask:0xf bank_mask:0xf
	v_fmac_f32_dpp v116, -v148, v16 quad_perm:[0,0,0,0] row_mask:0xf bank_mask:0xf
	v_fmac_f32_dpp v117, -v149, v17 quad_perm:[0,0,0,0] row_mask:0xf bank_mask:0xf
	ds_read_b32 v209, v124 offset:76
	v_fmac_f32_dpp v118, -v148, v19 quad_perm:[1,1,1,1] row_mask:0xf bank_mask:0xf
	v_fmac_f32_dpp v119, -v149, v20 quad_perm:[1,1,1,1] row_mask:0xf bank_mask:0xf
	v_fmac_f32_dpp v116, -v148, v21 quad_perm:[2,2,2,2] row_mask:0xf bank_mask:0xf
	ds_read_u16_d16_hi v251, v123 offset:5168
	v_fmac_f32_dpp v117, -v149, v22 quad_perm:[2,2,2,2] row_mask:0xf bank_mask:0xf
	v_fmac_f32_dpp v118, -v148, v23 quad_perm:[3,3,3,3] row_mask:0xf bank_mask:0xf
	v_fmac_f32_dpp v119, -v149, v24 quad_perm:[3,3,3,3] row_mask:0xf bank_mask:0xf
	ds_read_b64 v[190:191], v125 offset:5440
	v_add_f32_e32 v121, v117, v116
	v_add_f32_e32 v122, v118, v119
	v_add_f32_e32 v25, v122, v121
	s_waitcnt lgkmcnt(11)
; __device__ __forceinline__ float bf2f(bf16 v) { return __uint_as_float(((unsigned)v) << 16); }
; #define GDN_LOADROW(buf, rr_, i_) do { _Pragma("unroll") for (int j4 = 0; j4 < ((i_) + 3) / 4; ++j4) buf[j4] = *(const f32x4*)(Lm + (i_) * GP_LSTR + 4 * j4); rr_ = bf2f(*(const bf16*)(xsrc + (i_) * GP_STR * 2)) * scl[i_]; } while (0)
; template <int STRIP> __device__ __forceinline__ void ph_gdn_prep_fast(const bf16* __restrict__ proj, const float* __restrict__ small, const float* __restrict__ conv_w, const float* __restrict__ a_log, const float* __restrict__ dt_bias, ...
;     ...
;             rA = bf2f(*(const bf16*)xsrc) * scl[0];
;     ...
; #pragma unroll
;             for (int i = 0; i < 64; i += 2) {
;                 GDN_LOADROW(bB, rB, i + 1);
;                 GDN_ROW(bA, rA, i);
;                 if (i + 2 < 64) GDN_LOADROW(bA, rA, i + 2);
;                 GDN_ROW(bB, rB, i + 1);
;             }
	v_mul_f32_dpp v120, v150, v4 quad_perm:[0,0,0,0] row_mask:0xf bank_mask:0xf
	v_fma_f32 v116, v185, v249, -v120
	v_mul_f32_dpp v117, -v151, v5 quad_perm:[0,0,0,0] row_mask:0xf bank_mask:0xf
	v_mul_f32_dpp v118, -v150, v6 quad_perm:[1,1,1,1] row_mask:0xf bank_mask:0xf
	v_mul_f32_dpp v119, -v151, v12 quad_perm:[1,1,1,1] row_mask:0xf bank_mask:0xf
	ds_read_b64 v[192:193], v125 offset:5472
	v_fmac_f32_dpp v116, -v150, v7 quad_perm:[2,2,2,2] row_mask:0xf bank_mask:0xf
	v_fmac_f32_dpp v117, -v151, v13 quad_perm:[2,2,2,2] row_mask:0xf bank_mask:0xf
	v_fmac_f32_dpp v118, -v150, v14 quad_perm:[3,3,3,3] row_mask:0xf bank_mask:0xf
	ds_read_b64 v[194:195], v125 offset:5504
	v_fmac_f32_dpp v119, -v151, v15 quad_perm:[3,3,3,3] row_mask:0xf bank_mask:0xf
	v_fmac_f32_dpp v116, -v152, v16 quad_perm:[0,0,0,0] row_mask:0xf bank_mask:0xf
	v_fmac_f32_dpp v117, -v153, v17 quad_perm:[0,0,0,0] row_mask:0xf bank_mask:0xf
	ds_read_b32 v210, v124 offset:80
	v_fmac_f32_dpp v118, -v152, v19 quad_perm:[1,1,1,1] row_mask:0xf bank_mask:0xf
	v_fmac_f32_dpp v119, -v153, v20 quad_perm:[1,1,1,1] row_mask:0xf bank_mask:0xf
	v_fmac_f32_dpp v116, -v152, v21 quad_perm:[2,2,2,2] row_mask:0xf bank_mask:0xf
	ds_read_u16_d16_hi v252, v123 offset:5440
	v_fmac_f32_dpp v117, -v153, v22 quad_perm:[2,2,2,2] row_mask:0xf bank_mask:0xf
	v_fmac_f32_dpp v118, -v152, v23 quad_perm:[3,3,3,3] row_mask:0xf bank_mask:0xf
	v_fmac_f32_dpp v119, -v153, v24 quad_perm:[3,3,3,3] row_mask:0xf bank_mask:0xf
	ds_read_b64 v[196:197], v125 offset:5712
	v_fmac_f32_dpp v116, -v154, v25 quad_perm:[0,0,0,0] row_mask:0xf bank_mask:0xf
	v_add_f32_e32 v121, v117, v116
	v_add_f32_e32 v122, v118, v119
	v_add_f32_e32 v27, v122, v121
	s_waitcnt lgkmcnt(11)
	v_mul_f32_dpp v120, v156, v4 quad_perm:[0,0,0,0] row_mask:0xf bank_mask:0xf
	v_fma_f32 v116, v208, v250, -v120
	v_mul_f32_dpp v117, -v157, v5 quad_perm:[0,0,0,0] row_mask:0xf bank_mask:0xf
	v_mul_f32_dpp v118, -v156, v6 quad_perm:[1,1,1,1] row_mask:0xf bank_mask:0xf
	ds_read_b64 v[198:199], v125 offset:5744
	v_mul_f32_dpp v119, -v157, v12 quad_perm:[1,1,1,1] row_mask:0xf bank_mask:0xf
	v_fmac_f32_dpp v116, -v156, v7 quad_perm:[2,2,2,2] row_mask:0xf bank_mask:0xf
	v_fmac_f32_dpp v117, -v157, v13 quad_perm:[2,2,2,2] row_mask:0xf bank_mask:0xf
	ds_read_b64 v[200:201], v125 offset:5776
	v_fmac_f32_dpp v118, -v156, v14 quad_perm:[3,3,3,3] row_mask:0xf bank_mask:0xf
	v_fmac_f32_dpp v119, -v157, v15 quad_perm:[3,3,3,3] row_mask:0xf bank_mask:0xf
	v_fmac_f32_dpp v116, -v158, v16 quad_perm:[0,0,0,0] row_mask:0xf bank_mask:0xf
	ds_read_b32 v211, v124 offset:84
	v_fmac_f32_dpp v117, -v159, v17 quad_perm:[0,0,0,0] row_mask:0xf bank_mask:0xf
	v_fmac_f32_dpp v118, -v158, v19 quad_perm:[1,1,1,1] row_mask:0xf bank_mask:0xf
	v_fmac_f32_dpp v119, -v159, v20 quad_perm:[1,1,1,1] row_mask:0xf bank_mask:0xf
	ds_read_u16_d16_hi v253, v123 offset:5712
	v_fmac_f32_dpp v116, -v158, v21 quad_perm:[2,2,2,2] row_mask:0xf bank_mask:0xf
	v_fmac_f32_dpp v117, -v159, v22 quad_perm:[2,2,2,2] row_mask:0xf bank_mask:0xf
	v_fmac_f32_dpp v118, -v158, v23 quad_perm:[3,3,3,3] row_mask:0xf bank_mask:0xf
	ds_read_b64 v[202:203], v125 offset:5984
	v_fmac_f32_dpp v119, -v159, v24 quad_perm:[3,3,3,3] row_mask:0xf bank_mask:0xf
	v_fmac_f32_dpp v116, -v160, v25 quad_perm:[0,0,0,0] row_mask:0xf bank_mask:0xf
	v_fmac_f32_dpp v117, -v161, v27 quad_perm:[0,0,0,0] row_mask:0xf bank_mask:0xf
	ds_read_b64 v[204:205], v125 offset:6016
	v_add_f32_e32 v121, v117, v116
	v_add_f32_e32 v122, v118, v119
	v_add_f32_e32 v28, v122, v121
	s_waitcnt lgkmcnt(12)
	v_mul_f32_dpp v120, v162, v4 quad_perm:[0,0,0,0] row_mask:0xf bank_mask:0xf
	v_fma_f32 v116, v209, v251, -v120
	v_mul_f32_dpp v117, -v163, v5 quad_perm:[0,0,0,0] row_mask:0xf bank_mask:0xf
	v_mul_f32_dpp v118, -v162, v6 quad_perm:[1,1,1,1] row_mask:0xf bank_mask:0xf
	v_mul_f32_dpp v119, -v163, v12 quad_perm:[1,1,1,1] row_mask:0xf bank_mask:0xf
	ds_read_b64 v[206:207], v125 offset:6048
	v_fmac_f32_dpp v116, -v162, v7 quad_perm:[2,2,2,2] row_mask:0xf bank_mask:0xf
	v_fmac_f32_dpp v117, -v163, v13 quad_perm:[2,2,2,2] row_mask:0xf bank_mask:0xf
	v_fmac_f32_dpp v118, -v162, v14 quad_perm:[3,3,3,3] row_mask:0xf bank_mask:0xf
	ds_read_b32 v212, v124 offset:88
	v_fmac_f32_dpp v119, -v163, v15 quad_perm:[3,3,3,3] row_mask:0xf bank_mask:0xf
	v_fmac_f32_dpp v116, -v186, v16 quad_perm:[0,0,0,0] row_mask:0xf bank_mask:0xf
	v_fmac_f32_dpp v117, -v187, v17 quad_perm:[0,0,0,0] row_mask:0xf bank_mask:0xf
	ds_read_u16_d16_hi v126, v123 offset:5984
	v_fmac_f32_dpp v118, -v186, v19 quad_perm:[1,1,1,1] row_mask:0xf bank_mask:0xf
	v_fmac_f32_dpp v119, -v187, v20 quad_perm:[1,1,1,1] row_mask:0xf bank_mask:0xf
	v_fmac_f32_dpp v116, -v186, v21 quad_perm:[2,2,2,2] row_mask:0xf bank_mask:0xf
	ds_read_b64 v[164:165], v125 offset:6256
	v_fmac_f32_dpp v117, -v187, v22 quad_perm:[2,2,2,2] row_mask:0xf bank_mask:0xf
	v_fmac_f32_dpp v118, -v186, v23 quad_perm:[3,3,3,3] row_mask:0xf bank_mask:0xf
	v_fmac_f32_dpp v119, -v187, v24 quad_perm:[3,3,3,3] row_mask:0xf bank_mask:0xf
	ds_read_b64 v[166:167], v125 offset:6288
	v_fmac_f32_dpp v116, -v188, v25 quad_perm:[0,0,0,0] row_mask:0xf bank_mask:0xf
	v_fmac_f32_dpp v117, -v189, v27 quad_perm:[0,0,0,0] row_mask:0xf bank_mask:0xf
	v_fmac_f32_dpp v118, -v188, v28 quad_perm:[1,1,1,1] row_mask:0xf bank_mask:0xf
	ds_read_b64 v[168:169], v125 offset:6320
	v_add_f32_e32 v121, v117, v116
	v_add_f32_e32 v122, v118, v119
	v_add_f32_e32 v29, v122, v121
	s_waitcnt lgkmcnt(13)
; __device__ __forceinline__ float bf2f(bf16 v) { return __uint_as_float(((unsigned)v) << 16); }
; #define GDN_LOADROW(buf, rr_, i_) do { _Pragma("unroll") for (int j4 = 0; j4 < ((i_) + 3) / 4; ++j4) buf[j4] = *(const f32x4*)(Lm + (i_) * GP_LSTR + 4 * j4); rr_ = bf2f(*(const bf16*)(xsrc + (i_) * GP_STR * 2)) * scl[i_]; } while (0)
; template <int STRIP> __device__ __forceinline__ void ph_gdn_prep_fast(const bf16* __restrict__ proj, const float* __restrict__ small, const float* __restrict__ conv_w, const float* __restrict__ a_log, const float* __restrict__ dt_bias, ...
;     ...
;             float U[64];
;             const float* scl = isw ? (sgc + 256) : sbeta;
;             f32x4 bA[16], bB[16]; float rA, rB = 0.f;
;             rA = bf2f(*(const bf16*)xsrc) * scl[0];
;     ...
; #pragma unroll
;             for (int i = 0; i < 64; i += 2) {
;                 GDN_LOADROW(bB, rB, i + 1);
;                 GDN_ROW(bA, rA, i);
;                 if (i + 2 < 64) GDN_LOADROW(bA, rA, i + 2);
;                 GDN_ROW(bB, rB, i + 1);
;             }
	v_mul_f32_dpp v120, v190, v4 quad_perm:[0,0,0,0] row_mask:0xf bank_mask:0xf
	v_fma_f32 v116, v210, v252, -v120
	v_mul_f32_dpp v117, -v191, v5 quad_perm:[0,0,0,0] row_mask:0xf bank_mask:0xf
	v_mul_f32_dpp v118, -v190, v6 quad_perm:[1,1,1,1] row_mask:0xf bank_mask:0xf
	v_mul_f32_dpp v119, -v191, v12 quad_perm:[1,1,1,1] row_mask:0xf bank_mask:0xf
	ds_read_b32 v213, v124 offset:92
	v_fmac_f32_dpp v116, -v190, v7 quad_perm:[2,2,2,2] row_mask:0xf bank_mask:0xf
	v_fmac_f32_dpp v117, -v191, v13 quad_perm:[2,2,2,2] row_mask:0xf bank_mask:0xf
	v_fmac_f32_dpp v118, -v190, v14 quad_perm:[3,3,3,3] row_mask:0xf bank_mask:0xf
	ds_read_u16_d16_hi v127, v123 offset:6256
	v_fmac_f32_dpp v119, -v191, v15 quad_perm:[3,3,3,3] row_mask:0xf bank_mask:0xf
	v_fmac_f32_dpp v116, -v192, v16 quad_perm:[0,0,0,0] row_mask:0xf bank_mask:0xf
	v_fmac_f32_dpp v117, -v193, v17 quad_perm:[0,0,0,0] row_mask:0xf bank_mask:0xf
	ds_read_b64 v[170:171], v125 offset:6528
	v_fmac_f32_dpp v118, -v192, v19 quad_perm:[1,1,1,1] row_mask:0xf bank_mask:0xf
	v_fmac_f32_dpp v119, -v193, v20 quad_perm:[1,1,1,1] row_mask:0xf bank_mask:0xf
	v_fmac_f32_dpp v116, -v192, v21 quad_perm:[2,2,2,2] row_mask:0xf bank_mask:0xf
	ds_read_b64 v[132:133], v125 offset:6560
	v_fmac_f32_dpp v117, -v193, v22 quad_perm:[2,2,2,2] row_mask:0xf bank_mask:0xf
	v_fmac_f32_dpp v118, -v192, v23 quad_perm:[3,3,3,3] row_mask:0xf bank_mask:0xf
	v_fmac_f32_dpp v119, -v193, v24 quad_perm:[3,3,3,3] row_mask:0xf bank_mask:0xf
	ds_read_b64 v[134:135], v125 offset:6592
	v_fmac_f32_dpp v116, -v194, v25 quad_perm:[0,0,0,0] row_mask:0xf bank_mask:0xf
	v_fmac_f32_dpp v117, -v195, v27 quad_perm:[0,0,0,0] row_mask:0xf bank_mask:0xf
	v_fmac_f32_dpp v118, -v194, v28 quad_perm:[1,1,1,1] row_mask:0xf bank_mask:0xf
	ds_read_b32 v214, v124 offset:96
	v_fmac_f32_dpp v119, -v195, v29 quad_perm:[1,1,1,1] row_mask:0xf bank_mask:0xf
	v_add_f32_e32 v121, v117, v116
	v_add_f32_e32 v122, v118, v119
	v_add_f32_e32 v30, v122, v121
	s_waitcnt lgkmcnt(14)
	v_mul_f32_dpp v120, v196, v4 quad_perm:[0,0,0,0] row_mask:0xf bank_mask:0xf
	v_fma_f32 v116, v211, v253, -v120
	v_mul_f32_dpp v117, -v197, v5 quad_perm:[0,0,0,0] row_mask:0xf bank_mask:0xf
	v_mul_f32_dpp v118, -v196, v6 quad_perm:[1,1,1,1] row_mask:0xf bank_mask:0xf
	ds_read_u16_d16_hi v244, v123 offset:6528
	v_mul_f32_dpp v119, -v197, v12 quad_perm:[1,1,1,1] row_mask:0xf bank_mask:0xf
	v_fmac_f32_dpp v116, -v196, v7 quad_perm:[2,2,2,2] row_mask:0xf bank_mask:0xf
	v_fmac_f32_dpp v117, -v197, v13 quad_perm:[2,2,2,2] row_mask:0xf bank_mask:0xf
	ds_read_b64 v[136:137], v125 offset:6800
	v_fmac_f32_dpp v118, -v196, v14 quad_perm:[3,3,3,3] row_mask:0xf bank_mask:0xf
	v_fmac_f32_dpp v119, -v197, v15 quad_perm:[3,3,3,3] row_mask:0xf bank_mask:0xf
	v_fmac_f32_dpp v116, -v198, v16 quad_perm:[0,0,0,0] row_mask:0xf bank_mask:0xf
	ds_read_b64 v[138:139], v125 offset:6832
	v_fmac_f32_dpp v117, -v199, v17 quad_perm:[0,0,0,0] row_mask:0xf bank_mask:0xf
	v_fmac_f32_dpp v118, -v198, v19 quad_perm:[1,1,1,1] row_mask:0xf bank_mask:0xf
	v_fmac_f32_dpp v119, -v199, v20 quad_perm:[1,1,1,1] row_mask:0xf bank_mask:0xf
	ds_read_b64 v[140:141], v125 offset:6864
	v_fmac_f32_dpp v116, -v198, v21 quad_perm:[2,2,2,2] row_mask:0xf bank_mask:0xf
	v_fmac_f32_dpp v117, -v199, v22 quad_perm:[2,2,2,2] row_mask:0xf bank_mask:0xf
	v_fmac_f32_dpp v118, -v198, v23 quad_perm:[3,3,3,3] row_mask:0xf bank_mask:0xf
	ds_read_b64 v[142:143], v125 offset:6896
	v_fmac_f32_dpp v119, -v199, v24 quad_perm:[3,3,3,3] row_mask:0xf bank_mask:0xf
	v_fmac_f32_dpp v116, -v200, v25 quad_perm:[0,0,0,0] row_mask:0xf bank_mask:0xf
	v_fmac_f32_dpp v117, -v201, v27 quad_perm:[0,0,0,0] row_mask:0xf bank_mask:0xf
	ds_read_b32 v215, v124 offset:100
	v_fmac_f32_dpp v118, -v200, v28 quad_perm:[1,1,1,1] row_mask:0xf bank_mask:0xf
	v_fmac_f32_dpp v119, -v201, v29 quad_perm:[1,1,1,1] row_mask:0xf bank_mask:0xf
	v_fmac_f32_dpp v116, -v200, v30 quad_perm:[2,2,2,2] row_mask:0xf bank_mask:0xf
	ds_read_u16_d16_hi v245, v123 offset:6800
	v_add_f32_e32 v121, v117, v116
	v_add_f32_e32 v122, v118, v119
	v_add_f32_e32 v31, v122, v121
	s_waitcnt lgkmcnt(15)
	v_mul_f32_dpp v120, v202, v4 quad_perm:[0,0,0,0] row_mask:0xf bank_mask:0xf
	v_fma_f32 v116, v212, v126, -v120
	v_mul_f32_dpp v117, -v203, v5 quad_perm:[0,0,0,0] row_mask:0xf bank_mask:0xf
	v_mul_f32_dpp v118, -v202, v6 quad_perm:[1,1,1,1] row_mask:0xf bank_mask:0xf
	v_mul_f32_dpp v119, -v203, v12 quad_perm:[1,1,1,1] row_mask:0xf bank_mask:0xf
	ds_read_b64 v[144:145], v125 offset:7072
	v_fmac_f32_dpp v116, -v202, v7 quad_perm:[2,2,2,2] row_mask:0xf bank_mask:0xf
	v_fmac_f32_dpp v117, -v203, v13 quad_perm:[2,2,2,2] row_mask:0xf bank_mask:0xf
	v_fmac_f32_dpp v118, -v202, v14 quad_perm:[3,3,3,3] row_mask:0xf bank_mask:0xf
	ds_read_b64 v[146:147], v125 offset:7104
	v_fmac_f32_dpp v119, -v203, v15 quad_perm:[3,3,3,3] row_mask:0xf bank_mask:0xf
	v_fmac_f32_dpp v116, -v204, v16 quad_perm:[0,0,0,0] row_mask:0xf bank_mask:0xf
	v_fmac_f32_dpp v117, -v205, v17 quad_perm:[0,0,0,0] row_mask:0xf bank_mask:0xf
	ds_read_b64 v[148:149], v125 offset:7136
	v_fmac_f32_dpp v118, -v204, v19 quad_perm:[1,1,1,1] row_mask:0xf bank_mask:0xf
	v_fmac_f32_dpp v119, -v205, v20 quad_perm:[1,1,1,1] row_mask:0xf bank_mask:0xf
	v_fmac_f32_dpp v116, -v204, v21 quad_perm:[2,2,2,2] row_mask:0xf bank_mask:0xf
	ds_read_b64 v[150:151], v125 offset:7168
	v_fmac_f32_dpp v117, -v205, v22 quad_perm:[2,2,2,2] row_mask:0xf bank_mask:0xf
	v_fmac_f32_dpp v118, -v204, v23 quad_perm:[3,3,3,3] row_mask:0xf bank_mask:0xf
	v_fmac_f32_dpp v119, -v205, v24 quad_perm:[3,3,3,3] row_mask:0xf bank_mask:0xf
	ds_read_b32 v216, v124 offset:104
	v_fmac_f32_dpp v116, -v206, v25 quad_perm:[0,0,0,0] row_mask:0xf bank_mask:0xf
	v_fmac_f32_dpp v117, -v207, v27 quad_perm:[0,0,0,0] row_mask:0xf bank_mask:0xf
	v_fmac_f32_dpp v118, -v206, v28 quad_perm:[1,1,1,1] row_mask:0xf bank_mask:0xf
	ds_read_u16_d16_hi v246, v123 offset:7072
	v_fmac_f32_dpp v119, -v207, v29 quad_perm:[1,1,1,1] row_mask:0xf bank_mask:0xf
	v_fmac_f32_dpp v116, -v206, v30 quad_perm:[2,2,2,2] row_mask:0xf bank_mask:0xf
	v_fmac_f32_dpp v117, -v207, v31 quad_perm:[2,2,2,2] row_mask:0xf bank_mask:0xf
	ds_read_b64 v[152:153], v125 offset:7344
	v_add_f32_e32 v121, v117, v116
	v_add_f32_e32 v122, v118, v119
	v_add_f32_e32 v32, v122, v121
	s_waitcnt lgkmcnt(15)
; __device__ __forceinline__ float bf2f(bf16 v) { return __uint_as_float(((unsigned)v) << 16); }
; #define GDN_LOADROW(buf, rr_, i_) do { _Pragma("unroll") for (int j4 = 0; j4 < ((i_) + 3) / 4; ++j4) buf[j4] = *(const f32x4*)(Lm + (i_) * GP_LSTR + 4 * j4); rr_ = bf2f(*(const bf16*)(xsrc + (i_) * GP_STR * 2)) * scl[i_]; } while (0)
; template <int STRIP> __device__ __forceinline__ void ph_gdn_prep_fast(const bf16* __restrict__ proj, const float* __restrict__ small, const float* __restrict__ conv_w, const float* __restrict__ a_log, const float* __restrict__ dt_bias, ...
;     ...
;             float U[64];
;             const float* scl = isw ? (sgc + 256) : sbeta;
;             f32x4 bA[16], bB[16]; float rA, rB = 0.f;
;             rA = bf2f(*(const bf16*)xsrc) * scl[0];
;     ...
; #pragma unroll
;             for (int i = 0; i < 64; i += 2) {
;                 GDN_LOADROW(bB, rB, i + 1);
;                 GDN_ROW(bA, rA, i);
;                 if (i + 2 < 64) GDN_LOADROW(bA, rA, i + 2);
;                 GDN_ROW(bB, rB, i + 1);
;             }
	v_mul_f32_dpp v120, v164, v4 quad_perm:[0,0,0,0] row_mask:0xf bank_mask:0xf
	v_fma_f32 v116, v213, v127, -v120
	v_mul_f32_dpp v117, -v165, v5 quad_perm:[0,0,0,0] row_mask:0xf bank_mask:0xf
	v_mul_f32_dpp v118, -v164, v6 quad_perm:[1,1,1,1] row_mask:0xf bank_mask:0xf
	v_mul_f32_dpp v119, -v165, v12 quad_perm:[1,1,1,1] row_mask:0xf bank_mask:0xf
	ds_read_b64 v[154:155], v125 offset:7376
	v_fmac_f32_dpp v116, -v164, v7 quad_perm:[2,2,2,2] row_mask:0xf bank_mask:0xf
	v_fmac_f32_dpp v117, -v165, v13 quad_perm:[2,2,2,2] row_mask:0xf bank_mask:0xf
	v_fmac_f32_dpp v118, -v164, v14 quad_perm:[3,3,3,3] row_mask:0xf bank_mask:0xf
	ds_read_b64 v[156:157], v125 offset:7408
	v_fmac_f32_dpp v119, -v165, v15 quad_perm:[3,3,3,3] row_mask:0xf bank_mask:0xf
	v_fmac_f32_dpp v116, -v166, v16 quad_perm:[0,0,0,0] row_mask:0xf bank_mask:0xf
	v_fmac_f32_dpp v117, -v167, v17 quad_perm:[0,0,0,0] row_mask:0xf bank_mask:0xf
	ds_read_b64 v[158:159], v125 offset:7440
	v_fmac_f32_dpp v118, -v166, v19 quad_perm:[1,1,1,1] row_mask:0xf bank_mask:0xf
	v_fmac_f32_dpp v119, -v167, v20 quad_perm:[1,1,1,1] row_mask:0xf bank_mask:0xf
	v_fmac_f32_dpp v116, -v166, v21 quad_perm:[2,2,2,2] row_mask:0xf bank_mask:0xf
	ds_read_b32 v217, v124 offset:108
	v_fmac_f32_dpp v117, -v167, v22 quad_perm:[2,2,2,2] row_mask:0xf bank_mask:0xf
	v_fmac_f32_dpp v118, -v166, v23 quad_perm:[3,3,3,3] row_mask:0xf bank_mask:0xf
	v_fmac_f32_dpp v119, -v167, v24 quad_perm:[3,3,3,3] row_mask:0xf bank_mask:0xf
	ds_read_u16_d16_hi v247, v123 offset:7344
	v_fmac_f32_dpp v116, -v168, v25 quad_perm:[0,0,0,0] row_mask:0xf bank_mask:0xf
	v_fmac_f32_dpp v117, -v169, v27 quad_perm:[0,0,0,0] row_mask:0xf bank_mask:0xf
	v_fmac_f32_dpp v118, -v168, v28 quad_perm:[1,1,1,1] row_mask:0xf bank_mask:0xf
	v_fmac_f32_dpp v119, -v169, v29 quad_perm:[1,1,1,1] row_mask:0xf bank_mask:0xf
	v_fmac_f32_dpp v116, -v168, v30 quad_perm:[2,2,2,2] row_mask:0xf bank_mask:0xf
	v_fmac_f32_dpp v117, -v169, v31 quad_perm:[2,2,2,2] row_mask:0xf bank_mask:0xf
	v_fmac_f32_dpp v118, -v168, v32 quad_perm:[3,3,3,3] row_mask:0xf bank_mask:0xf
	v_add_f32_e32 v121, v117, v116
	v_add_f32_e32 v122, v118, v119
	v_add_f32_e32 v33, v122, v121
	s_waitcnt lgkmcnt(15)
	v_mul_f32_dpp v120, v170, v4 quad_perm:[0,0,0,0] row_mask:0xf bank_mask:0xf
	v_fma_f32 v116, v214, v244, -v120
	v_mul_f32_dpp v117, -v171, v5 quad_perm:[0,0,0,0] row_mask:0xf bank_mask:0xf
	v_mul_f32_dpp v118, -v170, v6 quad_perm:[1,1,1,1] row_mask:0xf bank_mask:0xf
	ds_read_b64 v[160:161], v125 offset:7616
	v_mul_f32_dpp v119, -v171, v12 quad_perm:[1,1,1,1] row_mask:0xf bank_mask:0xf
	v_fmac_f32_dpp v116, -v170, v7 quad_perm:[2,2,2,2] row_mask:0xf bank_mask:0xf
	v_fmac_f32_dpp v117, -v171, v13 quad_perm:[2,2,2,2] row_mask:0xf bank_mask:0xf
	ds_read_b64 v[162:163], v125 offset:7648
	v_fmac_f32_dpp v118, -v170, v14 quad_perm:[3,3,3,3] row_mask:0xf bank_mask:0xf
	v_fmac_f32_dpp v119, -v171, v15 quad_perm:[3,3,3,3] row_mask:0xf bank_mask:0xf
	v_fmac_f32_dpp v116, -v132, v16 quad_perm:[0,0,0,0] row_mask:0xf bank_mask:0xf
	ds_read_b64 v[186:187], v125 offset:7680
	v_fmac_f32_dpp v117, -v133, v17 quad_perm:[0,0,0,0] row_mask:0xf bank_mask:0xf
	v_fmac_f32_dpp v118, -v132, v19 quad_perm:[1,1,1,1] row_mask:0xf bank_mask:0xf
	v_fmac_f32_dpp v119, -v133, v20 quad_perm:[1,1,1,1] row_mask:0xf bank_mask:0xf
	ds_read_b64 v[188:189], v125 offset:7712
	v_fmac_f32_dpp v116, -v132, v21 quad_perm:[2,2,2,2] row_mask:0xf bank_mask:0xf
	v_fmac_f32_dpp v117, -v133, v22 quad_perm:[2,2,2,2] row_mask:0xf bank_mask:0xf
	v_fmac_f32_dpp v118, -v132, v23 quad_perm:[3,3,3,3] row_mask:0xf bank_mask:0xf
	ds_read_b32 v218, v124 offset:112
	v_fmac_f32_dpp v119, -v133, v24 quad_perm:[3,3,3,3] row_mask:0xf bank_mask:0xf
	v_fmac_f32_dpp v116, -v134, v25 quad_perm:[0,0,0,0] row_mask:0xf bank_mask:0xf
	v_fmac_f32_dpp v117, -v135, v27 quad_perm:[0,0,0,0] row_mask:0xf bank_mask:0xf
	ds_read_u16_d16_hi v248, v123 offset:7616
	v_fmac_f32_dpp v118, -v134, v28 quad_perm:[1,1,1,1] row_mask:0xf bank_mask:0xf
	v_fmac_f32_dpp v119, -v135, v29 quad_perm:[1,1,1,1] row_mask:0xf bank_mask:0xf
	v_fmac_f32_dpp v116, -v134, v30 quad_perm:[2,2,2,2] row_mask:0xf bank_mask:0xf
	v_fmac_f32_dpp v117, -v135, v31 quad_perm:[2,2,2,2] row_mask:0xf bank_mask:0xf
	v_fmac_f32_dpp v118, -v134, v32 quad_perm:[3,3,3,3] row_mask:0xf bank_mask:0xf
	v_fmac_f32_dpp v119, -v135, v33 quad_perm:[3,3,3,3] row_mask:0xf bank_mask:0xf
	v_add_f32_e32 v121, v117, v116
	v_add_f32_e32 v122, v118, v119
	v_add_f32_e32 v34, v122, v121
	s_waitcnt lgkmcnt(15)
; __device__ __forceinline__ float bf2f(bf16 v) { return __uint_as_float(((unsigned)v) << 16); }
; #define GDN_LOADROW(buf, rr_, i_) do { _Pragma("unroll") for (int j4 = 0; j4 < ((i_) + 3) / 4; ++j4) buf[j4] = *(const f32x4*)(Lm + (i_) * GP_LSTR + 4 * j4); rr_ = bf2f(*(const bf16*)(xsrc + (i_) * GP_STR * 2)) * scl[i_]; } while (0)
; template <int STRIP> __device__ __forceinline__ void ph_gdn_prep_fast(const bf16* __restrict__ proj, const float* __restrict__ small, const float* __restrict__ conv_w, const float* __restrict__ a_log, const float* __restrict__ dt_bias, ...
;     ...
;             float U[64];
;             const float* scl = isw ? (sgc + 256) : sbeta;
;             f32x4 bA[16], bB[16]; float rA, rB = 0.f;
;             rA = bf2f(*(const bf16*)xsrc) * scl[0];
;     ...
; #pragma unroll
;             for (int i = 0; i < 64; i += 2) {
;                 GDN_LOADROW(bB, rB, i + 1);
;                 GDN_ROW(bA, rA, i);
;                 if (i + 2 < 64) GDN_LOADROW(bA, rA, i + 2);
;                 GDN_ROW(bB, rB, i + 1);
;             }
	v_mul_f32_dpp v120, v136, v4 quad_perm:[0,0,0,0] row_mask:0xf bank_mask:0xf
	v_fma_f32 v116, v215, v245, -v120
	v_mul_f32_dpp v117, -v137, v5 quad_perm:[0,0,0,0] row_mask:0xf bank_mask:0xf
	v_mul_f32_dpp v118, -v136, v6 quad_perm:[1,1,1,1] row_mask:0xf bank_mask:0xf
	v_mul_f32_dpp v119, -v137, v12 quad_perm:[1,1,1,1] row_mask:0xf bank_mask:0xf
	ds_read_b64 v[190:191], v125 offset:7888
	v_fmac_f32_dpp v116, -v136, v7 quad_perm:[2,2,2,2] row_mask:0xf bank_mask:0xf
	v_fmac_f32_dpp v117, -v137, v13 quad_perm:[2,2,2,2] row_mask:0xf bank_mask:0xf
	v_fmac_f32_dpp v118, -v136, v14 quad_perm:[3,3,3,3] row_mask:0xf bank_mask:0xf
	ds_read_b64 v[192:193], v125 offset:7920
	v_fmac_f32_dpp v119, -v137, v15 quad_perm:[3,3,3,3] row_mask:0xf bank_mask:0xf
	v_fmac_f32_dpp v116, -v138, v16 quad_perm:[0,0,0,0] row_mask:0xf bank_mask:0xf
	v_fmac_f32_dpp v117, -v139, v17 quad_perm:[0,0,0,0] row_mask:0xf bank_mask:0xf
	ds_read_b64 v[194:195], v125 offset:7952
	v_fmac_f32_dpp v118, -v138, v19 quad_perm:[1,1,1,1] row_mask:0xf bank_mask:0xf
	v_fmac_f32_dpp v119, -v139, v20 quad_perm:[1,1,1,1] row_mask:0xf bank_mask:0xf
	v_fmac_f32_dpp v116, -v138, v21 quad_perm:[2,2,2,2] row_mask:0xf bank_mask:0xf
	ds_read_b64 v[196:197], v125 offset:7984
	v_fmac_f32_dpp v117, -v139, v22 quad_perm:[2,2,2,2] row_mask:0xf bank_mask:0xf
	v_fmac_f32_dpp v118, -v138, v23 quad_perm:[3,3,3,3] row_mask:0xf bank_mask:0xf
	v_fmac_f32_dpp v119, -v139, v24 quad_perm:[3,3,3,3] row_mask:0xf bank_mask:0xf
	ds_read_b32 v219, v124 offset:116
	v_fmac_f32_dpp v116, -v140, v25 quad_perm:[0,0,0,0] row_mask:0xf bank_mask:0xf
	v_fmac_f32_dpp v117, -v141, v27 quad_perm:[0,0,0,0] row_mask:0xf bank_mask:0xf
	v_fmac_f32_dpp v118, -v140, v28 quad_perm:[1,1,1,1] row_mask:0xf bank_mask:0xf
	ds_read_u16_d16_hi v249, v123 offset:7888
	v_fmac_f32_dpp v119, -v141, v29 quad_perm:[1,1,1,1] row_mask:0xf bank_mask:0xf
	v_fmac_f32_dpp v116, -v140, v30 quad_perm:[2,2,2,2] row_mask:0xf bank_mask:0xf
	v_fmac_f32_dpp v117, -v141, v31 quad_perm:[2,2,2,2] row_mask:0xf bank_mask:0xf
	v_fmac_f32_dpp v118, -v140, v32 quad_perm:[3,3,3,3] row_mask:0xf bank_mask:0xf
	v_fmac_f32_dpp v119, -v141, v33 quad_perm:[3,3,3,3] row_mask:0xf bank_mask:0xf
	v_fmac_f32_dpp v116, -v142, v34 quad_perm:[0,0,0,0] row_mask:0xf bank_mask:0xf
	v_add_f32_e32 v121, v117, v116
	v_add_f32_e32 v122, v118, v119
	v_add_f32_e32 v35, v122, v121
	s_waitcnt lgkmcnt(15)
	v_mul_f32_dpp v120, v144, v4 quad_perm:[0,0,0,0] row_mask:0xf bank_mask:0xf
	v_fma_f32 v116, v216, v246, -v120
	v_mul_f32_dpp v117, -v145, v5 quad_perm:[0,0,0,0] row_mask:0xf bank_mask:0xf
	v_mul_f32_dpp v118, -v144, v6 quad_perm:[1,1,1,1] row_mask:0xf bank_mask:0xf
	v_mul_f32_dpp v119, -v145, v12 quad_perm:[1,1,1,1] row_mask:0xf bank_mask:0xf
	ds_read_b64 v[198:199], v125 offset:8160
	v_fmac_f32_dpp v116, -v144, v7 quad_perm:[2,2,2,2] row_mask:0xf bank_mask:0xf
	v_fmac_f32_dpp v117, -v145, v13 quad_perm:[2,2,2,2] row_mask:0xf bank_mask:0xf
	v_fmac_f32_dpp v118, -v144, v14 quad_perm:[3,3,3,3] row_mask:0xf bank_mask:0xf
	ds_read_b64 v[200:201], v125 offset:8192
	v_fmac_f32_dpp v119, -v145, v15 quad_perm:[3,3,3,3] row_mask:0xf bank_mask:0xf
	v_fmac_f32_dpp v116, -v146, v16 quad_perm:[0,0,0,0] row_mask:0xf bank_mask:0xf
	v_fmac_f32_dpp v117, -v147, v17 quad_perm:[0,0,0,0] row_mask:0xf bank_mask:0xf
	ds_read_b64 v[202:203], v125 offset:8224
	v_fmac_f32_dpp v118, -v146, v19 quad_perm:[1,1,1,1] row_mask:0xf bank_mask:0xf
	v_fmac_f32_dpp v119, -v147, v20 quad_perm:[1,1,1,1] row_mask:0xf bank_mask:0xf
	v_fmac_f32_dpp v116, -v146, v21 quad_perm:[2,2,2,2] row_mask:0xf bank_mask:0xf
	ds_read_b64 v[204:205], v125 offset:8256
	v_fmac_f32_dpp v117, -v147, v22 quad_perm:[2,2,2,2] row_mask:0xf bank_mask:0xf
	v_fmac_f32_dpp v118, -v146, v23 quad_perm:[3,3,3,3] row_mask:0xf bank_mask:0xf
	v_fmac_f32_dpp v119, -v147, v24 quad_perm:[3,3,3,3] row_mask:0xf bank_mask:0xf
	ds_read_b32 v220, v124 offset:120
	v_fmac_f32_dpp v116, -v148, v25 quad_perm:[0,0,0,0] row_mask:0xf bank_mask:0xf
	v_fmac_f32_dpp v117, -v149, v27 quad_perm:[0,0,0,0] row_mask:0xf bank_mask:0xf
	v_fmac_f32_dpp v118, -v148, v28 quad_perm:[1,1,1,1] row_mask:0xf bank_mask:0xf
	ds_read_u16_d16_hi v250, v123 offset:8160
	v_fmac_f32_dpp v119, -v149, v29 quad_perm:[1,1,1,1] row_mask:0xf bank_mask:0xf
	v_fmac_f32_dpp v116, -v148, v30 quad_perm:[2,2,2,2] row_mask:0xf bank_mask:0xf
	v_fmac_f32_dpp v117, -v149, v31 quad_perm:[2,2,2,2] row_mask:0xf bank_mask:0xf
	v_fmac_f32_dpp v118, -v148, v32 quad_perm:[3,3,3,3] row_mask:0xf bank_mask:0xf
	v_fmac_f32_dpp v119, -v149, v33 quad_perm:[3,3,3,3] row_mask:0xf bank_mask:0xf
	v_fmac_f32_dpp v116, -v150, v34 quad_perm:[0,0,0,0] row_mask:0xf bank_mask:0xf
	v_fmac_f32_dpp v117, -v151, v35 quad_perm:[0,0,0,0] row_mask:0xf bank_mask:0xf
	v_add_f32_e32 v121, v117, v116
	v_add_f32_e32 v122, v118, v119
	v_add_f32_e32 v36, v122, v121
	s_waitcnt lgkmcnt(15)
; __device__ __forceinline__ float bf2f(bf16 v) { return __uint_as_float(((unsigned)v) << 16); }
; #define GDN_LOADROW(buf, rr_, i_) do { _Pragma("unroll") for (int j4 = 0; j4 < ((i_) + 3) / 4; ++j4) buf[j4] = *(const f32x4*)(Lm + (i_) * GP_LSTR + 4 * j4); rr_ = bf2f(*(const bf16*)(xsrc + (i_) * GP_STR * 2)) * scl[i_]; } while (0)
; template <int STRIP> __device__ __forceinline__ void ph_gdn_prep_fast(const bf16* __restrict__ proj, const float* __restrict__ small, const float* __restrict__ conv_w, const float* __restrict__ a_log, const float* __restrict__ dt_bias, ...
;     ...
;             float U[64];
;             const float* scl = isw ? (sgc + 256) : sbeta;
;             f32x4 bA[16], bB[16]; float rA, rB = 0.f;
;             rA = bf2f(*(const bf16*)xsrc) * scl[0];
;     ...
; #pragma unroll
;             for (int i = 0; i < 64; i += 2) {
;                 GDN_LOADROW(bB, rB, i + 1);
;                 GDN_ROW(bA, rA, i);
;                 if (i + 2 < 64) GDN_LOADROW(bA, rA, i + 2);
;                 GDN_ROW(bB, rB, i + 1);
;             }
	v_mul_f32_dpp v120, v152, v4 quad_perm:[0,0,0,0] row_mask:0xf bank_mask:0xf
	v_fma_f32 v116, v217, v247, -v120
	v_mul_f32_dpp v117, -v153, v5 quad_perm:[0,0,0,0] row_mask:0xf bank_mask:0xf
	v_mul_f32_dpp v118, -v152, v6 quad_perm:[1,1,1,1] row_mask:0xf bank_mask:0xf
	ds_read_b64 v[206:207], v125 offset:8432
	v_mul_f32_dpp v119, -v153, v12 quad_perm:[1,1,1,1] row_mask:0xf bank_mask:0xf
	v_fmac_f32_dpp v116, -v152, v7 quad_perm:[2,2,2,2] row_mask:0xf bank_mask:0xf
	v_fmac_f32_dpp v117, -v153, v13 quad_perm:[2,2,2,2] row_mask:0xf bank_mask:0xf
	ds_read_b64 v[164:165], v125 offset:8464
	v_fmac_f32_dpp v118, -v152, v14 quad_perm:[3,3,3,3] row_mask:0xf bank_mask:0xf
	v_fmac_f32_dpp v119, -v153, v15 quad_perm:[3,3,3,3] row_mask:0xf bank_mask:0xf
	v_fmac_f32_dpp v116, -v154, v16 quad_perm:[0,0,0,0] row_mask:0xf bank_mask:0xf
	ds_read_b64 v[166:167], v125 offset:8496
	v_fmac_f32_dpp v117, -v155, v17 quad_perm:[0,0,0,0] row_mask:0xf bank_mask:0xf
	v_fmac_f32_dpp v118, -v154, v19 quad_perm:[1,1,1,1] row_mask:0xf bank_mask:0xf
	v_fmac_f32_dpp v119, -v155, v20 quad_perm:[1,1,1,1] row_mask:0xf bank_mask:0xf
	ds_read_b64 v[168:169], v125 offset:8528
	v_fmac_f32_dpp v116, -v154, v21 quad_perm:[2,2,2,2] row_mask:0xf bank_mask:0xf
	v_fmac_f32_dpp v117, -v155, v22 quad_perm:[2,2,2,2] row_mask:0xf bank_mask:0xf
	v_fmac_f32_dpp v118, -v154, v23 quad_perm:[3,3,3,3] row_mask:0xf bank_mask:0xf
	ds_read_b32 v221, v124 offset:124
	v_fmac_f32_dpp v119, -v155, v24 quad_perm:[3,3,3,3] row_mask:0xf bank_mask:0xf
	v_fmac_f32_dpp v116, -v156, v25 quad_perm:[0,0,0,0] row_mask:0xf bank_mask:0xf
	v_fmac_f32_dpp v117, -v157, v27 quad_perm:[0,0,0,0] row_mask:0xf bank_mask:0xf
	ds_read_u16_d16_hi v251, v123 offset:8432
	v_fmac_f32_dpp v118, -v156, v28 quad_perm:[1,1,1,1] row_mask:0xf bank_mask:0xf
	v_fmac_f32_dpp v119, -v157, v29 quad_perm:[1,1,1,1] row_mask:0xf bank_mask:0xf
	v_fmac_f32_dpp v116, -v156, v30 quad_perm:[2,2,2,2] row_mask:0xf bank_mask:0xf
	v_fmac_f32_dpp v117, -v157, v31 quad_perm:[2,2,2,2] row_mask:0xf bank_mask:0xf
	v_fmac_f32_dpp v118, -v156, v32 quad_perm:[3,3,3,3] row_mask:0xf bank_mask:0xf
	v_fmac_f32_dpp v119, -v157, v33 quad_perm:[3,3,3,3] row_mask:0xf bank_mask:0xf
	v_fmac_f32_dpp v116, -v158, v34 quad_perm:[0,0,0,0] row_mask:0xf bank_mask:0xf
	v_fmac_f32_dpp v117, -v159, v35 quad_perm:[0,0,0,0] row_mask:0xf bank_mask:0xf
	v_fmac_f32_dpp v118, -v158, v36 quad_perm:[1,1,1,1] row_mask:0xf bank_mask:0xf
	v_add_f32_e32 v121, v117, v116
	v_add_f32_e32 v122, v118, v119
	v_add_f32_e32 v37, v122, v121
	s_waitcnt lgkmcnt(15)
	v_mul_f32_dpp v120, v160, v4 quad_perm:[0,0,0,0] row_mask:0xf bank_mask:0xf
	v_fma_f32 v116, v218, v248, -v120
	v_mul_f32_dpp v117, -v161, v5 quad_perm:[0,0,0,0] row_mask:0xf bank_mask:0xf
	v_mul_f32_dpp v118, -v160, v6 quad_perm:[1,1,1,1] row_mask:0xf bank_mask:0xf
	v_mul_f32_dpp v119, -v161, v12 quad_perm:[1,1,1,1] row_mask:0xf bank_mask:0xf
	v_fmac_f32_dpp v116, -v160, v7 quad_perm:[2,2,2,2] row_mask:0xf bank_mask:0xf
	v_fmac_f32_dpp v117, -v161, v13 quad_perm:[2,2,2,2] row_mask:0xf bank_mask:0xf
	v_fmac_f32_dpp v118, -v160, v14 quad_perm:[3,3,3,3] row_mask:0xf bank_mask:0xf
	v_fmac_f32_dpp v119, -v161, v15 quad_perm:[3,3,3,3] row_mask:0xf bank_mask:0xf
	v_fmac_f32_dpp v116, -v162, v16 quad_perm:[0,0,0,0] row_mask:0xf bank_mask:0xf
	v_fmac_f32_dpp v117, -v163, v17 quad_perm:[0,0,0,0] row_mask:0xf bank_mask:0xf
	v_fmac_f32_dpp v118, -v162, v19 quad_perm:[1,1,1,1] row_mask:0xf bank_mask:0xf
	v_fmac_f32_dpp v119, -v163, v20 quad_perm:[1,1,1,1] row_mask:0xf bank_mask:0xf
	v_fmac_f32_dpp v116, -v162, v21 quad_perm:[2,2,2,2] row_mask:0xf bank_mask:0xf
	v_fmac_f32_dpp v117, -v163, v22 quad_perm:[2,2,2,2] row_mask:0xf bank_mask:0xf
	v_fmac_f32_dpp v118, -v162, v23 quad_perm:[3,3,3,3] row_mask:0xf bank_mask:0xf
	v_fmac_f32_dpp v119, -v163, v24 quad_perm:[3,3,3,3] row_mask:0xf bank_mask:0xf
	v_fmac_f32_dpp v116, -v186, v25 quad_perm:[0,0,0,0] row_mask:0xf bank_mask:0xf
	v_fmac_f32_dpp v117, -v187, v27 quad_perm:[0,0,0,0] row_mask:0xf bank_mask:0xf
	v_fmac_f32_dpp v118, -v186, v28 quad_perm:[1,1,1,1] row_mask:0xf bank_mask:0xf
	v_fmac_f32_dpp v119, -v187, v29 quad_perm:[1,1,1,1] row_mask:0xf bank_mask:0xf
	v_fmac_f32_dpp v116, -v186, v30 quad_perm:[2,2,2,2] row_mask:0xf bank_mask:0xf
	v_fmac_f32_dpp v117, -v187, v31 quad_perm:[2,2,2,2] row_mask:0xf bank_mask:0xf
	v_fmac_f32_dpp v118, -v186, v32 quad_perm:[3,3,3,3] row_mask:0xf bank_mask:0xf
	v_fmac_f32_dpp v119, -v187, v33 quad_perm:[3,3,3,3] row_mask:0xf bank_mask:0xf
	v_fmac_f32_dpp v116, -v188, v34 quad_perm:[0,0,0,0] row_mask:0xf bank_mask:0xf
	v_fmac_f32_dpp v117, -v189, v35 quad_perm:[0,0,0,0] row_mask:0xf bank_mask:0xf
	v_fmac_f32_dpp v118, -v188, v36 quad_perm:[1,1,1,1] row_mask:0xf bank_mask:0xf
	v_fmac_f32_dpp v119, -v189, v37 quad_perm:[1,1,1,1] row_mask:0xf bank_mask:0xf
	v_add_f32_e32 v121, v117, v116
	v_add_f32_e32 v122, v118, v119
	v_add_f32_e32 v38, v122, v121
	s_waitcnt lgkmcnt(12)
; __device__ __forceinline__ float bf2f(bf16 v) { return __uint_as_float(((unsigned)v) << 16); }
; #define GDN_LOADROW(buf, rr_, i_) do { _Pragma("unroll") for (int j4 = 0; j4 < ((i_) + 3) / 4; ++j4) buf[j4] = *(const f32x4*)(Lm + (i_) * GP_LSTR + 4 * j4); rr_ = bf2f(*(const bf16*)(xsrc + (i_) * GP_STR * 2)) * scl[i_]; } while (0)
; template <int STRIP> __device__ __forceinline__ void ph_gdn_prep_fast(const bf16* __restrict__ proj, const float* __restrict__ small, const float* __restrict__ conv_w, const float* __restrict__ a_log, const float* __restrict__ dt_bias, ...
;     ...
;             float U[64];
;             const float* scl = isw ? (sgc + 256) : sbeta;
;             f32x4 bA[16], bB[16]; float rA, rB = 0.f;
;             rA = bf2f(*(const bf16*)xsrc) * scl[0];
;     ...
; #pragma unroll
;             for (int i = 0; i < 64; i += 2) {
;                 GDN_LOADROW(bB, rB, i + 1);
;                 GDN_ROW(bA, rA, i);
;                 if (i + 2 < 64) GDN_LOADROW(bA, rA, i + 2);
;                 GDN_ROW(bB, rB, i + 1);
;             }
	v_mul_f32_dpp v120, v190, v4 quad_perm:[0,0,0,0] row_mask:0xf bank_mask:0xf
	v_fma_f32 v116, v219, v249, -v120
	v_mul_f32_dpp v117, -v191, v5 quad_perm:[0,0,0,0] row_mask:0xf bank_mask:0xf
	v_mul_f32_dpp v118, -v190, v6 quad_perm:[1,1,1,1] row_mask:0xf bank_mask:0xf
	v_mul_f32_dpp v119, -v191, v12 quad_perm:[1,1,1,1] row_mask:0xf bank_mask:0xf
	v_fmac_f32_dpp v116, -v190, v7 quad_perm:[2,2,2,2] row_mask:0xf bank_mask:0xf
	v_fmac_f32_dpp v117, -v191, v13 quad_perm:[2,2,2,2] row_mask:0xf bank_mask:0xf
	v_fmac_f32_dpp v118, -v190, v14 quad_perm:[3,3,3,3] row_mask:0xf bank_mask:0xf
	v_fmac_f32_dpp v119, -v191, v15 quad_perm:[3,3,3,3] row_mask:0xf bank_mask:0xf
	v_fmac_f32_dpp v116, -v192, v16 quad_perm:[0,0,0,0] row_mask:0xf bank_mask:0xf
	v_fmac_f32_dpp v117, -v193, v17 quad_perm:[0,0,0,0] row_mask:0xf bank_mask:0xf
	v_fmac_f32_dpp v118, -v192, v19 quad_perm:[1,1,1,1] row_mask:0xf bank_mask:0xf
	v_fmac_f32_dpp v119, -v193, v20 quad_perm:[1,1,1,1] row_mask:0xf bank_mask:0xf
	v_fmac_f32_dpp v116, -v192, v21 quad_perm:[2,2,2,2] row_mask:0xf bank_mask:0xf
	v_fmac_f32_dpp v117, -v193, v22 quad_perm:[2,2,2,2] row_mask:0xf bank_mask:0xf
	v_fmac_f32_dpp v118, -v192, v23 quad_perm:[3,3,3,3] row_mask:0xf bank_mask:0xf
	v_fmac_f32_dpp v119, -v193, v24 quad_perm:[3,3,3,3] row_mask:0xf bank_mask:0xf
	v_fmac_f32_dpp v116, -v194, v25 quad_perm:[0,0,0,0] row_mask:0xf bank_mask:0xf
	v_fmac_f32_dpp v117, -v195, v27 quad_perm:[0,0,0,0] row_mask:0xf bank_mask:0xf
	v_fmac_f32_dpp v118, -v194, v28 quad_perm:[1,1,1,1] row_mask:0xf bank_mask:0xf
	v_fmac_f32_dpp v119, -v195, v29 quad_perm:[1,1,1,1] row_mask:0xf bank_mask:0xf
	v_fmac_f32_dpp v116, -v194, v30 quad_perm:[2,2,2,2] row_mask:0xf bank_mask:0xf
	v_fmac_f32_dpp v117, -v195, v31 quad_perm:[2,2,2,2] row_mask:0xf bank_mask:0xf
	v_fmac_f32_dpp v118, -v194, v32 quad_perm:[3,3,3,3] row_mask:0xf bank_mask:0xf
	v_fmac_f32_dpp v119, -v195, v33 quad_perm:[3,3,3,3] row_mask:0xf bank_mask:0xf
	v_fmac_f32_dpp v116, -v196, v34 quad_perm:[0,0,0,0] row_mask:0xf bank_mask:0xf
	v_fmac_f32_dpp v117, -v197, v35 quad_perm:[0,0,0,0] row_mask:0xf bank_mask:0xf
	v_fmac_f32_dpp v118, -v196, v36 quad_perm:[1,1,1,1] row_mask:0xf bank_mask:0xf
	v_fmac_f32_dpp v119, -v197, v37 quad_perm:[1,1,1,1] row_mask:0xf bank_mask:0xf
	v_fmac_f32_dpp v116, -v196, v38 quad_perm:[2,2,2,2] row_mask:0xf bank_mask:0xf
	v_add_f32_e32 v121, v117, v116
	v_add_f32_e32 v122, v118, v119
	v_add_f32_e32 v39, v122, v121
	s_waitcnt lgkmcnt(6)
	v_mul_f32_dpp v120, v198, v4 quad_perm:[0,0,0,0] row_mask:0xf bank_mask:0xf
	v_fma_f32 v116, v220, v250, -v120
	v_mul_f32_dpp v117, -v199, v5 quad_perm:[0,0,0,0] row_mask:0xf bank_mask:0xf
	v_mul_f32_dpp v118, -v198, v6 quad_perm:[1,1,1,1] row_mask:0xf bank_mask:0xf
	v_mul_f32_dpp v119, -v199, v12 quad_perm:[1,1,1,1] row_mask:0xf bank_mask:0xf
	v_fmac_f32_dpp v116, -v198, v7 quad_perm:[2,2,2,2] row_mask:0xf bank_mask:0xf
	v_fmac_f32_dpp v117, -v199, v13 quad_perm:[2,2,2,2] row_mask:0xf bank_mask:0xf
	v_fmac_f32_dpp v118, -v198, v14 quad_perm:[3,3,3,3] row_mask:0xf bank_mask:0xf
	v_fmac_f32_dpp v119, -v199, v15 quad_perm:[3,3,3,3] row_mask:0xf bank_mask:0xf
	v_fmac_f32_dpp v116, -v200, v16 quad_perm:[0,0,0,0] row_mask:0xf bank_mask:0xf
	v_fmac_f32_dpp v117, -v201, v17 quad_perm:[0,0,0,0] row_mask:0xf bank_mask:0xf
	v_fmac_f32_dpp v118, -v200, v19 quad_perm:[1,1,1,1] row_mask:0xf bank_mask:0xf
	v_fmac_f32_dpp v119, -v201, v20 quad_perm:[1,1,1,1] row_mask:0xf bank_mask:0xf
	v_fmac_f32_dpp v116, -v200, v21 quad_perm:[2,2,2,2] row_mask:0xf bank_mask:0xf
	v_fmac_f32_dpp v117, -v201, v22 quad_perm:[2,2,2,2] row_mask:0xf bank_mask:0xf
	v_fmac_f32_dpp v118, -v200, v23 quad_perm:[3,3,3,3] row_mask:0xf bank_mask:0xf
	v_fmac_f32_dpp v119, -v201, v24 quad_perm:[3,3,3,3] row_mask:0xf bank_mask:0xf
	v_fmac_f32_dpp v116, -v202, v25 quad_perm:[0,0,0,0] row_mask:0xf bank_mask:0xf
	v_fmac_f32_dpp v117, -v203, v27 quad_perm:[0,0,0,0] row_mask:0xf bank_mask:0xf
	v_fmac_f32_dpp v118, -v202, v28 quad_perm:[1,1,1,1] row_mask:0xf bank_mask:0xf
	v_fmac_f32_dpp v119, -v203, v29 quad_perm:[1,1,1,1] row_mask:0xf bank_mask:0xf
	v_fmac_f32_dpp v116, -v202, v30 quad_perm:[2,2,2,2] row_mask:0xf bank_mask:0xf
	v_fmac_f32_dpp v117, -v203, v31 quad_perm:[2,2,2,2] row_mask:0xf bank_mask:0xf
	v_fmac_f32_dpp v118, -v202, v32 quad_perm:[3,3,3,3] row_mask:0xf bank_mask:0xf
	v_fmac_f32_dpp v119, -v203, v33 quad_perm:[3,3,3,3] row_mask:0xf bank_mask:0xf
	v_fmac_f32_dpp v116, -v204, v34 quad_perm:[0,0,0,0] row_mask:0xf bank_mask:0xf
	v_fmac_f32_dpp v117, -v205, v35 quad_perm:[0,0,0,0] row_mask:0xf bank_mask:0xf
	v_fmac_f32_dpp v118, -v204, v36 quad_perm:[1,1,1,1] row_mask:0xf bank_mask:0xf
	v_fmac_f32_dpp v119, -v205, v37 quad_perm:[1,1,1,1] row_mask:0xf bank_mask:0xf
	v_fmac_f32_dpp v116, -v204, v38 quad_perm:[2,2,2,2] row_mask:0xf bank_mask:0xf
	v_fmac_f32_dpp v117, -v205, v39 quad_perm:[2,2,2,2] row_mask:0xf bank_mask:0xf
	v_add_f32_e32 v121, v117, v116
	v_add_f32_e32 v122, v118, v119
	v_add_f32_e32 v40, v122, v121
	s_waitcnt lgkmcnt(0)
; __device__ __forceinline__ float bf2f(bf16 v) { return __uint_as_float(((unsigned)v) << 16); }
; #define GDN_LOADROW(buf, rr_, i_) do { _Pragma("unroll") for (int j4 = 0; j4 < ((i_) + 3) / 4; ++j4) buf[j4] = *(const f32x4*)(Lm + (i_) * GP_LSTR + 4 * j4); rr_ = bf2f(*(const bf16*)(xsrc + (i_) * GP_STR * 2)) * scl[i_]; } while (0)
; template <int STRIP> __device__ __forceinline__ void ph_gdn_prep_fast(const bf16* __restrict__ proj, const float* __restrict__ small, const float* __restrict__ conv_w, const float* __restrict__ a_log, const float* __restrict__ dt_bias, ...
;     ...
;             float U[64];
;             const float* scl = isw ? (sgc + 256) : sbeta;
;             f32x4 bA[16], bB[16]; float rA, rB = 0.f;
;             rA = bf2f(*(const bf16*)xsrc) * scl[0];
;     ...
; #pragma unroll
;             for (int i = 0; i < 64; i += 2) {
;                 GDN_LOADROW(bB, rB, i + 1);
;                 GDN_ROW(bA, rA, i);
;                 if (i + 2 < 64) GDN_LOADROW(bA, rA, i + 2);
;                 GDN_ROW(bB, rB, i + 1);
;             }
	v_mul_f32_dpp v120, v206, v4 quad_perm:[0,0,0,0] row_mask:0xf bank_mask:0xf
	v_fma_f32 v116, v221, v251, -v120
	v_mul_f32_dpp v117, -v207, v5 quad_perm:[0,0,0,0] row_mask:0xf bank_mask:0xf
	v_mul_f32_dpp v118, -v206, v6 quad_perm:[1,1,1,1] row_mask:0xf bank_mask:0xf
	v_mul_f32_dpp v119, -v207, v12 quad_perm:[1,1,1,1] row_mask:0xf bank_mask:0xf
	v_fmac_f32_dpp v116, -v206, v7 quad_perm:[2,2,2,2] row_mask:0xf bank_mask:0xf
	v_fmac_f32_dpp v117, -v207, v13 quad_perm:[2,2,2,2] row_mask:0xf bank_mask:0xf
	v_fmac_f32_dpp v118, -v206, v14 quad_perm:[3,3,3,3] row_mask:0xf bank_mask:0xf
	v_fmac_f32_dpp v119, -v207, v15 quad_perm:[3,3,3,3] row_mask:0xf bank_mask:0xf
	v_fmac_f32_dpp v116, -v164, v16 quad_perm:[0,0,0,0] row_mask:0xf bank_mask:0xf
	v_fmac_f32_dpp v117, -v165, v17 quad_perm:[0,0,0,0] row_mask:0xf bank_mask:0xf
	v_fmac_f32_dpp v118, -v164, v19 quad_perm:[1,1,1,1] row_mask:0xf bank_mask:0xf
	v_fmac_f32_dpp v119, -v165, v20 quad_perm:[1,1,1,1] row_mask:0xf bank_mask:0xf
	v_fmac_f32_dpp v116, -v164, v21 quad_perm:[2,2,2,2] row_mask:0xf bank_mask:0xf
	v_fmac_f32_dpp v117, -v165, v22 quad_perm:[2,2,2,2] row_mask:0xf bank_mask:0xf
	v_fmac_f32_dpp v118, -v164, v23 quad_perm:[3,3,3,3] row_mask:0xf bank_mask:0xf
	v_fmac_f32_dpp v119, -v165, v24 quad_perm:[3,3,3,3] row_mask:0xf bank_mask:0xf
	v_fmac_f32_dpp v116, -v166, v25 quad_perm:[0,0,0,0] row_mask:0xf bank_mask:0xf
	v_fmac_f32_dpp v117, -v167, v27 quad_perm:[0,0,0,0] row_mask:0xf bank_mask:0xf
	v_fmac_f32_dpp v118, -v166, v28 quad_perm:[1,1,1,1] row_mask:0xf bank_mask:0xf
	v_fmac_f32_dpp v119, -v167, v29 quad_perm:[1,1,1,1] row_mask:0xf bank_mask:0xf
	v_fmac_f32_dpp v116, -v166, v30 quad_perm:[2,2,2,2] row_mask:0xf bank_mask:0xf
	v_fmac_f32_dpp v117, -v167, v31 quad_perm:[2,2,2,2] row_mask:0xf bank_mask:0xf
	v_fmac_f32_dpp v118, -v166, v32 quad_perm:[3,3,3,3] row_mask:0xf bank_mask:0xf
	v_fmac_f32_dpp v119, -v167, v33 quad_perm:[3,3,3,3] row_mask:0xf bank_mask:0xf
	v_fmac_f32_dpp v116, -v168, v34 quad_perm:[0,0,0,0] row_mask:0xf bank_mask:0xf
	v_fmac_f32_dpp v117, -v169, v35 quad_perm:[0,0,0,0] row_mask:0xf bank_mask:0xf
	v_fmac_f32_dpp v118, -v168, v36 quad_perm:[1,1,1,1] row_mask:0xf bank_mask:0xf
	v_fmac_f32_dpp v119, -v169, v37 quad_perm:[1,1,1,1] row_mask:0xf bank_mask:0xf
	v_fmac_f32_dpp v116, -v168, v38 quad_perm:[2,2,2,2] row_mask:0xf bank_mask:0xf
	v_fmac_f32_dpp v117, -v169, v39 quad_perm:[2,2,2,2] row_mask:0xf bank_mask:0xf
	v_fmac_f32_dpp v118, -v168, v40 quad_perm:[3,3,3,3] row_mask:0xf bank_mask:0xf
	v_add_f32_e32 v121, v117, v116
	v_add_f32_e32 v122, v118, v119
	v_add_f32_e32 v41, v122, v121
	v_permlane32_swap_b32_e32 v4, v5
	v_permlane32_swap_b32_e32 v6, v12
	v_permlane32_swap_b32_e32 v7, v13
	v_permlane32_swap_b32_e32 v14, v15
	v_permlane32_swap_b32_e32 v16, v17
	v_permlane32_swap_b32_e32 v19, v20
	v_permlane32_swap_b32_e32 v21, v22
	v_permlane32_swap_b32_e32 v23, v24
	v_permlane32_swap_b32_e32 v25, v27
	v_permlane32_swap_b32_e32 v28, v29
	v_permlane32_swap_b32_e32 v30, v31
	v_permlane32_swap_b32_e32 v32, v33
	v_permlane32_swap_b32_e32 v34, v35
	v_permlane32_swap_b32_e32 v36, v37
	v_permlane32_swap_b32_e32 v38, v39
	v_permlane32_swap_b32_e32 v40, v41
	v_mfma_f32_32x32x2_f32 v[132:147], v172, v4, 0
	ds_read_b32 v181, v124 offset:128
	v_mfma_f32_32x32x2_f32 v[148:163], v172, v5, 0
	ds_read_u16_d16_hi v252, v123 offset:8704
	v_mfma_f32_32x32x2_f32 v[132:147], v173, v6, v[132:147]
	ds_read_b64 v[170:171], v125 offset:9104
	v_mfma_f32_32x32x2_f32 v[148:163], v173, v12, v[148:163]
	ds_read_b32 v182, v124 offset:132
	v_permlane32_swap_b32_e32 v4, v5
	v_mfma_f32_32x32x2_f32 v[132:147], v174, v7, v[132:147]
	ds_read_u16_d16_hi v253, v123 offset:8976
	v_mfma_f32_32x32x2_f32 v[148:163], v174, v13, v[148:163]
	ds_read_b64 v[186:187], v125 offset:9376
	v_permlane32_swap_b32_e32 v6, v12
	v_mfma_f32_32x32x2_f32 v[132:147], v175, v14, v[132:147]
	ds_read_b32 v183, v124 offset:136
	v_mfma_f32_32x32x2_f32 v[148:163], v175, v15, v[148:163]
	ds_read_u16_d16_hi v126, v123 offset:9248
	v_permlane32_swap_b32_e32 v7, v13
	v_mfma_f32_32x32x2_f32 v[132:147], v176, v16, v[132:147]
	ds_read_b64 v[188:189], v125 offset:9648
	v_mfma_f32_32x32x2_f32 v[148:163], v176, v17, v[148:163]
	ds_read_b32 v185, v124 offset:140
	v_permlane32_swap_b32_e32 v14, v15
	v_mfma_f32_32x32x2_f32 v[132:147], v177, v19, v[132:147]
	ds_read_u16_d16_hi v127, v123 offset:9520
	v_mfma_f32_32x32x2_f32 v[148:163], v177, v20, v[148:163]
	ds_read_b64 v[190:191], v125 offset:9920
	v_permlane32_swap_b32_e32 v16, v17
	v_mfma_f32_32x32x2_f32 v[132:147], v178, v21, v[132:147]
	ds_read_b32 v208, v124 offset:144
	v_mfma_f32_32x32x2_f32 v[148:163], v178, v22, v[148:163]
	ds_read_u16_d16_hi v244, v123 offset:9792
	v_permlane32_swap_b32_e32 v19, v20
	v_mfma_f32_32x32x2_f32 v[132:147], v179, v23, v[132:147]
	ds_read_b64 v[192:193], v125 offset:10192
	v_mfma_f32_32x32x2_f32 v[148:163], v179, v24, v[148:163]
	ds_read_b32 v209, v124 offset:148
	v_permlane32_swap_b32_e32 v21, v22
	v_mfma_f32_32x32x2_f32 v[132:147], v222, v25, v[132:147]
	ds_read_u16_d16_hi v245, v123 offset:10064
	v_mfma_f32_32x32x2_f32 v[148:163], v222, v27, v[148:163]
	ds_read_b64 v[194:195], v125 offset:10464
	v_permlane32_swap_b32_e32 v23, v24
	v_mfma_f32_32x32x2_f32 v[132:147], v223, v28, v[132:147]
	ds_read_b32 v210, v124 offset:152
	v_mfma_f32_32x32x2_f32 v[148:163], v223, v29, v[148:163]
	ds_read_u16_d16_hi v246, v123 offset:10336
	v_permlane32_swap_b32_e32 v25, v27
	v_mfma_f32_32x32x2_f32 v[132:147], v224, v30, v[132:147]
	ds_read_b64 v[196:197], v125 offset:10736
	v_mfma_f32_32x32x2_f32 v[148:163], v224, v31, v[148:163]
	ds_read_b32 v211, v124 offset:156
; __device__ __forceinline__ float bf2f(bf16 v) { return __uint_as_float(((unsigned)v) << 16); }
; #define GDN_LOADROW(buf, rr_, i_) do { _Pragma("unroll") for (int j4 = 0; j4 < ((i_) + 3) / 4; ++j4) buf[j4] = *(const f32x4*)(Lm + (i_) * GP_LSTR + 4 * j4); rr_ = bf2f(*(const bf16*)(xsrc + (i_) * GP_STR * 2)) * scl[i_]; } while (0)
; template <int STRIP> __device__ __forceinline__ void ph_gdn_prep_fast(const bf16* __restrict__ proj, const float* __restrict__ small, const float* __restrict__ conv_w, const float* __restrict__ a_log, const float* __restrict__ dt_bias, ...
;     ...
;             float U[64];
;             const float* scl = isw ? (sgc + 256) : sbeta;
;             f32x4 bA[16], bB[16]; float rA, rB = 0.f;
;             rA = bf2f(*(const bf16*)xsrc) * scl[0];
;     ...
; #pragma unroll
;             for (int i = 0; i < 64; i += 2) {
;                 GDN_LOADROW(bB, rB, i + 1);
;                 GDN_ROW(bA, rA, i);
;                 if (i + 2 < 64) GDN_LOADROW(bA, rA, i + 2);
;                 GDN_ROW(bB, rB, i + 1);
;             }
	v_permlane32_swap_b32_e32 v28, v29
	v_mfma_f32_32x32x2_f32 v[132:147], v225, v32, v[132:147]
	ds_read_u16_d16_hi v247, v123 offset:10608
	v_mfma_f32_32x32x2_f32 v[148:163], v225, v33, v[148:163]
	ds_read_b64 v[198:199], v125 offset:11008
	v_permlane32_swap_b32_e32 v30, v31
	v_mfma_f32_32x32x2_f32 v[132:147], v226, v34, v[132:147]
	ds_read_b32 v212, v124 offset:160
	v_mfma_f32_32x32x2_f32 v[148:163], v226, v35, v[148:163]
	ds_read_u16_d16_hi v248, v123 offset:10880
	v_permlane32_swap_b32_e32 v32, v33
	v_mfma_f32_32x32x2_f32 v[132:147], v227, v36, v[132:147]
	ds_read_b64 v[200:201], v125 offset:11280
	v_mfma_f32_32x32x2_f32 v[148:163], v227, v37, v[148:163]
	ds_read_b64 v[202:203], v125 offset:11312
	v_permlane32_swap_b32_e32 v34, v35
	v_mfma_f32_32x32x2_f32 v[132:147], v228, v38, v[132:147]
	ds_read_b32 v213, v124 offset:164
	v_mfma_f32_32x32x2_f32 v[148:163], v228, v39, v[148:163]
	ds_read_u16_d16_hi v249, v123 offset:11152
	v_permlane32_swap_b32_e32 v36, v37
	v_mfma_f32_32x32x2_f32 v[132:147], v229, v40, v[132:147]
	ds_read_b64 v[204:205], v125 offset:11552
	v_mfma_f32_32x32x2_f32 v[148:163], v229, v41, v[148:163]
	ds_read_b64 v[206:207], v125 offset:11584
	v_permlane32_swap_b32_e32 v38, v39
	v_permlane32_swap_b32_e32 v40, v41
	s_nop 7
	s_nop 7
	s_nop 3
	v_permlane32_swap_b32_e32 v132, v148
	v_permlane32_swap_b32_e32 v133, v149
	v_permlane32_swap_b32_e32 v134, v150
	v_permlane32_swap_b32_e32 v135, v151
	v_permlane32_swap_b32_e32 v136, v152
	v_permlane32_swap_b32_e32 v137, v153
	v_permlane32_swap_b32_e32 v138, v154
	v_permlane32_swap_b32_e32 v139, v155
	v_permlane32_swap_b32_e32 v140, v156
	v_permlane32_swap_b32_e32 v141, v157
	v_permlane32_swap_b32_e32 v142, v158
	v_permlane32_swap_b32_e32 v143, v159
	v_permlane32_swap_b32_e32 v144, v160
	v_permlane32_swap_b32_e32 v145, v161
	v_permlane32_swap_b32_e32 v146, v162
	v_permlane32_swap_b32_e32 v147, v163
	s_waitcnt lgkmcnt(15)
	v_fma_f32 v116, v181, v252, -v132
	v_add_f32_e32 v42, 0, v116
	s_waitcnt lgkmcnt(15)
	v_fma_f32 v116, v182, v253, -v133
	v_fmac_f32_dpp v116, -v170, v42 quad_perm:[0,0,0,0] row_mask:0xf bank_mask:0xf
	v_add_f32_e32 v43, 0, v116
	s_waitcnt lgkmcnt(15)
	v_fma_f32 v116, v183, v126, -v134
	v_fmac_f32_dpp v116, -v186, v42 quad_perm:[0,0,0,0] row_mask:0xf bank_mask:0xf
	v_mul_f32_dpp v117, -v187, v43 quad_perm:[0,0,0,0] row_mask:0xf bank_mask:0xf
	ds_read_b32 v214, v124 offset:168
	v_add_f32_e32 v44, v117, v116
	s_waitcnt lgkmcnt(15)
	v_fma_f32 v116, v185, v127, -v135
	v_fmac_f32_dpp v116, -v188, v42 quad_perm:[0,0,0,0] row_mask:0xf bank_mask:0xf
	v_mul_f32_dpp v117, -v189, v43 quad_perm:[0,0,0,0] row_mask:0xf bank_mask:0xf
	v_mul_f32_dpp v118, -v188, v44 quad_perm:[1,1,1,1] row_mask:0xf bank_mask:0xf
	ds_read_u16_d16_hi v250, v123 offset:11424
	v_add_f32_e32 v121, v117, v116
	v_add_f32_e32 v45, v118, v121
	s_waitcnt lgkmcnt(15)
	v_fma_f32 v116, v208, v244, -v148
	v_fmac_f32_dpp v116, -v190, v42 quad_perm:[0,0,0,0] row_mask:0xf bank_mask:0xf
	v_mul_f32_dpp v117, -v191, v43 quad_perm:[0,0,0,0] row_mask:0xf bank_mask:0xf
	v_mul_f32_dpp v118, -v190, v44 quad_perm:[1,1,1,1] row_mask:0xf bank_mask:0xf
	ds_read_b64 v[164:165], v125 offset:11824
	v_mul_f32_dpp v119, -v191, v45 quad_perm:[1,1,1,1] row_mask:0xf bank_mask:0xf
	v_add_f32_e32 v121, v117, v116
	v_add_f32_e32 v122, v118, v119
	v_add_f32_e32 v46, v122, v121
	s_waitcnt lgkmcnt(15)
	v_fma_f32 v116, v209, v245, -v149
	v_fmac_f32_dpp v116, -v192, v42 quad_perm:[0,0,0,0] row_mask:0xf bank_mask:0xf
	v_mul_f32_dpp v117, -v193, v43 quad_perm:[0,0,0,0] row_mask:0xf bank_mask:0xf
	ds_read_b64 v[166:167], v125 offset:11856
	v_mul_f32_dpp v118, -v192, v44 quad_perm:[1,1,1,1] row_mask:0xf bank_mask:0xf
	v_mul_f32_dpp v119, -v193, v45 quad_perm:[1,1,1,1] row_mask:0xf bank_mask:0xf
	v_fmac_f32_dpp v116, -v192, v46 quad_perm:[2,2,2,2] row_mask:0xf bank_mask:0xf
	ds_read_b32 v215, v124 offset:172
	v_add_f32_e32 v121, v117, v116
	v_add_f32_e32 v122, v118, v119
	v_add_f32_e32 v47, v122, v121
	s_waitcnt lgkmcnt(15)
	v_fma_f32 v116, v210, v246, -v150
	v_fmac_f32_dpp v116, -v194, v42 quad_perm:[0,0,0,0] row_mask:0xf bank_mask:0xf
	v_mul_f32_dpp v117, -v195, v43 quad_perm:[0,0,0,0] row_mask:0xf bank_mask:0xf
	v_mul_f32_dpp v118, -v194, v44 quad_perm:[1,1,1,1] row_mask:0xf bank_mask:0xf
	ds_read_u16_d16_hi v251, v123 offset:11696
	v_mul_f32_dpp v119, -v195, v45 quad_perm:[1,1,1,1] row_mask:0xf bank_mask:0xf
	v_fmac_f32_dpp v116, -v194, v46 quad_perm:[2,2,2,2] row_mask:0xf bank_mask:0xf
	v_fmac_f32_dpp v117, -v195, v47 quad_perm:[2,2,2,2] row_mask:0xf bank_mask:0xf
	ds_read_b64 v[168:169], v125 offset:12096
	v_add_f32_e32 v121, v117, v116
	v_add_f32_e32 v122, v118, v119
	v_add_f32_e32 v48, v122, v121
	s_waitcnt lgkmcnt(15)
	v_fma_f32 v116, v211, v247, -v151
	v_fmac_f32_dpp v116, -v196, v42 quad_perm:[0,0,0,0] row_mask:0xf bank_mask:0xf
	v_mul_f32_dpp v117, -v197, v43 quad_perm:[0,0,0,0] row_mask:0xf bank_mask:0xf
	v_mul_f32_dpp v118, -v196, v44 quad_perm:[1,1,1,1] row_mask:0xf bank_mask:0xf
	ds_read_b64 v[172:173], v125 offset:12128
	v_mul_f32_dpp v119, -v197, v45 quad_perm:[1,1,1,1] row_mask:0xf bank_mask:0xf
	v_fmac_f32_dpp v116, -v196, v46 quad_perm:[2,2,2,2] row_mask:0xf bank_mask:0xf
	v_fmac_f32_dpp v117, -v197, v47 quad_perm:[2,2,2,2] row_mask:0xf bank_mask:0xf
	ds_read_b32 v216, v124 offset:176
	v_fmac_f32_dpp v118, -v196, v48 quad_perm:[3,3,3,3] row_mask:0xf bank_mask:0xf
	v_add_f32_e32 v121, v117, v116
	v_add_f32_e32 v122, v118, v119
	v_add_f32_e32 v49, v122, v121
	s_waitcnt lgkmcnt(15)
; __device__ __forceinline__ float bf2f(bf16 v) { return __uint_as_float(((unsigned)v) << 16); }
; #define GDN_LOADROW(buf, rr_, i_) do { _Pragma("unroll") for (int j4 = 0; j4 < ((i_) + 3) / 4; ++j4) buf[j4] = *(const f32x4*)(Lm + (i_) * GP_LSTR + 4 * j4); rr_ = bf2f(*(const bf16*)(xsrc + (i_) * GP_STR * 2)) * scl[i_]; } while (0)
; template <int STRIP> __device__ __forceinline__ void ph_gdn_prep_fast(const bf16* __restrict__ proj, const float* __restrict__ small, const float* __restrict__ conv_w, const float* __restrict__ a_log, const float* __restrict__ dt_bias, ...
;     ...
;             float U[64];
;             const float* scl = isw ? (sgc + 256) : sbeta;
;             f32x4 bA[16], bB[16]; float rA, rB = 0.f;
;             rA = bf2f(*(const bf16*)xsrc) * scl[0];
;     ...
; #pragma unroll
;             for (int i = 0; i < 64; i += 2) {
;                 GDN_LOADROW(bB, rB, i + 1);
;                 GDN_ROW(bA, rA, i);
;                 if (i + 2 < 64) GDN_LOADROW(bA, rA, i + 2);
;                 GDN_ROW(bB, rB, i + 1);
;             }
	v_fma_f32 v116, v212, v248, -v136
	v_fmac_f32_dpp v116, -v198, v42 quad_perm:[0,0,0,0] row_mask:0xf bank_mask:0xf
	v_mul_f32_dpp v117, -v199, v43 quad_perm:[0,0,0,0] row_mask:0xf bank_mask:0xf
	ds_read_u16_d16_hi v252, v123 offset:11968
	v_mul_f32_dpp v118, -v198, v44 quad_perm:[1,1,1,1] row_mask:0xf bank_mask:0xf
	v_mul_f32_dpp v119, -v199, v45 quad_perm:[1,1,1,1] row_mask:0xf bank_mask:0xf
	v_fmac_f32_dpp v116, -v198, v46 quad_perm:[2,2,2,2] row_mask:0xf bank_mask:0xf
	ds_read_b64 v[174:175], v125 offset:12368
	v_fmac_f32_dpp v117, -v199, v47 quad_perm:[2,2,2,2] row_mask:0xf bank_mask:0xf
	v_fmac_f32_dpp v118, -v198, v48 quad_perm:[3,3,3,3] row_mask:0xf bank_mask:0xf
	v_fmac_f32_dpp v119, -v199, v49 quad_perm:[3,3,3,3] row_mask:0xf bank_mask:0xf
	ds_read_b64 v[176:177], v125 offset:12400
	v_add_f32_e32 v121, v117, v116
	v_add_f32_e32 v122, v118, v119
	v_add_f32_e32 v50, v122, v121
	s_waitcnt lgkmcnt(14)
	v_fma_f32 v116, v213, v249, -v137
	v_fmac_f32_dpp v116, -v200, v42 quad_perm:[0,0,0,0] row_mask:0xf bank_mask:0xf
	v_mul_f32_dpp v117, -v201, v43 quad_perm:[0,0,0,0] row_mask:0xf bank_mask:0xf
	v_mul_f32_dpp v118, -v200, v44 quad_perm:[1,1,1,1] row_mask:0xf bank_mask:0xf
	ds_read_b32 v217, v124 offset:180
	v_mul_f32_dpp v119, -v201, v45 quad_perm:[1,1,1,1] row_mask:0xf bank_mask:0xf
	v_fmac_f32_dpp v116, -v200, v46 quad_perm:[2,2,2,2] row_mask:0xf bank_mask:0xf
	v_fmac_f32_dpp v117, -v201, v47 quad_perm:[2,2,2,2] row_mask:0xf bank_mask:0xf
	ds_read_u16_d16_hi v253, v123 offset:12240
	v_fmac_f32_dpp v118, -v200, v48 quad_perm:[3,3,3,3] row_mask:0xf bank_mask:0xf
	v_fmac_f32_dpp v119, -v201, v49 quad_perm:[3,3,3,3] row_mask:0xf bank_mask:0xf
	v_fmac_f32_dpp v116, -v202, v50 quad_perm:[0,0,0,0] row_mask:0xf bank_mask:0xf
	ds_read_b64 v[178:179], v125 offset:12640
	v_add_f32_e32 v121, v117, v116
	v_add_f32_e32 v122, v118, v119
	v_add_f32_e32 v51, v122, v121
	s_waitcnt lgkmcnt(13)
	v_fma_f32 v116, v214, v250, -v138
	v_fmac_f32_dpp v116, -v204, v42 quad_perm:[0,0,0,0] row_mask:0xf bank_mask:0xf
	v_mul_f32_dpp v117, -v205, v43 quad_perm:[0,0,0,0] row_mask:0xf bank_mask:0xf
	v_mul_f32_dpp v118, -v204, v44 quad_perm:[1,1,1,1] row_mask:0xf bank_mask:0xf
	ds_read_b64 v[222:223], v125 offset:12672
	v_mul_f32_dpp v119, -v205, v45 quad_perm:[1,1,1,1] row_mask:0xf bank_mask:0xf
	v_fmac_f32_dpp v116, -v204, v46 quad_perm:[2,2,2,2] row_mask:0xf bank_mask:0xf
	v_fmac_f32_dpp v117, -v205, v47 quad_perm:[2,2,2,2] row_mask:0xf bank_mask:0xf
	ds_read_b32 v218, v124 offset:184
	v_fmac_f32_dpp v118, -v204, v48 quad_perm:[3,3,3,3] row_mask:0xf bank_mask:0xf
	v_fmac_f32_dpp v119, -v205, v49 quad_perm:[3,3,3,3] row_mask:0xf bank_mask:0xf
	v_fmac_f32_dpp v116, -v206, v50 quad_perm:[0,0,0,0] row_mask:0xf bank_mask:0xf
	ds_read_u16_d16_hi v126, v123 offset:12512
	v_fmac_f32_dpp v117, -v207, v51 quad_perm:[0,0,0,0] row_mask:0xf bank_mask:0xf
	v_add_f32_e32 v121, v117, v116
	v_add_f32_e32 v122, v118, v119
	v_add_f32_e32 v52, v122, v121
	s_waitcnt lgkmcnt(12)
	v_fma_f32 v116, v215, v251, -v139
	v_fmac_f32_dpp v116, -v164, v42 quad_perm:[0,0,0,0] row_mask:0xf bank_mask:0xf
	v_mul_f32_dpp v117, -v165, v43 quad_perm:[0,0,0,0] row_mask:0xf bank_mask:0xf
	ds_read_b64 v[224:225], v125 offset:12912
	v_mul_f32_dpp v118, -v164, v44 quad_perm:[1,1,1,1] row_mask:0xf bank_mask:0xf
	v_mul_f32_dpp v119, -v165, v45 quad_perm:[1,1,1,1] row_mask:0xf bank_mask:0xf
	v_fmac_f32_dpp v116, -v164, v46 quad_perm:[2,2,2,2] row_mask:0xf bank_mask:0xf
	ds_read_b64 v[226:227], v125 offset:12944
	v_fmac_f32_dpp v117, -v165, v47 quad_perm:[2,2,2,2] row_mask:0xf bank_mask:0xf
	v_fmac_f32_dpp v118, -v164, v48 quad_perm:[3,3,3,3] row_mask:0xf bank_mask:0xf
	v_fmac_f32_dpp v119, -v165, v49 quad_perm:[3,3,3,3] row_mask:0xf bank_mask:0xf
	ds_read_b32 v219, v124 offset:188
	v_fmac_f32_dpp v116, -v166, v50 quad_perm:[0,0,0,0] row_mask:0xf bank_mask:0xf
	v_fmac_f32_dpp v117, -v167, v51 quad_perm:[0,0,0,0] row_mask:0xf bank_mask:0xf
	v_fmac_f32_dpp v118, -v166, v52 quad_perm:[1,1,1,1] row_mask:0xf bank_mask:0xf
	ds_read_u16_d16_hi v127, v123 offset:12784
	v_add_f32_e32 v121, v117, v116
	v_add_f32_e32 v122, v118, v119
	v_add_f32_e32 v53, v122, v121
	s_waitcnt lgkmcnt(12)
	v_fma_f32 v116, v216, v252, -v152
	v_fmac_f32_dpp v116, -v168, v42 quad_perm:[0,0,0,0] row_mask:0xf bank_mask:0xf
	v_mul_f32_dpp v117, -v169, v43 quad_perm:[0,0,0,0] row_mask:0xf bank_mask:0xf
	v_mul_f32_dpp v118, -v168, v44 quad_perm:[1,1,1,1] row_mask:0xf bank_mask:0xf
	ds_read_b64 v[228:229], v125 offset:13184
	v_mul_f32_dpp v119, -v169, v45 quad_perm:[1,1,1,1] row_mask:0xf bank_mask:0xf
	v_fmac_f32_dpp v116, -v168, v46 quad_perm:[2,2,2,2] row_mask:0xf bank_mask:0xf
	v_fmac_f32_dpp v117, -v169, v47 quad_perm:[2,2,2,2] row_mask:0xf bank_mask:0xf
	ds_read_b64 v[170:171], v125 offset:13216
	v_fmac_f32_dpp v118, -v168, v48 quad_perm:[3,3,3,3] row_mask:0xf bank_mask:0xf
	v_fmac_f32_dpp v119, -v169, v49 quad_perm:[3,3,3,3] row_mask:0xf bank_mask:0xf
	v_fmac_f32_dpp v116, -v172, v50 quad_perm:[0,0,0,0] row_mask:0xf bank_mask:0xf
	ds_read_b32 v220, v124 offset:192
	v_fmac_f32_dpp v117, -v173, v51 quad_perm:[0,0,0,0] row_mask:0xf bank_mask:0xf
	v_fmac_f32_dpp v118, -v172, v52 quad_perm:[1,1,1,1] row_mask:0xf bank_mask:0xf
	v_fmac_f32_dpp v119, -v173, v53 quad_perm:[1,1,1,1] row_mask:0xf bank_mask:0xf
	ds_read_u16_d16_hi v244, v123 offset:13056
	v_add_f32_e32 v121, v117, v116
	v_add_f32_e32 v122, v118, v119
	v_add_f32_e32 v54, v122, v121
	s_waitcnt lgkmcnt(12)
; __device__ __forceinline__ float bf2f(bf16 v) { return __uint_as_float(((unsigned)v) << 16); }
; #define GDN_LOADROW(buf, rr_, i_) do { _Pragma("unroll") for (int j4 = 0; j4 < ((i_) + 3) / 4; ++j4) buf[j4] = *(const f32x4*)(Lm + (i_) * GP_LSTR + 4 * j4); rr_ = bf2f(*(const bf16*)(xsrc + (i_) * GP_STR * 2)) * scl[i_]; } while (0)
; template <int STRIP> __device__ __forceinline__ void ph_gdn_prep_fast(const bf16* __restrict__ proj, const float* __restrict__ small, const float* __restrict__ conv_w, const float* __restrict__ a_log, const float* __restrict__ dt_bias, ...
;     ...
;             float U[64];
;             const float* scl = isw ? (sgc + 256) : sbeta;
;             f32x4 bA[16], bB[16]; float rA, rB = 0.f;
;             rA = bf2f(*(const bf16*)xsrc) * scl[0];
;     ...
; #pragma unroll
;             for (int i = 0; i < 64; i += 2) {
;                 GDN_LOADROW(bB, rB, i + 1);
;                 GDN_ROW(bA, rA, i);
;                 if (i + 2 < 64) GDN_LOADROW(bA, rA, i + 2);
;                 GDN_ROW(bB, rB, i + 1);
;             }
	v_fma_f32 v116, v217, v253, -v153
	v_fmac_f32_dpp v116, -v174, v42 quad_perm:[0,0,0,0] row_mask:0xf bank_mask:0xf
	v_mul_f32_dpp v117, -v175, v43 quad_perm:[0,0,0,0] row_mask:0xf bank_mask:0xf
	v_mul_f32_dpp v118, -v174, v44 quad_perm:[1,1,1,1] row_mask:0xf bank_mask:0xf
	ds_read_b64 v[186:187], v125 offset:13456
	v_mul_f32_dpp v119, -v175, v45 quad_perm:[1,1,1,1] row_mask:0xf bank_mask:0xf
	v_fmac_f32_dpp v116, -v174, v46 quad_perm:[2,2,2,2] row_mask:0xf bank_mask:0xf
	v_fmac_f32_dpp v117, -v175, v47 quad_perm:[2,2,2,2] row_mask:0xf bank_mask:0xf
	ds_read_b64 v[188:189], v125 offset:13488
	v_fmac_f32_dpp v118, -v174, v48 quad_perm:[3,3,3,3] row_mask:0xf bank_mask:0xf
	v_fmac_f32_dpp v119, -v175, v49 quad_perm:[3,3,3,3] row_mask:0xf bank_mask:0xf
	v_fmac_f32_dpp v116, -v176, v50 quad_perm:[0,0,0,0] row_mask:0xf bank_mask:0xf
	ds_read_b64 v[190:191], v125 offset:13520
	v_fmac_f32_dpp v117, -v177, v51 quad_perm:[0,0,0,0] row_mask:0xf bank_mask:0xf
	v_fmac_f32_dpp v118, -v176, v52 quad_perm:[1,1,1,1] row_mask:0xf bank_mask:0xf
	v_fmac_f32_dpp v119, -v177, v53 quad_perm:[1,1,1,1] row_mask:0xf bank_mask:0xf
	ds_read_b32 v221, v124 offset:196
	v_fmac_f32_dpp v116, -v176, v54 quad_perm:[2,2,2,2] row_mask:0xf bank_mask:0xf
	v_add_f32_e32 v121, v117, v116
	v_add_f32_e32 v122, v118, v119
	v_add_f32_e32 v55, v122, v121
	s_waitcnt lgkmcnt(12)
	v_fma_f32 v116, v218, v126, -v154
	v_fmac_f32_dpp v116, -v178, v42 quad_perm:[0,0,0,0] row_mask:0xf bank_mask:0xf
	v_mul_f32_dpp v117, -v179, v43 quad_perm:[0,0,0,0] row_mask:0xf bank_mask:0xf
	ds_read_u16_d16_hi v245, v123 offset:13328
	v_mul_f32_dpp v118, -v178, v44 quad_perm:[1,1,1,1] row_mask:0xf bank_mask:0xf
	v_mul_f32_dpp v119, -v179, v45 quad_perm:[1,1,1,1] row_mask:0xf bank_mask:0xf
	v_fmac_f32_dpp v116, -v178, v46 quad_perm:[2,2,2,2] row_mask:0xf bank_mask:0xf
	ds_read_b64 v[192:193], v125 offset:13728
	v_fmac_f32_dpp v117, -v179, v47 quad_perm:[2,2,2,2] row_mask:0xf bank_mask:0xf
	v_fmac_f32_dpp v118, -v178, v48 quad_perm:[3,3,3,3] row_mask:0xf bank_mask:0xf
	v_fmac_f32_dpp v119, -v179, v49 quad_perm:[3,3,3,3] row_mask:0xf bank_mask:0xf
	ds_read_b64 v[194:195], v125 offset:13760
	v_fmac_f32_dpp v116, -v222, v50 quad_perm:[0,0,0,0] row_mask:0xf bank_mask:0xf
	v_fmac_f32_dpp v117, -v223, v51 quad_perm:[0,0,0,0] row_mask:0xf bank_mask:0xf
	v_fmac_f32_dpp v118, -v222, v52 quad_perm:[1,1,1,1] row_mask:0xf bank_mask:0xf
	ds_read_b64 v[196:197], v125 offset:13792
	v_fmac_f32_dpp v119, -v223, v53 quad_perm:[1,1,1,1] row_mask:0xf bank_mask:0xf
	v_fmac_f32_dpp v116, -v222, v54 quad_perm:[2,2,2,2] row_mask:0xf bank_mask:0xf
	v_fmac_f32_dpp v117, -v223, v55 quad_perm:[2,2,2,2] row_mask:0xf bank_mask:0xf
	ds_read_b32 v181, v124 offset:200
	v_add_f32_e32 v121, v117, v116
	v_add_f32_e32 v122, v118, v119
	v_add_f32_e32 v56, v122, v121
	s_waitcnt lgkmcnt(13)
	v_fma_f32 v116, v219, v127, -v155
	v_fmac_f32_dpp v116, -v224, v42 quad_perm:[0,0,0,0] row_mask:0xf bank_mask:0xf
	v_mul_f32_dpp v117, -v225, v43 quad_perm:[0,0,0,0] row_mask:0xf bank_mask:0xf
	v_mul_f32_dpp v118, -v224, v44 quad_perm:[1,1,1,1] row_mask:0xf bank_mask:0xf
	ds_read_u16_d16_hi v246, v123 offset:13600
	v_mul_f32_dpp v119, -v225, v45 quad_perm:[1,1,1,1] row_mask:0xf bank_mask:0xf
	v_fmac_f32_dpp v116, -v224, v46 quad_perm:[2,2,2,2] row_mask:0xf bank_mask:0xf
	v_fmac_f32_dpp v117, -v225, v47 quad_perm:[2,2,2,2] row_mask:0xf bank_mask:0xf
	ds_read_b64 v[198:199], v125 offset:14000
	v_fmac_f32_dpp v118, -v224, v48 quad_perm:[3,3,3,3] row_mask:0xf bank_mask:0xf
	v_fmac_f32_dpp v119, -v225, v49 quad_perm:[3,3,3,3] row_mask:0xf bank_mask:0xf
	v_fmac_f32_dpp v116, -v226, v50 quad_perm:[0,0,0,0] row_mask:0xf bank_mask:0xf
	ds_read_b64 v[200:201], v125 offset:14032
	v_fmac_f32_dpp v117, -v227, v51 quad_perm:[0,0,0,0] row_mask:0xf bank_mask:0xf
	v_fmac_f32_dpp v118, -v226, v52 quad_perm:[1,1,1,1] row_mask:0xf bank_mask:0xf
	v_fmac_f32_dpp v119, -v227, v53 quad_perm:[1,1,1,1] row_mask:0xf bank_mask:0xf
	ds_read_b64 v[202:203], v125 offset:14064
	v_fmac_f32_dpp v116, -v226, v54 quad_perm:[2,2,2,2] row_mask:0xf bank_mask:0xf
	v_fmac_f32_dpp v117, -v227, v55 quad_perm:[2,2,2,2] row_mask:0xf bank_mask:0xf
	v_fmac_f32_dpp v118, -v226, v56 quad_perm:[3,3,3,3] row_mask:0xf bank_mask:0xf
	ds_read_b32 v182, v124 offset:204
	v_add_f32_e32 v121, v117, v116
	v_add_f32_e32 v122, v118, v119
	v_add_f32_e32 v57, v122, v121
	s_waitcnt lgkmcnt(14)
	v_fma_f32 v116, v220, v244, -v140
	v_fmac_f32_dpp v116, -v228, v42 quad_perm:[0,0,0,0] row_mask:0xf bank_mask:0xf
	v_mul_f32_dpp v117, -v229, v43 quad_perm:[0,0,0,0] row_mask:0xf bank_mask:0xf
	v_mul_f32_dpp v118, -v228, v44 quad_perm:[1,1,1,1] row_mask:0xf bank_mask:0xf
	ds_read_u16_d16_hi v247, v123 offset:13872
	v_mul_f32_dpp v119, -v229, v45 quad_perm:[1,1,1,1] row_mask:0xf bank_mask:0xf
	v_fmac_f32_dpp v116, -v228, v46 quad_perm:[2,2,2,2] row_mask:0xf bank_mask:0xf
	v_fmac_f32_dpp v117, -v229, v47 quad_perm:[2,2,2,2] row_mask:0xf bank_mask:0xf
	ds_read_b64 v[204:205], v125 offset:14272
	v_fmac_f32_dpp v118, -v228, v48 quad_perm:[3,3,3,3] row_mask:0xf bank_mask:0xf
	v_fmac_f32_dpp v119, -v229, v49 quad_perm:[3,3,3,3] row_mask:0xf bank_mask:0xf
	v_fmac_f32_dpp v116, -v170, v50 quad_perm:[0,0,0,0] row_mask:0xf bank_mask:0xf
	ds_read_b64 v[206:207], v125 offset:14304
	v_fmac_f32_dpp v117, -v171, v51 quad_perm:[0,0,0,0] row_mask:0xf bank_mask:0xf
	v_fmac_f32_dpp v118, -v170, v52 quad_perm:[1,1,1,1] row_mask:0xf bank_mask:0xf
	v_fmac_f32_dpp v119, -v171, v53 quad_perm:[1,1,1,1] row_mask:0xf bank_mask:0xf
	ds_read_b64 v[164:165], v125 offset:14336
	v_fmac_f32_dpp v116, -v170, v54 quad_perm:[2,2,2,2] row_mask:0xf bank_mask:0xf
	v_fmac_f32_dpp v117, -v171, v55 quad_perm:[2,2,2,2] row_mask:0xf bank_mask:0xf
	v_fmac_f32_dpp v118, -v170, v56 quad_perm:[3,3,3,3] row_mask:0xf bank_mask:0xf
	ds_read_b32 v183, v124 offset:208
	v_fmac_f32_dpp v119, -v171, v57 quad_perm:[3,3,3,3] row_mask:0xf bank_mask:0xf
	v_add_f32_e32 v121, v117, v116
	v_add_f32_e32 v122, v118, v119
	v_add_f32_e32 v58, v122, v121
	s_waitcnt lgkmcnt(14)
; __device__ __forceinline__ float bf2f(bf16 v) { return __uint_as_float(((unsigned)v) << 16); }
; #define GDN_LOADROW(buf, rr_, i_) do { _Pragma("unroll") for (int j4 = 0; j4 < ((i_) + 3) / 4; ++j4) buf[j4] = *(const f32x4*)(Lm + (i_) * GP_LSTR + 4 * j4); rr_ = bf2f(*(const bf16*)(xsrc + (i_) * GP_STR * 2)) * scl[i_]; } while (0)
; template <int STRIP> __device__ __forceinline__ void ph_gdn_prep_fast(const bf16* __restrict__ proj, const float* __restrict__ small, const float* __restrict__ conv_w, const float* __restrict__ a_log, const float* __restrict__ dt_bias, ...
;     ...
;             float U[64];
;             const float* scl = isw ? (sgc + 256) : sbeta;
;             f32x4 bA[16], bB[16]; float rA, rB = 0.f;
;             rA = bf2f(*(const bf16*)xsrc) * scl[0];
;     ...
; #pragma unroll
;             for (int i = 0; i < 64; i += 2) {
;                 GDN_LOADROW(bB, rB, i + 1);
;                 GDN_ROW(bA, rA, i);
;                 if (i + 2 < 64) GDN_LOADROW(bA, rA, i + 2);
;                 GDN_ROW(bB, rB, i + 1);
;             }
	v_fma_f32 v116, v221, v245, -v141
	v_fmac_f32_dpp v116, -v186, v42 quad_perm:[0,0,0,0] row_mask:0xf bank_mask:0xf
	v_mul_f32_dpp v117, -v187, v43 quad_perm:[0,0,0,0] row_mask:0xf bank_mask:0xf
	ds_read_u16_d16_hi v248, v123 offset:14144
	v_mul_f32_dpp v118, -v186, v44 quad_perm:[1,1,1,1] row_mask:0xf bank_mask:0xf
	v_mul_f32_dpp v119, -v187, v45 quad_perm:[1,1,1,1] row_mask:0xf bank_mask:0xf
	v_fmac_f32_dpp v116, -v186, v46 quad_perm:[2,2,2,2] row_mask:0xf bank_mask:0xf
	ds_read_b64 v[166:167], v125 offset:14544
	v_fmac_f32_dpp v117, -v187, v47 quad_perm:[2,2,2,2] row_mask:0xf bank_mask:0xf
	v_fmac_f32_dpp v118, -v186, v48 quad_perm:[3,3,3,3] row_mask:0xf bank_mask:0xf
	v_fmac_f32_dpp v119, -v187, v49 quad_perm:[3,3,3,3] row_mask:0xf bank_mask:0xf
	ds_read_b64 v[168:169], v125 offset:14576
	v_fmac_f32_dpp v116, -v188, v50 quad_perm:[0,0,0,0] row_mask:0xf bank_mask:0xf
	v_fmac_f32_dpp v117, -v189, v51 quad_perm:[0,0,0,0] row_mask:0xf bank_mask:0xf
	v_fmac_f32_dpp v118, -v188, v52 quad_perm:[1,1,1,1] row_mask:0xf bank_mask:0xf
	ds_read_b64 v[172:173], v125 offset:14608
	v_fmac_f32_dpp v119, -v189, v53 quad_perm:[1,1,1,1] row_mask:0xf bank_mask:0xf
	v_fmac_f32_dpp v116, -v188, v54 quad_perm:[2,2,2,2] row_mask:0xf bank_mask:0xf
	v_fmac_f32_dpp v117, -v189, v55 quad_perm:[2,2,2,2] row_mask:0xf bank_mask:0xf
	ds_read_b32 v185, v124 offset:212
	v_fmac_f32_dpp v118, -v188, v56 quad_perm:[3,3,3,3] row_mask:0xf bank_mask:0xf
	v_fmac_f32_dpp v119, -v189, v57 quad_perm:[3,3,3,3] row_mask:0xf bank_mask:0xf
	v_fmac_f32_dpp v116, -v190, v58 quad_perm:[0,0,0,0] row_mask:0xf bank_mask:0xf
	ds_read_u16_d16_hi v249, v123 offset:14416
	v_add_f32_e32 v121, v117, v116
	v_add_f32_e32 v122, v118, v119
	v_add_f32_e32 v59, v122, v121
	s_waitcnt lgkmcnt(15)
	v_fma_f32 v116, v181, v246, -v142
	v_fmac_f32_dpp v116, -v192, v42 quad_perm:[0,0,0,0] row_mask:0xf bank_mask:0xf
	v_mul_f32_dpp v117, -v193, v43 quad_perm:[0,0,0,0] row_mask:0xf bank_mask:0xf
	v_mul_f32_dpp v118, -v192, v44 quad_perm:[1,1,1,1] row_mask:0xf bank_mask:0xf
	ds_read_b64 v[174:175], v125 offset:14816
	v_mul_f32_dpp v119, -v193, v45 quad_perm:[1,1,1,1] row_mask:0xf bank_mask:0xf
	v_fmac_f32_dpp v116, -v192, v46 quad_perm:[2,2,2,2] row_mask:0xf bank_mask:0xf
	v_fmac_f32_dpp v117, -v193, v47 quad_perm:[2,2,2,2] row_mask:0xf bank_mask:0xf
	ds_read_b64 v[176:177], v125 offset:14848
	v_fmac_f32_dpp v118, -v192, v48 quad_perm:[3,3,3,3] row_mask:0xf bank_mask:0xf
	v_fmac_f32_dpp v119, -v193, v49 quad_perm:[3,3,3,3] row_mask:0xf bank_mask:0xf
	v_fmac_f32_dpp v116, -v194, v50 quad_perm:[0,0,0,0] row_mask:0xf bank_mask:0xf
	ds_read_b64 v[178:179], v125 offset:14880
	v_fmac_f32_dpp v117, -v195, v51 quad_perm:[0,0,0,0] row_mask:0xf bank_mask:0xf
	v_fmac_f32_dpp v118, -v194, v52 quad_perm:[1,1,1,1] row_mask:0xf bank_mask:0xf
	v_fmac_f32_dpp v119, -v195, v53 quad_perm:[1,1,1,1] row_mask:0xf bank_mask:0xf
	ds_read_b32 v208, v124 offset:216
	v_fmac_f32_dpp v116, -v194, v54 quad_perm:[2,2,2,2] row_mask:0xf bank_mask:0xf
	v_fmac_f32_dpp v117, -v195, v55 quad_perm:[2,2,2,2] row_mask:0xf bank_mask:0xf
	v_fmac_f32_dpp v118, -v194, v56 quad_perm:[3,3,3,3] row_mask:0xf bank_mask:0xf
	ds_read_u16_d16_hi v250, v123 offset:14688
	v_fmac_f32_dpp v119, -v195, v57 quad_perm:[3,3,3,3] row_mask:0xf bank_mask:0xf
	v_fmac_f32_dpp v116, -v196, v58 quad_perm:[0,0,0,0] row_mask:0xf bank_mask:0xf
	v_fmac_f32_dpp v117, -v197, v59 quad_perm:[0,0,0,0] row_mask:0xf bank_mask:0xf
	ds_read_b64 v[222:223], v125 offset:15088
	v_add_f32_e32 v121, v117, v116
	v_add_f32_e32 v122, v118, v119
	v_add_f32_e32 v60, v122, v121
	s_waitcnt lgkmcnt(15)
	v_fma_f32 v116, v182, v247, -v143
	v_fmac_f32_dpp v116, -v198, v42 quad_perm:[0,0,0,0] row_mask:0xf bank_mask:0xf
	v_mul_f32_dpp v117, -v199, v43 quad_perm:[0,0,0,0] row_mask:0xf bank_mask:0xf
	v_mul_f32_dpp v118, -v198, v44 quad_perm:[1,1,1,1] row_mask:0xf bank_mask:0xf
	ds_read_b64 v[224:225], v125 offset:15120
	v_mul_f32_dpp v119, -v199, v45 quad_perm:[1,1,1,1] row_mask:0xf bank_mask:0xf
	v_fmac_f32_dpp v116, -v198, v46 quad_perm:[2,2,2,2] row_mask:0xf bank_mask:0xf
	v_fmac_f32_dpp v117, -v199, v47 quad_perm:[2,2,2,2] row_mask:0xf bank_mask:0xf
	ds_read_b64 v[226:227], v125 offset:15152
	v_fmac_f32_dpp v118, -v198, v48 quad_perm:[3,3,3,3] row_mask:0xf bank_mask:0xf
	v_fmac_f32_dpp v119, -v199, v49 quad_perm:[3,3,3,3] row_mask:0xf bank_mask:0xf
	v_fmac_f32_dpp v116, -v200, v50 quad_perm:[0,0,0,0] row_mask:0xf bank_mask:0xf
	ds_read_b32 v209, v124 offset:220
	v_fmac_f32_dpp v117, -v201, v51 quad_perm:[0,0,0,0] row_mask:0xf bank_mask:0xf
	v_fmac_f32_dpp v118, -v200, v52 quad_perm:[1,1,1,1] row_mask:0xf bank_mask:0xf
	v_fmac_f32_dpp v119, -v201, v53 quad_perm:[1,1,1,1] row_mask:0xf bank_mask:0xf
	ds_read_u16_d16_hi v251, v123 offset:14960
	v_fmac_f32_dpp v116, -v200, v54 quad_perm:[2,2,2,2] row_mask:0xf bank_mask:0xf
	v_fmac_f32_dpp v117, -v201, v55 quad_perm:[2,2,2,2] row_mask:0xf bank_mask:0xf
	v_fmac_f32_dpp v118, -v200, v56 quad_perm:[3,3,3,3] row_mask:0xf bank_mask:0xf
	ds_read_b64 v[228:229], v125 offset:15360
	v_fmac_f32_dpp v119, -v201, v57 quad_perm:[3,3,3,3] row_mask:0xf bank_mask:0xf
	v_fmac_f32_dpp v116, -v202, v58 quad_perm:[0,0,0,0] row_mask:0xf bank_mask:0xf
	v_fmac_f32_dpp v117, -v203, v59 quad_perm:[0,0,0,0] row_mask:0xf bank_mask:0xf
	ds_read_b64 v[170:171], v125 offset:15392
	v_fmac_f32_dpp v118, -v202, v60 quad_perm:[1,1,1,1] row_mask:0xf bank_mask:0xf
	v_add_f32_e32 v121, v117, v116
	v_add_f32_e32 v122, v118, v119
	v_add_f32_e32 v61, v122, v121
	s_waitcnt lgkmcnt(15)
; __device__ __forceinline__ float bf2f(bf16 v) { return __uint_as_float(((unsigned)v) << 16); }
; #define GDN_LOADROW(buf, rr_, i_) do { _Pragma("unroll") for (int j4 = 0; j4 < ((i_) + 3) / 4; ++j4) buf[j4] = *(const f32x4*)(Lm + (i_) * GP_LSTR + 4 * j4); rr_ = bf2f(*(const bf16*)(xsrc + (i_) * GP_STR * 2)) * scl[i_]; } while (0)
; template <int STRIP> __device__ __forceinline__ void ph_gdn_prep_fast(const bf16* __restrict__ proj, const float* __restrict__ small, const float* __restrict__ conv_w, const float* __restrict__ a_log, const float* __restrict__ dt_bias, ...
;     ...
;             float U[64];
;             const float* scl = isw ? (sgc + 256) : sbeta;
;             f32x4 bA[16], bB[16]; float rA, rB = 0.f;
;             rA = bf2f(*(const bf16*)xsrc) * scl[0];
;     ...
; #pragma unroll
;             for (int i = 0; i < 64; i += 2) {
;                 GDN_LOADROW(bB, rB, i + 1);
;                 GDN_ROW(bA, rA, i);
;                 if (i + 2 < 64) GDN_LOADROW(bA, rA, i + 2);
;                 GDN_ROW(bB, rB, i + 1);
;             }
	v_fma_f32 v116, v183, v248, -v156
	v_fmac_f32_dpp v116, -v204, v42 quad_perm:[0,0,0,0] row_mask:0xf bank_mask:0xf
	v_mul_f32_dpp v117, -v205, v43 quad_perm:[0,0,0,0] row_mask:0xf bank_mask:0xf
	ds_read_b64 v[186:187], v125 offset:15424
	v_mul_f32_dpp v118, -v204, v44 quad_perm:[1,1,1,1] row_mask:0xf bank_mask:0xf
	v_mul_f32_dpp v119, -v205, v45 quad_perm:[1,1,1,1] row_mask:0xf bank_mask:0xf
	v_fmac_f32_dpp v116, -v204, v46 quad_perm:[2,2,2,2] row_mask:0xf bank_mask:0xf
	ds_read_b32 v210, v124 offset:224
	v_fmac_f32_dpp v117, -v205, v47 quad_perm:[2,2,2,2] row_mask:0xf bank_mask:0xf
	v_fmac_f32_dpp v118, -v204, v48 quad_perm:[3,3,3,3] row_mask:0xf bank_mask:0xf
	v_fmac_f32_dpp v119, -v205, v49 quad_perm:[3,3,3,3] row_mask:0xf bank_mask:0xf
	ds_read_u16_d16_hi v252, v123 offset:15232
	v_fmac_f32_dpp v116, -v206, v50 quad_perm:[0,0,0,0] row_mask:0xf bank_mask:0xf
	v_fmac_f32_dpp v117, -v207, v51 quad_perm:[0,0,0,0] row_mask:0xf bank_mask:0xf
	v_fmac_f32_dpp v118, -v206, v52 quad_perm:[1,1,1,1] row_mask:0xf bank_mask:0xf
	ds_read_b64 v[188:189], v125 offset:15632
	v_fmac_f32_dpp v119, -v207, v53 quad_perm:[1,1,1,1] row_mask:0xf bank_mask:0xf
	v_fmac_f32_dpp v116, -v206, v54 quad_perm:[2,2,2,2] row_mask:0xf bank_mask:0xf
	v_fmac_f32_dpp v117, -v207, v55 quad_perm:[2,2,2,2] row_mask:0xf bank_mask:0xf
	ds_read_b64 v[190:191], v125 offset:15664
	v_fmac_f32_dpp v118, -v206, v56 quad_perm:[3,3,3,3] row_mask:0xf bank_mask:0xf
	v_fmac_f32_dpp v119, -v207, v57 quad_perm:[3,3,3,3] row_mask:0xf bank_mask:0xf
	v_fmac_f32_dpp v116, -v164, v58 quad_perm:[0,0,0,0] row_mask:0xf bank_mask:0xf
	ds_read_b64 v[192:193], v125 offset:15696
	v_fmac_f32_dpp v117, -v165, v59 quad_perm:[0,0,0,0] row_mask:0xf bank_mask:0xf
	v_fmac_f32_dpp v118, -v164, v60 quad_perm:[1,1,1,1] row_mask:0xf bank_mask:0xf
	v_fmac_f32_dpp v119, -v165, v61 quad_perm:[1,1,1,1] row_mask:0xf bank_mask:0xf
	ds_read_b64 v[194:195], v125 offset:15728
	v_add_f32_e32 v121, v117, v116
	v_add_f32_e32 v122, v118, v119
	v_add_f32_e32 v62, v122, v121
	s_waitcnt lgkmcnt(15)
	v_fma_f32 v116, v185, v249, -v157
	v_fmac_f32_dpp v116, -v166, v42 quad_perm:[0,0,0,0] row_mask:0xf bank_mask:0xf
	v_mul_f32_dpp v117, -v167, v43 quad_perm:[0,0,0,0] row_mask:0xf bank_mask:0xf
	v_mul_f32_dpp v118, -v166, v44 quad_perm:[1,1,1,1] row_mask:0xf bank_mask:0xf
	ds_read_b32 v211, v124 offset:228
	v_mul_f32_dpp v119, -v167, v45 quad_perm:[1,1,1,1] row_mask:0xf bank_mask:0xf
	v_fmac_f32_dpp v116, -v166, v46 quad_perm:[2,2,2,2] row_mask:0xf bank_mask:0xf
	v_fmac_f32_dpp v117, -v167, v47 quad_perm:[2,2,2,2] row_mask:0xf bank_mask:0xf
	ds_read_u16_d16_hi v253, v123 offset:15504
	v_fmac_f32_dpp v118, -v166, v48 quad_perm:[3,3,3,3] row_mask:0xf bank_mask:0xf
	v_fmac_f32_dpp v119, -v167, v49 quad_perm:[3,3,3,3] row_mask:0xf bank_mask:0xf
	v_fmac_f32_dpp v116, -v168, v50 quad_perm:[0,0,0,0] row_mask:0xf bank_mask:0xf
	ds_read_b64 v[196:197], v125 offset:15904
	v_fmac_f32_dpp v117, -v169, v51 quad_perm:[0,0,0,0] row_mask:0xf bank_mask:0xf
	v_fmac_f32_dpp v118, -v168, v52 quad_perm:[1,1,1,1] row_mask:0xf bank_mask:0xf
	v_fmac_f32_dpp v119, -v169, v53 quad_perm:[1,1,1,1] row_mask:0xf bank_mask:0xf
	ds_read_b64 v[198:199], v125 offset:15936
	v_fmac_f32_dpp v116, -v168, v54 quad_perm:[2,2,2,2] row_mask:0xf bank_mask:0xf
	v_fmac_f32_dpp v117, -v169, v55 quad_perm:[2,2,2,2] row_mask:0xf bank_mask:0xf
	v_fmac_f32_dpp v118, -v168, v56 quad_perm:[3,3,3,3] row_mask:0xf bank_mask:0xf
	ds_read_b64 v[200:201], v125 offset:15968
	v_fmac_f32_dpp v119, -v169, v57 quad_perm:[3,3,3,3] row_mask:0xf bank_mask:0xf
	v_fmac_f32_dpp v116, -v172, v58 quad_perm:[0,0,0,0] row_mask:0xf bank_mask:0xf
	v_fmac_f32_dpp v117, -v173, v59 quad_perm:[0,0,0,0] row_mask:0xf bank_mask:0xf
	ds_read_b64 v[202:203], v125 offset:16000
	v_fmac_f32_dpp v118, -v172, v60 quad_perm:[1,1,1,1] row_mask:0xf bank_mask:0xf
	v_fmac_f32_dpp v119, -v173, v61 quad_perm:[1,1,1,1] row_mask:0xf bank_mask:0xf
	v_fmac_f32_dpp v116, -v172, v62 quad_perm:[2,2,2,2] row_mask:0xf bank_mask:0xf
	ds_read_b32 v212, v124 offset:232
	v_add_f32_e32 v121, v117, v116
	v_add_f32_e32 v122, v118, v119
	v_add_f32_e32 v63, v122, v121
	s_waitcnt lgkmcnt(15)
	v_fma_f32 v116, v208, v250, -v158
	v_fmac_f32_dpp v116, -v174, v42 quad_perm:[0,0,0,0] row_mask:0xf bank_mask:0xf
	v_mul_f32_dpp v117, -v175, v43 quad_perm:[0,0,0,0] row_mask:0xf bank_mask:0xf
	v_mul_f32_dpp v118, -v174, v44 quad_perm:[1,1,1,1] row_mask:0xf bank_mask:0xf
	ds_read_u16_d16_hi v126, v123 offset:15776
	v_mul_f32_dpp v119, -v175, v45 quad_perm:[1,1,1,1] row_mask:0xf bank_mask:0xf
	v_fmac_f32_dpp v116, -v174, v46 quad_perm:[2,2,2,2] row_mask:0xf bank_mask:0xf
	v_fmac_f32_dpp v117, -v175, v47 quad_perm:[2,2,2,2] row_mask:0xf bank_mask:0xf
	ds_read_b64 v[204:205], v125 offset:16176
	v_fmac_f32_dpp v118, -v174, v48 quad_perm:[3,3,3,3] row_mask:0xf bank_mask:0xf
	v_fmac_f32_dpp v119, -v175, v49 quad_perm:[3,3,3,3] row_mask:0xf bank_mask:0xf
	v_fmac_f32_dpp v116, -v176, v50 quad_perm:[0,0,0,0] row_mask:0xf bank_mask:0xf
	ds_read_b64 v[206:207], v125 offset:16208
	v_fmac_f32_dpp v117, -v177, v51 quad_perm:[0,0,0,0] row_mask:0xf bank_mask:0xf
	v_fmac_f32_dpp v118, -v176, v52 quad_perm:[1,1,1,1] row_mask:0xf bank_mask:0xf
	v_fmac_f32_dpp v119, -v177, v53 quad_perm:[1,1,1,1] row_mask:0xf bank_mask:0xf
	ds_read_b64 v[164:165], v125 offset:16240
	v_fmac_f32_dpp v116, -v176, v54 quad_perm:[2,2,2,2] row_mask:0xf bank_mask:0xf
	v_fmac_f32_dpp v117, -v177, v55 quad_perm:[2,2,2,2] row_mask:0xf bank_mask:0xf
	v_fmac_f32_dpp v118, -v176, v56 quad_perm:[3,3,3,3] row_mask:0xf bank_mask:0xf
	ds_read_b64 v[166:167], v125 offset:16272
	v_fmac_f32_dpp v119, -v177, v57 quad_perm:[3,3,3,3] row_mask:0xf bank_mask:0xf
	v_fmac_f32_dpp v116, -v178, v58 quad_perm:[0,0,0,0] row_mask:0xf bank_mask:0xf
	v_fmac_f32_dpp v117, -v179, v59 quad_perm:[0,0,0,0] row_mask:0xf bank_mask:0xf
	ds_read_b32 v213, v124 offset:236
	v_fmac_f32_dpp v118, -v178, v60 quad_perm:[1,1,1,1] row_mask:0xf bank_mask:0xf
	v_fmac_f32_dpp v119, -v179, v61 quad_perm:[1,1,1,1] row_mask:0xf bank_mask:0xf
	v_fmac_f32_dpp v116, -v178, v62 quad_perm:[2,2,2,2] row_mask:0xf bank_mask:0xf
	ds_read_u16_d16_hi v127, v123 offset:16048
	v_fmac_f32_dpp v117, -v179, v63 quad_perm:[2,2,2,2] row_mask:0xf bank_mask:0xf
	v_add_f32_e32 v121, v117, v116
	v_add_f32_e32 v122, v118, v119
	v_add_f32_e32 v64, v122, v121
	s_waitcnt lgkmcnt(15)
; __device__ __forceinline__ float bf2f(bf16 v) { return __uint_as_float(((unsigned)v) << 16); }
; #define GDN_LOADROW(buf, rr_, i_) do { _Pragma("unroll") for (int j4 = 0; j4 < ((i_) + 3) / 4; ++j4) buf[j4] = *(const f32x4*)(Lm + (i_) * GP_LSTR + 4 * j4); rr_ = bf2f(*(const bf16*)(xsrc + (i_) * GP_STR * 2)) * scl[i_]; } while (0)
; template <int STRIP> __device__ __forceinline__ void ph_gdn_prep_fast(const bf16* __restrict__ proj, const float* __restrict__ small, const float* __restrict__ conv_w, const float* __restrict__ a_log, const float* __restrict__ dt_bias, ...
;     ...
;             float U[64];
;             const float* scl = isw ? (sgc + 256) : sbeta;
;             f32x4 bA[16], bB[16]; float rA, rB = 0.f;
;             rA = bf2f(*(const bf16*)xsrc) * scl[0];
;     ...
; #pragma unroll
;             for (int i = 0; i < 64; i += 2) {
;                 GDN_LOADROW(bB, rB, i + 1);
;                 GDN_ROW(bA, rA, i);
;                 if (i + 2 < 64) GDN_LOADROW(bA, rA, i + 2);
;                 GDN_ROW(bB, rB, i + 1);
;             }
	v_fma_f32 v116, v209, v251, -v159
	v_fmac_f32_dpp v116, -v222, v42 quad_perm:[0,0,0,0] row_mask:0xf bank_mask:0xf
	v_mul_f32_dpp v117, -v223, v43 quad_perm:[0,0,0,0] row_mask:0xf bank_mask:0xf
	v_mul_f32_dpp v118, -v222, v44 quad_perm:[1,1,1,1] row_mask:0xf bank_mask:0xf
	v_mul_f32_dpp v119, -v223, v45 quad_perm:[1,1,1,1] row_mask:0xf bank_mask:0xf
	v_fmac_f32_dpp v116, -v222, v46 quad_perm:[2,2,2,2] row_mask:0xf bank_mask:0xf
	v_fmac_f32_dpp v117, -v223, v47 quad_perm:[2,2,2,2] row_mask:0xf bank_mask:0xf
	v_fmac_f32_dpp v118, -v222, v48 quad_perm:[3,3,3,3] row_mask:0xf bank_mask:0xf
	v_fmac_f32_dpp v119, -v223, v49 quad_perm:[3,3,3,3] row_mask:0xf bank_mask:0xf
	v_fmac_f32_dpp v116, -v224, v50 quad_perm:[0,0,0,0] row_mask:0xf bank_mask:0xf
	v_fmac_f32_dpp v117, -v225, v51 quad_perm:[0,0,0,0] row_mask:0xf bank_mask:0xf
	v_fmac_f32_dpp v118, -v224, v52 quad_perm:[1,1,1,1] row_mask:0xf bank_mask:0xf
	v_fmac_f32_dpp v119, -v225, v53 quad_perm:[1,1,1,1] row_mask:0xf bank_mask:0xf
	v_fmac_f32_dpp v116, -v224, v54 quad_perm:[2,2,2,2] row_mask:0xf bank_mask:0xf
	v_fmac_f32_dpp v117, -v225, v55 quad_perm:[2,2,2,2] row_mask:0xf bank_mask:0xf
	v_fmac_f32_dpp v118, -v224, v56 quad_perm:[3,3,3,3] row_mask:0xf bank_mask:0xf
	v_fmac_f32_dpp v119, -v225, v57 quad_perm:[3,3,3,3] row_mask:0xf bank_mask:0xf
	v_fmac_f32_dpp v116, -v226, v58 quad_perm:[0,0,0,0] row_mask:0xf bank_mask:0xf
	v_fmac_f32_dpp v117, -v227, v59 quad_perm:[0,0,0,0] row_mask:0xf bank_mask:0xf
	v_fmac_f32_dpp v118, -v226, v60 quad_perm:[1,1,1,1] row_mask:0xf bank_mask:0xf
	v_fmac_f32_dpp v119, -v227, v61 quad_perm:[1,1,1,1] row_mask:0xf bank_mask:0xf
	v_fmac_f32_dpp v116, -v226, v62 quad_perm:[2,2,2,2] row_mask:0xf bank_mask:0xf
	v_fmac_f32_dpp v117, -v227, v63 quad_perm:[2,2,2,2] row_mask:0xf bank_mask:0xf
	v_fmac_f32_dpp v118, -v226, v64 quad_perm:[3,3,3,3] row_mask:0xf bank_mask:0xf
	v_add_f32_e32 v121, v117, v116
	v_add_f32_e32 v122, v118, v119
	v_add_f32_e32 v65, v122, v121
	s_waitcnt lgkmcnt(15)
	v_fma_f32 v116, v210, v252, -v144
	v_fmac_f32_dpp v116, -v228, v42 quad_perm:[0,0,0,0] row_mask:0xf bank_mask:0xf
	v_mul_f32_dpp v117, -v229, v43 quad_perm:[0,0,0,0] row_mask:0xf bank_mask:0xf
	v_mul_f32_dpp v118, -v228, v44 quad_perm:[1,1,1,1] row_mask:0xf bank_mask:0xf
	ds_read_b64 v[168:169], v125 offset:16448
	v_mul_f32_dpp v119, -v229, v45 quad_perm:[1,1,1,1] row_mask:0xf bank_mask:0xf
	v_fmac_f32_dpp v116, -v228, v46 quad_perm:[2,2,2,2] row_mask:0xf bank_mask:0xf
	v_fmac_f32_dpp v117, -v229, v47 quad_perm:[2,2,2,2] row_mask:0xf bank_mask:0xf
	ds_read_b64 v[172:173], v125 offset:16480
	v_fmac_f32_dpp v118, -v228, v48 quad_perm:[3,3,3,3] row_mask:0xf bank_mask:0xf
	v_fmac_f32_dpp v119, -v229, v49 quad_perm:[3,3,3,3] row_mask:0xf bank_mask:0xf
	v_fmac_f32_dpp v116, -v170, v50 quad_perm:[0,0,0,0] row_mask:0xf bank_mask:0xf
	ds_read_b64 v[174:175], v125 offset:16512
	v_fmac_f32_dpp v117, -v171, v51 quad_perm:[0,0,0,0] row_mask:0xf bank_mask:0xf
	v_fmac_f32_dpp v118, -v170, v52 quad_perm:[1,1,1,1] row_mask:0xf bank_mask:0xf
	v_fmac_f32_dpp v119, -v171, v53 quad_perm:[1,1,1,1] row_mask:0xf bank_mask:0xf
	ds_read_b64 v[176:177], v125 offset:16544
	v_fmac_f32_dpp v116, -v170, v54 quad_perm:[2,2,2,2] row_mask:0xf bank_mask:0xf
	v_fmac_f32_dpp v117, -v171, v55 quad_perm:[2,2,2,2] row_mask:0xf bank_mask:0xf
	v_fmac_f32_dpp v118, -v170, v56 quad_perm:[3,3,3,3] row_mask:0xf bank_mask:0xf
	ds_read_b32 v214, v124 offset:240
	v_fmac_f32_dpp v119, -v171, v57 quad_perm:[3,3,3,3] row_mask:0xf bank_mask:0xf
	v_fmac_f32_dpp v116, -v186, v58 quad_perm:[0,0,0,0] row_mask:0xf bank_mask:0xf
	v_fmac_f32_dpp v117, -v187, v59 quad_perm:[0,0,0,0] row_mask:0xf bank_mask:0xf
	ds_read_u16_d16_hi v244, v123 offset:16320
	v_fmac_f32_dpp v118, -v186, v60 quad_perm:[1,1,1,1] row_mask:0xf bank_mask:0xf
	v_fmac_f32_dpp v119, -v187, v61 quad_perm:[1,1,1,1] row_mask:0xf bank_mask:0xf
	v_fmac_f32_dpp v116, -v186, v62 quad_perm:[2,2,2,2] row_mask:0xf bank_mask:0xf
	v_fmac_f32_dpp v117, -v187, v63 quad_perm:[2,2,2,2] row_mask:0xf bank_mask:0xf
	v_fmac_f32_dpp v118, -v186, v64 quad_perm:[3,3,3,3] row_mask:0xf bank_mask:0xf
	v_fmac_f32_dpp v119, -v187, v65 quad_perm:[3,3,3,3] row_mask:0xf bank_mask:0xf
	v_add_f32_e32 v121, v117, v116
	v_add_f32_e32 v122, v118, v119
	v_add_f32_e32 v66, v122, v121
	s_waitcnt lgkmcnt(15)
	v_fma_f32 v116, v211, v253, -v145
	v_fmac_f32_dpp v116, -v188, v42 quad_perm:[0,0,0,0] row_mask:0xf bank_mask:0xf
	v_mul_f32_dpp v117, -v189, v43 quad_perm:[0,0,0,0] row_mask:0xf bank_mask:0xf
	v_mul_f32_dpp v118, -v188, v44 quad_perm:[1,1,1,1] row_mask:0xf bank_mask:0xf
	ds_read_b64 v[178:179], v125 offset:16720
	v_mul_f32_dpp v119, -v189, v45 quad_perm:[1,1,1,1] row_mask:0xf bank_mask:0xf
	v_fmac_f32_dpp v116, -v188, v46 quad_perm:[2,2,2,2] row_mask:0xf bank_mask:0xf
	v_fmac_f32_dpp v117, -v189, v47 quad_perm:[2,2,2,2] row_mask:0xf bank_mask:0xf
	ds_read_b64 v[222:223], v125 offset:16752
	v_fmac_f32_dpp v118, -v188, v48 quad_perm:[3,3,3,3] row_mask:0xf bank_mask:0xf
	v_fmac_f32_dpp v119, -v189, v49 quad_perm:[3,3,3,3] row_mask:0xf bank_mask:0xf
	v_fmac_f32_dpp v116, -v190, v50 quad_perm:[0,0,0,0] row_mask:0xf bank_mask:0xf
	ds_read_b64 v[224:225], v125 offset:16784
	v_fmac_f32_dpp v117, -v191, v51 quad_perm:[0,0,0,0] row_mask:0xf bank_mask:0xf
	v_fmac_f32_dpp v118, -v190, v52 quad_perm:[1,1,1,1] row_mask:0xf bank_mask:0xf
	v_fmac_f32_dpp v119, -v191, v53 quad_perm:[1,1,1,1] row_mask:0xf bank_mask:0xf
	ds_read_b64 v[226:227], v125 offset:16816
	v_fmac_f32_dpp v116, -v190, v54 quad_perm:[2,2,2,2] row_mask:0xf bank_mask:0xf
	v_fmac_f32_dpp v117, -v191, v55 quad_perm:[2,2,2,2] row_mask:0xf bank_mask:0xf
	v_fmac_f32_dpp v118, -v190, v56 quad_perm:[3,3,3,3] row_mask:0xf bank_mask:0xf
	ds_read_b32 v215, v124 offset:244
	v_fmac_f32_dpp v119, -v191, v57 quad_perm:[3,3,3,3] row_mask:0xf bank_mask:0xf
	v_fmac_f32_dpp v116, -v192, v58 quad_perm:[0,0,0,0] row_mask:0xf bank_mask:0xf
	v_fmac_f32_dpp v117, -v193, v59 quad_perm:[0,0,0,0] row_mask:0xf bank_mask:0xf
	ds_read_u16_d16_hi v245, v123 offset:16592
	v_fmac_f32_dpp v118, -v192, v60 quad_perm:[1,1,1,1] row_mask:0xf bank_mask:0xf
	v_fmac_f32_dpp v119, -v193, v61 quad_perm:[1,1,1,1] row_mask:0xf bank_mask:0xf
	v_fmac_f32_dpp v116, -v192, v62 quad_perm:[2,2,2,2] row_mask:0xf bank_mask:0xf
	v_fmac_f32_dpp v117, -v193, v63 quad_perm:[2,2,2,2] row_mask:0xf bank_mask:0xf
	v_fmac_f32_dpp v118, -v192, v64 quad_perm:[3,3,3,3] row_mask:0xf bank_mask:0xf
	v_fmac_f32_dpp v119, -v193, v65 quad_perm:[3,3,3,3] row_mask:0xf bank_mask:0xf
	v_fmac_f32_dpp v116, -v194, v66 quad_perm:[0,0,0,0] row_mask:0xf bank_mask:0xf
	v_add_f32_e32 v121, v117, v116
	v_add_f32_e32 v122, v118, v119
	v_add_f32_e32 v67, v122, v121
	s_waitcnt lgkmcnt(15)
; __device__ __forceinline__ float bf2f(bf16 v) { return __uint_as_float(((unsigned)v) << 16); }
; #define GDN_LOADROW(buf, rr_, i_) do { _Pragma("unroll") for (int j4 = 0; j4 < ((i_) + 3) / 4; ++j4) buf[j4] = *(const f32x4*)(Lm + (i_) * GP_LSTR + 4 * j4); rr_ = bf2f(*(const bf16*)(xsrc + (i_) * GP_STR * 2)) * scl[i_]; } while (0)
; template <int STRIP> __device__ __forceinline__ void ph_gdn_prep_fast(const bf16* __restrict__ proj, const float* __restrict__ small, const float* __restrict__ conv_w, const float* __restrict__ a_log, const float* __restrict__ dt_bias, ...
;     ...
;             float U[64];
;             const float* scl = isw ? (sgc + 256) : sbeta;
;             f32x4 bA[16], bB[16]; float rA, rB = 0.f;
;             rA = bf2f(*(const bf16*)xsrc) * scl[0];
;     ...
; #pragma unroll
;             for (int i = 0; i < 64; i += 2) {
;                 GDN_LOADROW(bB, rB, i + 1);
;                 GDN_ROW(bA, rA, i);
;                 if (i + 2 < 64) GDN_LOADROW(bA, rA, i + 2);
;                 GDN_ROW(bB, rB, i + 1);
;             }
	v_fma_f32 v116, v212, v126, -v146
	v_fmac_f32_dpp v116, -v196, v42 quad_perm:[0,0,0,0] row_mask:0xf bank_mask:0xf
	v_mul_f32_dpp v117, -v197, v43 quad_perm:[0,0,0,0] row_mask:0xf bank_mask:0xf
	ds_read_b64 v[228:229], v125 offset:16992
	v_mul_f32_dpp v118, -v196, v44 quad_perm:[1,1,1,1] row_mask:0xf bank_mask:0xf
	v_mul_f32_dpp v119, -v197, v45 quad_perm:[1,1,1,1] row_mask:0xf bank_mask:0xf
	v_fmac_f32_dpp v116, -v196, v46 quad_perm:[2,2,2,2] row_mask:0xf bank_mask:0xf
	ds_read_b64 v[170:171], v125 offset:17024
	v_fmac_f32_dpp v117, -v197, v47 quad_perm:[2,2,2,2] row_mask:0xf bank_mask:0xf
	v_fmac_f32_dpp v118, -v196, v48 quad_perm:[3,3,3,3] row_mask:0xf bank_mask:0xf
	v_fmac_f32_dpp v119, -v197, v49 quad_perm:[3,3,3,3] row_mask:0xf bank_mask:0xf
	ds_read_b64 v[186:187], v125 offset:17056
	v_fmac_f32_dpp v116, -v198, v50 quad_perm:[0,0,0,0] row_mask:0xf bank_mask:0xf
	v_fmac_f32_dpp v117, -v199, v51 quad_perm:[0,0,0,0] row_mask:0xf bank_mask:0xf
	v_fmac_f32_dpp v118, -v198, v52 quad_perm:[1,1,1,1] row_mask:0xf bank_mask:0xf
	ds_read_b64 v[188:189], v125 offset:17088
	v_fmac_f32_dpp v119, -v199, v53 quad_perm:[1,1,1,1] row_mask:0xf bank_mask:0xf
	v_fmac_f32_dpp v116, -v198, v54 quad_perm:[2,2,2,2] row_mask:0xf bank_mask:0xf
	v_fmac_f32_dpp v117, -v199, v55 quad_perm:[2,2,2,2] row_mask:0xf bank_mask:0xf
	ds_read_b32 v216, v124 offset:248
	v_fmac_f32_dpp v118, -v198, v56 quad_perm:[3,3,3,3] row_mask:0xf bank_mask:0xf
	v_fmac_f32_dpp v119, -v199, v57 quad_perm:[3,3,3,3] row_mask:0xf bank_mask:0xf
	v_fmac_f32_dpp v116, -v200, v58 quad_perm:[0,0,0,0] row_mask:0xf bank_mask:0xf
	ds_read_u16_d16_hi v246, v123 offset:16864
	v_fmac_f32_dpp v117, -v201, v59 quad_perm:[0,0,0,0] row_mask:0xf bank_mask:0xf
	v_fmac_f32_dpp v118, -v200, v60 quad_perm:[1,1,1,1] row_mask:0xf bank_mask:0xf
	v_fmac_f32_dpp v119, -v201, v61 quad_perm:[1,1,1,1] row_mask:0xf bank_mask:0xf
	v_fmac_f32_dpp v116, -v200, v62 quad_perm:[2,2,2,2] row_mask:0xf bank_mask:0xf
	v_fmac_f32_dpp v117, -v201, v63 quad_perm:[2,2,2,2] row_mask:0xf bank_mask:0xf
	v_fmac_f32_dpp v118, -v200, v64 quad_perm:[3,3,3,3] row_mask:0xf bank_mask:0xf
	v_fmac_f32_dpp v119, -v201, v65 quad_perm:[3,3,3,3] row_mask:0xf bank_mask:0xf
	v_fmac_f32_dpp v116, -v202, v66 quad_perm:[0,0,0,0] row_mask:0xf bank_mask:0xf
	v_fmac_f32_dpp v117, -v203, v67 quad_perm:[0,0,0,0] row_mask:0xf bank_mask:0xf
	v_add_f32_e32 v121, v117, v116
	v_add_f32_e32 v122, v118, v119
	v_add_f32_e32 v68, v122, v121
	s_waitcnt lgkmcnt(15)
	v_fma_f32 v116, v213, v127, -v147
	v_fmac_f32_dpp v116, -v204, v42 quad_perm:[0,0,0,0] row_mask:0xf bank_mask:0xf
	v_mul_f32_dpp v117, -v205, v43 quad_perm:[0,0,0,0] row_mask:0xf bank_mask:0xf
	v_mul_f32_dpp v118, -v204, v44 quad_perm:[1,1,1,1] row_mask:0xf bank_mask:0xf
	ds_read_b64 v[190:191], v125 offset:17264
	v_mul_f32_dpp v119, -v205, v45 quad_perm:[1,1,1,1] row_mask:0xf bank_mask:0xf
	v_fmac_f32_dpp v116, -v204, v46 quad_perm:[2,2,2,2] row_mask:0xf bank_mask:0xf
	v_fmac_f32_dpp v117, -v205, v47 quad_perm:[2,2,2,2] row_mask:0xf bank_mask:0xf
	ds_read_b64 v[192:193], v125 offset:17296
	v_fmac_f32_dpp v118, -v204, v48 quad_perm:[3,3,3,3] row_mask:0xf bank_mask:0xf
	v_fmac_f32_dpp v119, -v205, v49 quad_perm:[3,3,3,3] row_mask:0xf bank_mask:0xf
	v_fmac_f32_dpp v116, -v206, v50 quad_perm:[0,0,0,0] row_mask:0xf bank_mask:0xf
	ds_read_b64 v[194:195], v125 offset:17328
	v_fmac_f32_dpp v117, -v207, v51 quad_perm:[0,0,0,0] row_mask:0xf bank_mask:0xf
	v_fmac_f32_dpp v118, -v206, v52 quad_perm:[1,1,1,1] row_mask:0xf bank_mask:0xf
	v_fmac_f32_dpp v119, -v207, v53 quad_perm:[1,1,1,1] row_mask:0xf bank_mask:0xf
	ds_read_b64 v[196:197], v125 offset:17360
	v_fmac_f32_dpp v116, -v206, v54 quad_perm:[2,2,2,2] row_mask:0xf bank_mask:0xf
	v_fmac_f32_dpp v117, -v207, v55 quad_perm:[2,2,2,2] row_mask:0xf bank_mask:0xf
	v_fmac_f32_dpp v118, -v206, v56 quad_perm:[3,3,3,3] row_mask:0xf bank_mask:0xf
	ds_read_b32 v217, v124 offset:252
	v_fmac_f32_dpp v119, -v207, v57 quad_perm:[3,3,3,3] row_mask:0xf bank_mask:0xf
	v_fmac_f32_dpp v116, -v164, v58 quad_perm:[0,0,0,0] row_mask:0xf bank_mask:0xf
	v_fmac_f32_dpp v117, -v165, v59 quad_perm:[0,0,0,0] row_mask:0xf bank_mask:0xf
	ds_read_u16_d16_hi v247, v123 offset:17136
	v_fmac_f32_dpp v118, -v164, v60 quad_perm:[1,1,1,1] row_mask:0xf bank_mask:0xf
	v_fmac_f32_dpp v119, -v165, v61 quad_perm:[1,1,1,1] row_mask:0xf bank_mask:0xf
	v_fmac_f32_dpp v116, -v164, v62 quad_perm:[2,2,2,2] row_mask:0xf bank_mask:0xf
	v_fmac_f32_dpp v117, -v165, v63 quad_perm:[2,2,2,2] row_mask:0xf bank_mask:0xf
	v_fmac_f32_dpp v118, -v164, v64 quad_perm:[3,3,3,3] row_mask:0xf bank_mask:0xf
	v_fmac_f32_dpp v119, -v165, v65 quad_perm:[3,3,3,3] row_mask:0xf bank_mask:0xf
	v_fmac_f32_dpp v116, -v166, v66 quad_perm:[0,0,0,0] row_mask:0xf bank_mask:0xf
	v_fmac_f32_dpp v117, -v167, v67 quad_perm:[0,0,0,0] row_mask:0xf bank_mask:0xf
	v_fmac_f32_dpp v118, -v166, v68 quad_perm:[1,1,1,1] row_mask:0xf bank_mask:0xf
	v_add_f32_e32 v121, v117, v116
	v_add_f32_e32 v122, v118, v119
	v_add_f32_e32 v69, v122, v121
	s_waitcnt lgkmcnt(15)
; __device__ __forceinline__ float bf2f(bf16 v) { return __uint_as_float(((unsigned)v) << 16); }
; #define GDN_LOADROW(buf, rr_, i_) do { _Pragma("unroll") for (int j4 = 0; j4 < ((i_) + 3) / 4; ++j4) buf[j4] = *(const f32x4*)(Lm + (i_) * GP_LSTR + 4 * j4); rr_ = bf2f(*(const bf16*)(xsrc + (i_) * GP_STR * 2)) * scl[i_]; } while (0)
; template <int STRIP> __device__ __forceinline__ void ph_gdn_prep_fast(const bf16* __restrict__ proj, const float* __restrict__ small, const float* __restrict__ conv_w, const float* __restrict__ a_log, const float* __restrict__ dt_bias, ...
;     ...
;             float U[64];
;             const float* scl = isw ? (sgc + 256) : sbeta;
;             f32x4 bA[16], bB[16]; float rA, rB = 0.f;
;             rA = bf2f(*(const bf16*)xsrc) * scl[0];
;     ...
; #pragma unroll
;             for (int i = 0; i < 64; i += 2) {
;                 GDN_LOADROW(bB, rB, i + 1);
;                 GDN_ROW(bA, rA, i);
;                 if (i + 2 < 64) GDN_LOADROW(bA, rA, i + 2);
;                 GDN_ROW(bB, rB, i + 1);
;             }
	v_fma_f32 v116, v214, v244, -v160
	v_fmac_f32_dpp v116, -v168, v42 quad_perm:[0,0,0,0] row_mask:0xf bank_mask:0xf
	v_mul_f32_dpp v117, -v169, v43 quad_perm:[0,0,0,0] row_mask:0xf bank_mask:0xf
	v_mul_f32_dpp v118, -v168, v44 quad_perm:[1,1,1,1] row_mask:0xf bank_mask:0xf
	v_mul_f32_dpp v119, -v169, v45 quad_perm:[1,1,1,1] row_mask:0xf bank_mask:0xf
	v_fmac_f32_dpp v116, -v168, v46 quad_perm:[2,2,2,2] row_mask:0xf bank_mask:0xf
	v_fmac_f32_dpp v117, -v169, v47 quad_perm:[2,2,2,2] row_mask:0xf bank_mask:0xf
	v_fmac_f32_dpp v118, -v168, v48 quad_perm:[3,3,3,3] row_mask:0xf bank_mask:0xf
	v_fmac_f32_dpp v119, -v169, v49 quad_perm:[3,3,3,3] row_mask:0xf bank_mask:0xf
	v_fmac_f32_dpp v116, -v172, v50 quad_perm:[0,0,0,0] row_mask:0xf bank_mask:0xf
	v_fmac_f32_dpp v117, -v173, v51 quad_perm:[0,0,0,0] row_mask:0xf bank_mask:0xf
	v_fmac_f32_dpp v118, -v172, v52 quad_perm:[1,1,1,1] row_mask:0xf bank_mask:0xf
	v_fmac_f32_dpp v119, -v173, v53 quad_perm:[1,1,1,1] row_mask:0xf bank_mask:0xf
	v_fmac_f32_dpp v116, -v172, v54 quad_perm:[2,2,2,2] row_mask:0xf bank_mask:0xf
	v_fmac_f32_dpp v117, -v173, v55 quad_perm:[2,2,2,2] row_mask:0xf bank_mask:0xf
	v_fmac_f32_dpp v118, -v172, v56 quad_perm:[3,3,3,3] row_mask:0xf bank_mask:0xf
	v_fmac_f32_dpp v119, -v173, v57 quad_perm:[3,3,3,3] row_mask:0xf bank_mask:0xf
	v_fmac_f32_dpp v116, -v174, v58 quad_perm:[0,0,0,0] row_mask:0xf bank_mask:0xf
	v_fmac_f32_dpp v117, -v175, v59 quad_perm:[0,0,0,0] row_mask:0xf bank_mask:0xf
	v_fmac_f32_dpp v118, -v174, v60 quad_perm:[1,1,1,1] row_mask:0xf bank_mask:0xf
	v_fmac_f32_dpp v119, -v175, v61 quad_perm:[1,1,1,1] row_mask:0xf bank_mask:0xf
	v_fmac_f32_dpp v116, -v174, v62 quad_perm:[2,2,2,2] row_mask:0xf bank_mask:0xf
	v_fmac_f32_dpp v117, -v175, v63 quad_perm:[2,2,2,2] row_mask:0xf bank_mask:0xf
	v_fmac_f32_dpp v118, -v174, v64 quad_perm:[3,3,3,3] row_mask:0xf bank_mask:0xf
	v_fmac_f32_dpp v119, -v175, v65 quad_perm:[3,3,3,3] row_mask:0xf bank_mask:0xf
	v_fmac_f32_dpp v116, -v176, v66 quad_perm:[0,0,0,0] row_mask:0xf bank_mask:0xf
	v_fmac_f32_dpp v117, -v177, v67 quad_perm:[0,0,0,0] row_mask:0xf bank_mask:0xf
	v_fmac_f32_dpp v118, -v176, v68 quad_perm:[1,1,1,1] row_mask:0xf bank_mask:0xf
	v_fmac_f32_dpp v119, -v177, v69 quad_perm:[1,1,1,1] row_mask:0xf bank_mask:0xf
	v_add_f32_e32 v121, v117, v116
	v_add_f32_e32 v122, v118, v119
	v_add_f32_e32 v70, v122, v121
	s_waitcnt lgkmcnt(12)
	v_fma_f32 v116, v215, v245, -v161
	v_fmac_f32_dpp v116, -v178, v42 quad_perm:[0,0,0,0] row_mask:0xf bank_mask:0xf
	v_mul_f32_dpp v117, -v179, v43 quad_perm:[0,0,0,0] row_mask:0xf bank_mask:0xf
	v_mul_f32_dpp v118, -v178, v44 quad_perm:[1,1,1,1] row_mask:0xf bank_mask:0xf
	v_mul_f32_dpp v119, -v179, v45 quad_perm:[1,1,1,1] row_mask:0xf bank_mask:0xf
	v_fmac_f32_dpp v116, -v178, v46 quad_perm:[2,2,2,2] row_mask:0xf bank_mask:0xf
	v_fmac_f32_dpp v117, -v179, v47 quad_perm:[2,2,2,2] row_mask:0xf bank_mask:0xf
	v_fmac_f32_dpp v118, -v178, v48 quad_perm:[3,3,3,3] row_mask:0xf bank_mask:0xf
	v_fmac_f32_dpp v119, -v179, v49 quad_perm:[3,3,3,3] row_mask:0xf bank_mask:0xf
	v_fmac_f32_dpp v116, -v222, v50 quad_perm:[0,0,0,0] row_mask:0xf bank_mask:0xf
	v_fmac_f32_dpp v117, -v223, v51 quad_perm:[0,0,0,0] row_mask:0xf bank_mask:0xf
	v_fmac_f32_dpp v118, -v222, v52 quad_perm:[1,1,1,1] row_mask:0xf bank_mask:0xf
	v_fmac_f32_dpp v119, -v223, v53 quad_perm:[1,1,1,1] row_mask:0xf bank_mask:0xf
	v_fmac_f32_dpp v116, -v222, v54 quad_perm:[2,2,2,2] row_mask:0xf bank_mask:0xf
	v_fmac_f32_dpp v117, -v223, v55 quad_perm:[2,2,2,2] row_mask:0xf bank_mask:0xf
	v_fmac_f32_dpp v118, -v222, v56 quad_perm:[3,3,3,3] row_mask:0xf bank_mask:0xf
	v_fmac_f32_dpp v119, -v223, v57 quad_perm:[3,3,3,3] row_mask:0xf bank_mask:0xf
	v_fmac_f32_dpp v116, -v224, v58 quad_perm:[0,0,0,0] row_mask:0xf bank_mask:0xf
	v_fmac_f32_dpp v117, -v225, v59 quad_perm:[0,0,0,0] row_mask:0xf bank_mask:0xf
	v_fmac_f32_dpp v118, -v224, v60 quad_perm:[1,1,1,1] row_mask:0xf bank_mask:0xf
	v_fmac_f32_dpp v119, -v225, v61 quad_perm:[1,1,1,1] row_mask:0xf bank_mask:0xf
	v_fmac_f32_dpp v116, -v224, v62 quad_perm:[2,2,2,2] row_mask:0xf bank_mask:0xf
	v_fmac_f32_dpp v117, -v225, v63 quad_perm:[2,2,2,2] row_mask:0xf bank_mask:0xf
	v_fmac_f32_dpp v118, -v224, v64 quad_perm:[3,3,3,3] row_mask:0xf bank_mask:0xf
	v_fmac_f32_dpp v119, -v225, v65 quad_perm:[3,3,3,3] row_mask:0xf bank_mask:0xf
	v_fmac_f32_dpp v116, -v226, v66 quad_perm:[0,0,0,0] row_mask:0xf bank_mask:0xf
	v_fmac_f32_dpp v117, -v227, v67 quad_perm:[0,0,0,0] row_mask:0xf bank_mask:0xf
	v_fmac_f32_dpp v118, -v226, v68 quad_perm:[1,1,1,1] row_mask:0xf bank_mask:0xf
	v_fmac_f32_dpp v119, -v227, v69 quad_perm:[1,1,1,1] row_mask:0xf bank_mask:0xf
	v_fmac_f32_dpp v116, -v226, v70 quad_perm:[2,2,2,2] row_mask:0xf bank_mask:0xf
	v_add_f32_e32 v121, v117, v116
	v_add_f32_e32 v122, v118, v119
	v_add_f32_e32 v71, v122, v121
	s_waitcnt lgkmcnt(6)
; __device__ __forceinline__ int gperm(int x) { return (x & ~31) | ((x & 12) << 1) | ((x & 16) >> 2) | (x & 3); }
; #define GDN_LOADROW(buf, rr_, i_) do { _Pragma("unroll") for (int j4 = 0; j4 < ((i_) + 3) / 4; ++j4) buf[j4] = *(const f32x4*)(Lm + (i_) * GP_LSTR + 4 * j4); rr_ = bf2f(*(const bf16*)(xsrc + (i_) * GP_STR * 2)) * scl[i_]; } while (0)
; template <int STRIP> __device__ __forceinline__ void ph_gdn_prep_fast(const bf16* __restrict__ proj, const float* __restrict__ small, const float* __restrict__ conv_w, const float* __restrict__ a_log, const float* __restrict__ dt_bias, ...
;     ...
; #pragma unroll
;             for (int i = 0; i < 64; i += 2) {
;                 GDN_LOADROW(bB, rB, i + 1);
;                 GDN_ROW(bA, rA, i);
;                 if (i + 2 < 64) GDN_LOADROW(bA, rA, i + 2);
;                 GDN_ROW(bB, rB, i + 1);
;             }
;     ...
;             if (STRIP == 3) { if (U[63] == 12345.678f) EGL[ci] = U[5]; } else
;             if (!isw) { const int v = cc >> 4, c15 = cc & 15; bf16* dst = UF + ((size_t)ci * 8 + v) * 64 * 16;
;     ...
;             else { bf16* dst = WP + (size_t)ci * 64 * 128 + gperm(cc);
	v_fma_f32 v116, v216, v246, -v162
	v_fmac_f32_dpp v116, -v228, v42 quad_perm:[0,0,0,0] row_mask:0xf bank_mask:0xf
	v_mul_f32_dpp v117, -v229, v43 quad_perm:[0,0,0,0] row_mask:0xf bank_mask:0xf
	v_mul_f32_dpp v118, -v228, v44 quad_perm:[1,1,1,1] row_mask:0xf bank_mask:0xf
	v_mul_f32_dpp v119, -v229, v45 quad_perm:[1,1,1,1] row_mask:0xf bank_mask:0xf
	v_fmac_f32_dpp v116, -v228, v46 quad_perm:[2,2,2,2] row_mask:0xf bank_mask:0xf
	v_fmac_f32_dpp v117, -v229, v47 quad_perm:[2,2,2,2] row_mask:0xf bank_mask:0xf
	v_fmac_f32_dpp v118, -v228, v48 quad_perm:[3,3,3,3] row_mask:0xf bank_mask:0xf
	v_fmac_f32_dpp v119, -v229, v49 quad_perm:[3,3,3,3] row_mask:0xf bank_mask:0xf
	v_fmac_f32_dpp v116, -v170, v50 quad_perm:[0,0,0,0] row_mask:0xf bank_mask:0xf
	v_fmac_f32_dpp v117, -v171, v51 quad_perm:[0,0,0,0] row_mask:0xf bank_mask:0xf
	v_fmac_f32_dpp v118, -v170, v52 quad_perm:[1,1,1,1] row_mask:0xf bank_mask:0xf
	v_fmac_f32_dpp v119, -v171, v53 quad_perm:[1,1,1,1] row_mask:0xf bank_mask:0xf
	v_fmac_f32_dpp v116, -v170, v54 quad_perm:[2,2,2,2] row_mask:0xf bank_mask:0xf
	v_fmac_f32_dpp v117, -v171, v55 quad_perm:[2,2,2,2] row_mask:0xf bank_mask:0xf
	v_fmac_f32_dpp v118, -v170, v56 quad_perm:[3,3,3,3] row_mask:0xf bank_mask:0xf
	v_fmac_f32_dpp v119, -v171, v57 quad_perm:[3,3,3,3] row_mask:0xf bank_mask:0xf
	v_fmac_f32_dpp v116, -v186, v58 quad_perm:[0,0,0,0] row_mask:0xf bank_mask:0xf
	v_fmac_f32_dpp v117, -v187, v59 quad_perm:[0,0,0,0] row_mask:0xf bank_mask:0xf
	v_fmac_f32_dpp v118, -v186, v60 quad_perm:[1,1,1,1] row_mask:0xf bank_mask:0xf
	v_fmac_f32_dpp v119, -v187, v61 quad_perm:[1,1,1,1] row_mask:0xf bank_mask:0xf
	v_fmac_f32_dpp v116, -v186, v62 quad_perm:[2,2,2,2] row_mask:0xf bank_mask:0xf
	v_fmac_f32_dpp v117, -v187, v63 quad_perm:[2,2,2,2] row_mask:0xf bank_mask:0xf
	v_fmac_f32_dpp v118, -v186, v64 quad_perm:[3,3,3,3] row_mask:0xf bank_mask:0xf
	v_fmac_f32_dpp v119, -v187, v65 quad_perm:[3,3,3,3] row_mask:0xf bank_mask:0xf
	v_fmac_f32_dpp v116, -v188, v66 quad_perm:[0,0,0,0] row_mask:0xf bank_mask:0xf
	v_fmac_f32_dpp v117, -v189, v67 quad_perm:[0,0,0,0] row_mask:0xf bank_mask:0xf
	v_fmac_f32_dpp v118, -v188, v68 quad_perm:[1,1,1,1] row_mask:0xf bank_mask:0xf
	v_fmac_f32_dpp v119, -v189, v69 quad_perm:[1,1,1,1] row_mask:0xf bank_mask:0xf
	v_fmac_f32_dpp v116, -v188, v70 quad_perm:[2,2,2,2] row_mask:0xf bank_mask:0xf
	v_fmac_f32_dpp v117, -v189, v71 quad_perm:[2,2,2,2] row_mask:0xf bank_mask:0xf
	v_add_f32_e32 v121, v117, v116
	v_add_f32_e32 v122, v118, v119
	v_add_f32_e32 v26, v122, v121
	s_waitcnt lgkmcnt(0)
	v_fma_f32 v116, v217, v247, -v163
	v_fmac_f32_dpp v116, -v190, v42 quad_perm:[0,0,0,0] row_mask:0xf bank_mask:0xf
	v_mul_f32_dpp v117, -v191, v43 quad_perm:[0,0,0,0] row_mask:0xf bank_mask:0xf
	v_mul_f32_dpp v118, -v190, v44 quad_perm:[1,1,1,1] row_mask:0xf bank_mask:0xf
	v_mul_f32_dpp v119, -v191, v45 quad_perm:[1,1,1,1] row_mask:0xf bank_mask:0xf
	v_fmac_f32_dpp v116, -v190, v46 quad_perm:[2,2,2,2] row_mask:0xf bank_mask:0xf
	v_fmac_f32_dpp v117, -v191, v47 quad_perm:[2,2,2,2] row_mask:0xf bank_mask:0xf
	v_fmac_f32_dpp v118, -v190, v48 quad_perm:[3,3,3,3] row_mask:0xf bank_mask:0xf
	v_fmac_f32_dpp v119, -v191, v49 quad_perm:[3,3,3,3] row_mask:0xf bank_mask:0xf
	v_fmac_f32_dpp v116, -v192, v50 quad_perm:[0,0,0,0] row_mask:0xf bank_mask:0xf
	v_fmac_f32_dpp v117, -v193, v51 quad_perm:[0,0,0,0] row_mask:0xf bank_mask:0xf
	v_fmac_f32_dpp v118, -v192, v52 quad_perm:[1,1,1,1] row_mask:0xf bank_mask:0xf
	v_fmac_f32_dpp v119, -v193, v53 quad_perm:[1,1,1,1] row_mask:0xf bank_mask:0xf
	v_fmac_f32_dpp v116, -v192, v54 quad_perm:[2,2,2,2] row_mask:0xf bank_mask:0xf
	v_fmac_f32_dpp v117, -v193, v55 quad_perm:[2,2,2,2] row_mask:0xf bank_mask:0xf
	v_fmac_f32_dpp v118, -v192, v56 quad_perm:[3,3,3,3] row_mask:0xf bank_mask:0xf
	v_fmac_f32_dpp v119, -v193, v57 quad_perm:[3,3,3,3] row_mask:0xf bank_mask:0xf
	v_fmac_f32_dpp v116, -v194, v58 quad_perm:[0,0,0,0] row_mask:0xf bank_mask:0xf
	v_fmac_f32_dpp v117, -v195, v59 quad_perm:[0,0,0,0] row_mask:0xf bank_mask:0xf
	v_fmac_f32_dpp v118, -v194, v60 quad_perm:[1,1,1,1] row_mask:0xf bank_mask:0xf
	v_fmac_f32_dpp v119, -v195, v61 quad_perm:[1,1,1,1] row_mask:0xf bank_mask:0xf
	v_fmac_f32_dpp v116, -v194, v62 quad_perm:[2,2,2,2] row_mask:0xf bank_mask:0xf
	v_fmac_f32_dpp v117, -v195, v63 quad_perm:[2,2,2,2] row_mask:0xf bank_mask:0xf
	v_fmac_f32_dpp v118, -v194, v64 quad_perm:[3,3,3,3] row_mask:0xf bank_mask:0xf
	v_fmac_f32_dpp v119, -v195, v65 quad_perm:[3,3,3,3] row_mask:0xf bank_mask:0xf
	v_fmac_f32_dpp v116, -v196, v66 quad_perm:[0,0,0,0] row_mask:0xf bank_mask:0xf
	v_fmac_f32_dpp v117, -v197, v67 quad_perm:[0,0,0,0] row_mask:0xf bank_mask:0xf
	v_fmac_f32_dpp v118, -v196, v68 quad_perm:[1,1,1,1] row_mask:0xf bank_mask:0xf
	v_fmac_f32_dpp v119, -v197, v69 quad_perm:[1,1,1,1] row_mask:0xf bank_mask:0xf
	v_fmac_f32_dpp v116, -v196, v70 quad_perm:[2,2,2,2] row_mask:0xf bank_mask:0xf
	v_fmac_f32_dpp v117, -v197, v71 quad_perm:[2,2,2,2] row_mask:0xf bank_mask:0xf
	v_fmac_f32_dpp v118, -v196, v26 quad_perm:[3,3,3,3] row_mask:0xf bank_mask:0xf
	v_add_f32_e32 v121, v117, v116
	v_add_f32_e32 v122, v118, v119
	v_add_f32_e32 v72, v122, v121
	v_add_u32_e32 v8, v79, v8
	v_ashrrev_i32_e32 v9, 31, v8
	v_lshlrev_b64 v[8:9], 14, v[8:9]
	v_lshlrev_b32_e32 v73, 4, v78
	s_and_saveexec_b64 s[0:1], vcc
	s_xor_b64 s[0:1], exec, s[0:1]
	s_cbranch_execz .LBB0_1305
; __device__ __forceinline__ bf16 f2bf(float f) { return (bf16)(pk2(f, 0.f) & 0xffffu); }
; __device__ __forceinline__ int gperm(int x) { return (x & ~31) | ((x & 12) << 1) | ((x & 16) >> 2) | (x & 3); }
; template <int STRIP> __device__ __forceinline__ void ph_gdn_prep_fast(const bf16* __restrict__ proj, const float* __restrict__ small, const float* __restrict__ conv_w, const float* __restrict__ a_log, const float* __restrict__ dt_bias, ...
;     ...
;             else { bf16* dst = WP + (size_t)ci * 64 * 128 + gperm(cc);
; #pragma unroll
;                 for (int i = 0; i < 64; ++i) __builtin_nontemporal_store(f2bf(U[i]), dst + i * 128); }
	v_and_b32_e32 v2, 24, v18
	v_lshrrev_b32_e32 v18, 2, v78
	v_and_b32_e32 v18, 4, v18
	v_and_b32_e32 v73, 0x63, v78
	v_or3_b32 v2, v18, v73, v2
	v_lshl_add_u64 v[74:75], s[34:35], 0, v[8:9]
	v_lshlrev_b32_e32 v2, 1, v2
	v_lshl_add_u64 v[74:75], v[74:75], 0, v[2:3]
	v_cvt_pk_bf16_f32 v2, v4, s0
	global_store_short v[74:75], v2, off nt
	v_cvt_pk_bf16_f32 v2, v5, s0
	global_store_short v[74:75], v2, off offset:256 nt
	v_cvt_pk_bf16_f32 v2, v6, s0
	global_store_short v[74:75], v2, off offset:512 nt
	v_cvt_pk_bf16_f32 v2, v12, s0
	global_store_short v[74:75], v2, off offset:768 nt
	v_cvt_pk_bf16_f32 v2, v7, s0
	global_store_short v[74:75], v2, off offset:1024 nt
	v_cvt_pk_bf16_f32 v2, v13, s0
	global_store_short v[74:75], v2, off offset:1280 nt
	v_cvt_pk_bf16_f32 v2, v14, s0
	global_store_short v[74:75], v2, off offset:1536 nt
	v_cvt_pk_bf16_f32 v2, v15, s0
	global_store_short v[74:75], v2, off offset:1792 nt
	v_cvt_pk_bf16_f32 v2, v16, s0
	global_store_short v[74:75], v2, off offset:2048 nt
	v_cvt_pk_bf16_f32 v2, v17, s0
	global_store_short v[74:75], v2, off offset:2304 nt
	v_cvt_pk_bf16_f32 v2, v19, s0
	global_store_short v[74:75], v2, off offset:2560 nt
	v_cvt_pk_bf16_f32 v2, v20, s0
	global_store_short v[74:75], v2, off offset:2816 nt
	v_cvt_pk_bf16_f32 v2, v21, s0
	global_store_short v[74:75], v2, off offset:3072 nt
	v_cvt_pk_bf16_f32 v2, v22, s0
	v_add_co_u32_e32 v4, vcc, s79, v74
	global_store_short v[74:75], v2, off offset:3328 nt
	v_cvt_pk_bf16_f32 v2, v23, s0
	v_addc_co_u32_e32 v5, vcc, 0, v75, vcc
	global_store_short v[74:75], v2, off offset:3584 nt
	v_cvt_pk_bf16_f32 v2, v24, s0
	v_add_co_u32_e32 v6, vcc, s76, v74
	global_store_short v[74:75], v2, off offset:3840 nt
	v_cvt_pk_bf16_f32 v2, v25, s0
	v_addc_co_u32_e32 v7, vcc, 0, v75, vcc
	global_store_short v[6:7], v2, off offset:-4096 nt
	v_cvt_pk_bf16_f32 v2, v27, s0
	global_store_short v[4:5], v2, off offset:256 nt
	v_cvt_pk_bf16_f32 v2, v28, s0
	global_store_short v[4:5], v2, off offset:512 nt
	v_cvt_pk_bf16_f32 v2, v29, s0
	global_store_short v[4:5], v2, off offset:768 nt
	v_cvt_pk_bf16_f32 v2, v30, s0
	global_store_short v[4:5], v2, off offset:1024 nt
	v_cvt_pk_bf16_f32 v2, v31, s0
	global_store_short v[4:5], v2, off offset:1280 nt
	v_cvt_pk_bf16_f32 v2, v32, s0
	global_store_short v[4:5], v2, off offset:1536 nt
	v_cvt_pk_bf16_f32 v2, v33, s0
	global_store_short v[4:5], v2, off offset:1792 nt
	v_cvt_pk_bf16_f32 v2, v34, s0
	global_store_short v[4:5], v2, off offset:2048 nt
	v_cvt_pk_bf16_f32 v2, v35, s0
	global_store_short v[4:5], v2, off offset:2304 nt
	v_cvt_pk_bf16_f32 v2, v36, s0
	global_store_short v[4:5], v2, off offset:2560 nt
	v_cvt_pk_bf16_f32 v2, v37, s0
	global_store_short v[4:5], v2, off offset:2816 nt
	v_cvt_pk_bf16_f32 v2, v38, s0
	global_store_short v[4:5], v2, off offset:3072 nt
	v_cvt_pk_bf16_f32 v2, v39, s0
	global_store_short v[4:5], v2, off offset:3328 nt
	v_cvt_pk_bf16_f32 v2, v40, s0
	global_store_short v[4:5], v2, off offset:3584 nt
	v_cvt_pk_bf16_f32 v2, v41, s0
	global_store_short v[4:5], v2, off offset:3840 nt
	v_cvt_pk_bf16_f32 v2, v42, s0
	global_store_short v[6:7], v2, off nt
	v_cvt_pk_bf16_f32 v2, v43, s0
	global_store_short v[6:7], v2, off offset:256 nt
	v_cvt_pk_bf16_f32 v2, v44, s0
	global_store_short v[6:7], v2, off offset:512 nt
	v_cvt_pk_bf16_f32 v2, v45, s0
	global_store_short v[6:7], v2, off offset:768 nt
	v_cvt_pk_bf16_f32 v2, v46, s0
	global_store_short v[6:7], v2, off offset:1024 nt
	v_cvt_pk_bf16_f32 v2, v47, s0
	global_store_short v[6:7], v2, off offset:1280 nt
	v_cvt_pk_bf16_f32 v2, v48, s0
	global_store_short v[6:7], v2, off offset:1536 nt
	v_cvt_pk_bf16_f32 v2, v49, s0
	global_store_short v[6:7], v2, off offset:1792 nt
	v_cvt_pk_bf16_f32 v2, v50, s0
	global_store_short v[6:7], v2, off offset:2048 nt
	v_cvt_pk_bf16_f32 v2, v51, s0
	global_store_short v[6:7], v2, off offset:2304 nt
	v_cvt_pk_bf16_f32 v2, v52, s0
	global_store_short v[6:7], v2, off offset:2560 nt
	v_cvt_pk_bf16_f32 v2, v53, s0
	global_store_short v[6:7], v2, off offset:2816 nt
	v_cvt_pk_bf16_f32 v2, v54, s0
	global_store_short v[6:7], v2, off offset:3072 nt
	v_cvt_pk_bf16_f32 v2, v55, s0
	global_store_short v[6:7], v2, off offset:3328 nt
	v_cvt_pk_bf16_f32 v2, v56, s0
	s_movk_i32 s2, 0x3000
	global_store_short v[6:7], v2, off offset:3584 nt
	v_cvt_pk_bf16_f32 v2, v57, s0
	v_add_co_u32_e32 v4, vcc, s2, v74
	global_store_short v[6:7], v2, off offset:3840 nt
	v_cvt_pk_bf16_f32 v2, v58, s0
	v_addc_co_u32_e32 v5, vcc, 0, v75, vcc
	global_store_short v[4:5], v2, off nt
	v_cvt_pk_bf16_f32 v2, v59, s0
	global_store_short v[4:5], v2, off offset:256 nt
	v_cvt_pk_bf16_f32 v2, v60, s0
	global_store_short v[4:5], v2, off offset:512 nt
	v_cvt_pk_bf16_f32 v2, v61, s0
	global_store_short v[4:5], v2, off offset:768 nt
	v_cvt_pk_bf16_f32 v2, v62, s0
	global_store_short v[4:5], v2, off offset:1024 nt
	v_cvt_pk_bf16_f32 v2, v63, s0
	global_store_short v[4:5], v2, off offset:1280 nt
	v_cvt_pk_bf16_f32 v2, v64, s0
	global_store_short v[4:5], v2, off offset:1536 nt
	v_cvt_pk_bf16_f32 v2, v65, s0
	global_store_short v[4:5], v2, off offset:1792 nt
	v_cvt_pk_bf16_f32 v2, v66, s0
	global_store_short v[4:5], v2, off offset:2048 nt
	v_cvt_pk_bf16_f32 v2, v67, s0
	global_store_short v[4:5], v2, off offset:2304 nt
	v_cvt_pk_bf16_f32 v2, v68, s0
	global_store_short v[4:5], v2, off offset:2560 nt
	v_cvt_pk_bf16_f32 v2, v69, s0
	global_store_short v[4:5], v2, off offset:2816 nt
	v_cvt_pk_bf16_f32 v2, v70, s0
	global_store_short v[4:5], v2, off offset:3072 nt
	v_cvt_pk_bf16_f32 v2, v71, s0
	global_store_short v[4:5], v2, off offset:3328 nt
	v_cvt_pk_bf16_f32 v2, v26, s0
	global_store_short v[4:5], v2, off offset:3584 nt
	v_cvt_pk_bf16_f32 v2, v72, s0
	global_store_short v[4:5], v2, off offset:3840 nt
	v_lshlrev_b32_e32 v73, 4, v78
